# v61 + B1(buf0) staging of phase 3 issued mid-way through phase 2's compute segment (after 16 MFMAs), mirroring the phase-8 staging in phase 4
# baseline (speedup 1.0000x reference)
; #define PG8_STAGE(bufoff, gbase, voff) do { _Pragma("unroll") for (int _i = 0; _i < 2; ++_i) \
;         __builtin_amdgcn_global_load_lds((const unsigned*)((const char*)(gbase) + (voff)[_i]), (LAS unsigned*)(lds + (bufoff) + ldsw + _i * 8192), 16, 0, 0); } while (0)
; #define PG8_LDA(dst, b, h) do { _Pragma("unroll") for (int m = 0; m < 4; ++m) _Pragma("unroll") for (int k = 0; k < 2; ++k) dst[m][k] = *(const LAS bf16x8*)(lds + PG8_SA(b, h) + aoff + m * 2048 + k * 1024); } while (0)
; #define PG8_LDB(dst, b, h) do { _Pragma("unroll") for (int n = 0; n < 2; ++n) _Pragma("unroll") for (int k = 0; k < 2; ++k) dst[n][k] = *(const LAS bf16x8*)(lds + PG8_SB(b, h) + boff + n * 2048 + k * 1024); } while (0)
; #define PG8_MMA(ai, bj, At, Bt) do { __builtin_amdgcn_s_setprio(1); _Pragma("unroll") for (int m = 0; m < 4; ++m) _Pragma("unroll") for (int n = 0; n < 2; ++n) _Pragma("unroll") for (int k = 0; k < 2; ++k) \
;         acc[ai][bj][m][n] = __builtin_amdgcn_mfma_f32_16x16x32_bf16(Bt[n][k], At[m][k], acc[ai][bj][m][n], 0, 0, 0); __builtin_amdgcn_s_setprio(0); } while (0)
; #define PG8_WAIT_V(n) asm volatile("s_waitcnt vmcnt(" #n ")" ::: "memory")
; #define PG8_WAIT_L(n) asm volatile("s_waitcnt lgkmcnt(" #n ")" ::: "memory")
; template <class Epi, class Sched>
; __device__ __forceinline__ void gemm_phase(LAS unsigned char* lds, const Gemm g, const Sched& S, const Epi& E) {
;     ...
;         for (int t = 0; t < nt; t += 2) {
;             const bool last = (t == nt - 2);
;             const char* a1 = cA + (size_t)(t + 1) * kstep;
;             const char* a2 = last ? nA : cA + (size_t)(t + 2) * kstep; const char* b2 = last ? nB : cB + (size_t)(t + 2) * kstep;
;             const char* a3 = a2 + kstep; const char* b3 = b2 + kstep;
;             PG8_LDB(B0, 0, 0); PG8_SCHED; PG8_LDA(At, 0, 0); PG8_STAGE(PG8_SA(1, 1), a1 + hstep, voffA);
;             PG8_WAIT_L(8); PG8_BAR; PG8_WAIT_L(0); PG8_MMA(0, 0, At, B0); PG8_BAR; PG8_SCHED;
;             PG8_LDB(B1, 0, 1); PG8_STAGE(PG8_SB(0, 0), b2, voffB);
;             PG8_BAR; PG8_WAIT_L(0); PG8_MMA(0, 1, At, B1); PG8_BAR;
;             PG8_LDA(At, 0, 1); PG8_STAGE(PG8_SA(0, 0), a2, voffA);
;             PG8_BAR; PG8_WAIT_L(0); PG8_MMA(1, 0, At, B0); PG8_BAR; PG8_SCHED;
;             PG8_STAGE(PG8_SB(0, 1), b2 + hstep, voffB);
;             PG8_WAIT_V(6); PG8_BAR; PG8_MMA(1, 1, At, B1); PG8_BAR;
.LBB0_44:
	s_add_u32 s50, s28, 0x100
	s_addc_u32 s51, s29, 0
	s_cmpk_eq_i32 s75, 0x7c
	s_cselect_b32 s55, s27, s51
	s_cselect_b32 s54, s71, s50
	s_cselect_b32 s53, s25, s74
	s_cselect_b32 s52, s72, s73
	s_add_i32 m0, s9, 0xc000
	s_nop 0
	global_load_lds_dwordx4 v150, s[28:29]
	s_add_i32 m0, s9, 0xe000
	s_nop 0
	global_load_lds_dwordx4 v148, s[28:29]
	s_add_i32 s38, 0, 0x10000
	ds_read_b128 v[66:69], v226
	ds_read_b128 v[70:73], v226 offset:1024
	ds_read_b128 v[74:77], v226 offset:2048
	ds_read_b128 v[78:81], v226 offset:3072
	ds_read_b128 v[152:155], v165
	ds_read_b128 v[166:169], v165 offset:1024
	ds_read_b128 v[170:173], v165 offset:2048
	ds_read_b128 v[174:177], v165 offset:3072
	ds_read_b128 v[178:181], v165 offset:4096
	ds_read_b128 v[182:185], v165 offset:5120
	ds_read_b128 v[186:189], v165 offset:6144
	ds_read_b128 v[190:193], v165 offset:7168
	s_add_i32 s39, 0, 0x14000
	ds_read_b128 v[194:197], v226 offset:16384
	ds_read_b128 v[198:201], v226 offset:17408
	ds_read_b128 v[202:205], v226 offset:18432
	ds_read_b128 v[210:213], v226 offset:19456
	s_waitcnt lgkmcnt(4)
	s_barrier
	s_waitcnt lgkmcnt(0)
	v_mfma_f32_16x16x32_bf16 v[142:145], v[66:69], v[152:155], v[142:145]
	v_mfma_f32_16x16x32_bf16 v[138:141], v[74:77], v[152:155], v[138:141]
	v_mfma_f32_16x16x32_bf16 v[126:129], v[66:69], v[170:173], v[126:129]
	v_mfma_f32_16x16x32_bf16 v[122:125], v[74:77], v[170:173], v[122:125]
	v_mfma_f32_16x16x32_bf16 v[110:113], v[66:69], v[178:181], v[110:113]
	v_mfma_f32_16x16x32_bf16 v[106:109], v[74:77], v[178:181], v[106:109]
	v_mfma_f32_16x16x32_bf16 v[102:105], v[66:69], v[186:189], v[102:105]
	v_mfma_f32_16x16x32_bf16 v[98:101], v[74:77], v[186:189], v[98:101]
	v_mfma_f32_16x16x32_bf16 v[142:145], v[70:73], v[166:169], v[142:145]
	v_mfma_f32_16x16x32_bf16 v[138:141], v[78:81], v[166:169], v[138:141]
	v_mfma_f32_16x16x32_bf16 v[126:129], v[70:73], v[174:177], v[126:129]
	v_mfma_f32_16x16x32_bf16 v[122:125], v[78:81], v[174:177], v[122:125]
	v_mfma_f32_16x16x32_bf16 v[110:113], v[70:73], v[182:185], v[110:113]
	v_mfma_f32_16x16x32_bf16 v[106:109], v[78:81], v[182:185], v[106:109]
	v_mfma_f32_16x16x32_bf16 v[102:105], v[70:73], v[190:193], v[102:105]
	v_mfma_f32_16x16x32_bf16 v[98:101], v[78:81], v[190:193], v[98:101]
	v_mfma_f32_16x16x32_bf16 v[134:137], v[194:197], v[152:155], v[134:137]
	v_mfma_f32_16x16x32_bf16 v[130:133], v[202:205], v[152:155], v[130:133]
	v_mfma_f32_16x16x32_bf16 v[118:121], v[194:197], v[170:173], v[118:121]
	v_mfma_f32_16x16x32_bf16 v[114:117], v[202:205], v[170:173], v[114:117]
	v_mfma_f32_16x16x32_bf16 v[94:97], v[194:197], v[178:181], v[94:97]
	v_mfma_f32_16x16x32_bf16 v[90:93], v[202:205], v[178:181], v[90:93]
	v_mfma_f32_16x16x32_bf16 v[86:89], v[194:197], v[186:189], v[86:89]
	v_mfma_f32_16x16x32_bf16 v[82:85], v[202:205], v[186:189], v[82:85]
	v_mfma_f32_16x16x32_bf16 v[134:137], v[198:201], v[166:169], v[134:137]
	v_mfma_f32_16x16x32_bf16 v[130:133], v[210:213], v[166:169], v[130:133]
	v_mfma_f32_16x16x32_bf16 v[118:121], v[198:201], v[174:177], v[118:121]
	v_mfma_f32_16x16x32_bf16 v[114:117], v[210:213], v[174:177], v[114:117]
	v_mfma_f32_16x16x32_bf16 v[94:97], v[198:201], v[182:185], v[94:97]
	v_mfma_f32_16x16x32_bf16 v[90:93], v[210:213], v[182:185], v[90:93]
	v_mfma_f32_16x16x32_bf16 v[86:89], v[198:201], v[190:193], v[86:89]
	v_mfma_f32_16x16x32_bf16 v[82:85], v[210:213], v[190:193], v[82:85]
	s_barrier
	s_add_i32 s28, s38, s60
	s_mov_b32 m0, s28
	s_nop 0
	global_load_lds_dwordx4 v0, s[52:53]
	s_add_i32 m0, s28, 0x2000
	s_nop 0
	global_load_lds_dwordx4 v146, s[52:53]
	s_mov_b32 m0, s9
	s_nop 0
	global_load_lds_dwordx4 v0, s[54:55]
	s_mov_b32 m0, s61
	s_nop 0
	global_load_lds_dwordx4 v146, s[54:55]
	ds_read_b128 v[152:155], v165 offset:16384
	ds_read_b128 v[166:169], v165 offset:17408
	ds_read_b128 v[170:173], v165 offset:18432
	ds_read_b128 v[174:177], v165 offset:19456
	ds_read_b128 v[178:181], v165 offset:20480
	ds_read_b128 v[182:185], v165 offset:21504
	ds_read_b128 v[186:189], v165 offset:22528
	ds_read_b128 v[190:193], v165 offset:23552
	s_waitcnt vmcnt(4)
	s_waitcnt lgkmcnt(0)
	s_barrier
	v_mfma_f32_16x16x32_bf16 v[62:65], v[66:69], v[152:155], v[62:65]
	v_mfma_f32_16x16x32_bf16 v[58:61], v[74:77], v[152:155], v[58:61]
	v_mfma_f32_16x16x32_bf16 v[46:49], v[66:69], v[170:173], v[46:49]
	v_mfma_f32_16x16x32_bf16 v[42:45], v[74:77], v[170:173], v[42:45]
	v_mfma_f32_16x16x32_bf16 v[30:33], v[66:69], v[178:181], v[30:33]
	v_mfma_f32_16x16x32_bf16 v[26:29], v[74:77], v[178:181], v[26:29]
	v_mfma_f32_16x16x32_bf16 v[22:25], v[66:69], v[186:189], v[22:25]
	v_mfma_f32_16x16x32_bf16 v[14:17], v[74:77], v[186:189], v[14:17]
	v_mfma_f32_16x16x32_bf16 v[62:65], v[70:73], v[166:169], v[62:65]
	v_mfma_f32_16x16x32_bf16 v[58:61], v[78:81], v[166:169], v[58:61]
	v_mfma_f32_16x16x32_bf16 v[46:49], v[70:73], v[174:177], v[46:49]
	v_mfma_f32_16x16x32_bf16 v[42:45], v[78:81], v[174:177], v[42:45]
	v_mfma_f32_16x16x32_bf16 v[30:33], v[70:73], v[182:185], v[30:33]
	v_mfma_f32_16x16x32_bf16 v[26:29], v[78:81], v[182:185], v[26:29]
	v_mfma_f32_16x16x32_bf16 v[22:25], v[70:73], v[190:193], v[22:25]
	v_mfma_f32_16x16x32_bf16 v[14:17], v[78:81], v[190:193], v[14:17]
	s_add_u32 s28, s52, 0x200000
	s_addc_u32 s29, s53, 0
	s_add_i32 s38, s39, s60
	s_mov_b32 m0, s38
	s_nop 0
	global_load_lds_dwordx4 v0, s[28:29]
	s_add_i32 m0, s38, 0x2000
	s_nop 0
	global_load_lds_dwordx4 v146, s[28:29]
	v_mfma_f32_16x16x32_bf16 v[54:57], v[194:197], v[152:155], v[54:57]
	v_mfma_f32_16x16x32_bf16 v[50:53], v[202:205], v[152:155], v[50:53]
	v_mfma_f32_16x16x32_bf16 v[38:41], v[194:197], v[170:173], v[38:41]
	v_mfma_f32_16x16x32_bf16 v[34:37], v[202:205], v[170:173], v[34:37]
	v_mfma_f32_16x16x32_bf16 v[18:21], v[194:197], v[178:181], v[18:21]
	v_mfma_f32_16x16x32_bf16 v[10:13], v[202:205], v[178:181], v[10:13]
	v_mfma_f32_16x16x32_bf16 v[6:9], v[194:197], v[186:189], v[6:9]
	v_mfma_f32_16x16x32_bf16 v[2:5], v[202:205], v[186:189], v[2:5]
	v_mfma_f32_16x16x32_bf16 v[54:57], v[198:201], v[166:169], v[54:57]
	v_mfma_f32_16x16x32_bf16 v[50:53], v[210:213], v[166:169], v[50:53]
	v_mfma_f32_16x16x32_bf16 v[38:41], v[198:201], v[174:177], v[38:41]
	v_mfma_f32_16x16x32_bf16 v[34:37], v[210:213], v[174:177], v[34:37]
	v_mfma_f32_16x16x32_bf16 v[18:21], v[198:201], v[182:185], v[18:21]
	v_mfma_f32_16x16x32_bf16 v[10:13], v[210:213], v[182:185], v[10:13]
	v_mfma_f32_16x16x32_bf16 v[6:9], v[198:201], v[190:193], v[6:9]
	v_mfma_f32_16x16x32_bf16 v[2:5], v[210:213], v[190:193], v[2:5]
	s_barrier
; #define PG8_STAGE(bufoff, gbase, voff) do { _Pragma("unroll") for (int _i = 0; _i < 2; ++_i) \
;         __builtin_amdgcn_global_load_lds((const unsigned*)((const char*)(gbase) + (voff)[_i]), (LAS unsigned*)(lds + (bufoff) + ldsw + _i * 8192), 16, 0, 0); } while (0)
; #define PG8_LDA(dst, b, h) do { _Pragma("unroll") for (int m = 0; m < 4; ++m) _Pragma("unroll") for (int k = 0; k < 2; ++k) dst[m][k] = *(const LAS bf16x8*)(lds + PG8_SA(b, h) + aoff + m * 2048 + k * 1024); } while (0)
; #define PG8_LDB(dst, b, h) do { _Pragma("unroll") for (int n = 0; n < 2; ++n) _Pragma("unroll") for (int k = 0; k < 2; ++k) dst[n][k] = *(const LAS bf16x8*)(lds + PG8_SB(b, h) + boff + n * 2048 + k * 1024); } while (0)
; #define PG8_MMA(ai, bj, At, Bt) do { __builtin_amdgcn_s_setprio(1); _Pragma("unroll") for (int m = 0; m < 4; ++m) _Pragma("unroll") for (int n = 0; n < 2; ++n) _Pragma("unroll") for (int k = 0; k < 2; ++k) \
;         acc[ai][bj][m][n] = __builtin_amdgcn_mfma_f32_16x16x32_bf16(Bt[n][k], At[m][k], acc[ai][bj][m][n], 0, 0, 0); __builtin_amdgcn_s_setprio(0); } while (0)
; #define PG8_WAIT_V(n) asm volatile("s_waitcnt vmcnt(" #n ")" ::: "memory")
; #define PG8_BAR __builtin_amdgcn_s_barrier()
;     __device__ __forceinline__ void operator()(const f32x4 (&acc)[2][2][4][2], const Unit& u, int wr, int wc, int fr, int fq) const {
;         const bool lat = u.pm < 64; const int r = lat ? (u.pm >> 3) : 8;
;         const float* s = lat ? src_lat : src_ctx; float* d = lat ? dst_lat : dst_ctx;
;         const int row0 = (lat ? u.pm : u.pm - 64) * BM + wr * 64 + fr, col0 = u.pn * BM + wc * 32 + 4 * fq;
; template <class Epi, class Sched>
; __device__ __forceinline__ void gemm_phase(LAS unsigned char* lds, const Gemm g, const Sched& S, const Epi& E) {
;     ...
;             PG8_LDB(B0, 1, 0); PG8_SCHED; PG8_LDA(At, 1, 0); PG8_STAGE(PG8_SA(0, 1), a2 + hstep, voffA);
;             PG8_WAIT_L(8); PG8_BAR; PG8_WAIT_L(0); PG8_MMA(0, 0, At, B0); PG8_BAR; PG8_SCHED;
;             PG8_LDB(B1, 1, 1); PG8_STAGE(PG8_SB(1, 0), b3, voffB);
;             PG8_BAR; PG8_WAIT_L(0); PG8_MMA(0, 1, At, B1); PG8_BAR;
;             PG8_LDA(At, 1, 1); PG8_STAGE(PG8_SA(1, 0), a3, voffA);
;             PG8_BAR; PG8_WAIT_L(0); PG8_MMA(1, 0, At, B0); PG8_BAR; PG8_SCHED;
;             PG8_STAGE(PG8_SB(1, 1), b3 + hstep, voffB);
;             PG8_WAIT_V(6); PG8_BAR; PG8_MMA(1, 1, At, B1); PG8_BAR;
	s_add_u32 s28, s54, 0x200000
	s_addc_u32 s29, s55, 0
	s_mov_b32 m0, s62
	s_nop 0
	global_load_lds_dwordx4 v0, s[28:29]
	s_mov_b32 m0, s63
	s_nop 0
	global_load_lds_dwordx4 v146, s[28:29]
	s_add_i32 s38, 0, 0x18000
	ds_read_b128 v[66:69], v226 offset:32768
	ds_read_b128 v[70:73], v226 offset:33792
	ds_read_b128 v[74:77], v226 offset:34816
	ds_read_b128 v[78:81], v226 offset:35840
	ds_read_b128 v[152:155], v165 offset:32768
	ds_read_b128 v[166:169], v165 offset:33792
	ds_read_b128 v[170:173], v165 offset:34816
	ds_read_b128 v[174:177], v165 offset:35840
	ds_read_b128 v[178:181], v165 offset:36864
	ds_read_b128 v[182:185], v165 offset:37888
	ds_read_b128 v[186:189], v165 offset:38912
	ds_read_b128 v[190:193], v165 offset:39936
	s_add_i32 s39, 0, 0x1c000
	ds_read_b128 v[194:197], v226 offset:49152
	ds_read_b128 v[198:201], v226 offset:50176
	ds_read_b128 v[202:205], v226 offset:51200
	ds_read_b128 v[210:213], v226 offset:52224
	s_waitcnt lgkmcnt(4)
	s_barrier
	s_waitcnt lgkmcnt(0)
	v_mfma_f32_16x16x32_bf16 v[142:145], v[66:69], v[152:155], v[142:145]
	v_mfma_f32_16x16x32_bf16 v[138:141], v[74:77], v[152:155], v[138:141]
	v_mfma_f32_16x16x32_bf16 v[126:129], v[66:69], v[170:173], v[126:129]
	v_mfma_f32_16x16x32_bf16 v[122:125], v[74:77], v[170:173], v[122:125]
	v_mfma_f32_16x16x32_bf16 v[110:113], v[66:69], v[178:181], v[110:113]
	v_mfma_f32_16x16x32_bf16 v[106:109], v[74:77], v[178:181], v[106:109]
	v_mfma_f32_16x16x32_bf16 v[102:105], v[66:69], v[186:189], v[102:105]
	v_mfma_f32_16x16x32_bf16 v[98:101], v[74:77], v[186:189], v[98:101]
	v_mfma_f32_16x16x32_bf16 v[142:145], v[70:73], v[166:169], v[142:145]
	v_mfma_f32_16x16x32_bf16 v[138:141], v[78:81], v[166:169], v[138:141]
	v_mfma_f32_16x16x32_bf16 v[126:129], v[70:73], v[174:177], v[126:129]
	v_mfma_f32_16x16x32_bf16 v[122:125], v[78:81], v[174:177], v[122:125]
	v_mfma_f32_16x16x32_bf16 v[110:113], v[70:73], v[182:185], v[110:113]
	v_mfma_f32_16x16x32_bf16 v[106:109], v[78:81], v[182:185], v[106:109]
	v_mfma_f32_16x16x32_bf16 v[102:105], v[70:73], v[190:193], v[102:105]
	v_mfma_f32_16x16x32_bf16 v[98:101], v[78:81], v[190:193], v[98:101]
	v_mfma_f32_16x16x32_bf16 v[134:137], v[194:197], v[152:155], v[134:137]
	v_mfma_f32_16x16x32_bf16 v[130:133], v[202:205], v[152:155], v[130:133]
	v_mfma_f32_16x16x32_bf16 v[118:121], v[194:197], v[170:173], v[118:121]
	v_mfma_f32_16x16x32_bf16 v[114:117], v[202:205], v[170:173], v[114:117]
	v_mfma_f32_16x16x32_bf16 v[94:97], v[194:197], v[178:181], v[94:97]
	v_mfma_f32_16x16x32_bf16 v[90:93], v[202:205], v[178:181], v[90:93]
	v_mfma_f32_16x16x32_bf16 v[86:89], v[194:197], v[186:189], v[86:89]
	v_mfma_f32_16x16x32_bf16 v[82:85], v[202:205], v[186:189], v[82:85]
	v_mfma_f32_16x16x32_bf16 v[134:137], v[198:201], v[166:169], v[134:137]
	v_mfma_f32_16x16x32_bf16 v[130:133], v[210:213], v[166:169], v[130:133]
	v_mfma_f32_16x16x32_bf16 v[118:121], v[198:201], v[174:177], v[118:121]
	v_mfma_f32_16x16x32_bf16 v[114:117], v[210:213], v[174:177], v[114:117]
	v_mfma_f32_16x16x32_bf16 v[94:97], v[198:201], v[182:185], v[94:97]
	v_mfma_f32_16x16x32_bf16 v[90:93], v[210:213], v[182:185], v[90:93]
	v_mfma_f32_16x16x32_bf16 v[86:89], v[198:201], v[190:193], v[86:89]
	v_mfma_f32_16x16x32_bf16 v[82:85], v[210:213], v[190:193], v[82:85]
	s_barrier
	s_add_i32 s28, s38, s60
	s_add_u32 s100, s52, s36
	s_addc_u32 s101, s53, s37
	s_mov_b32 m0, s28
	s_nop 0
	global_load_lds_dwordx4 v0, s[100:101]
	s_add_i32 m0, s28, 0x2000
	s_nop 0
	global_load_lds_dwordx4 v146, s[100:101]
	s_mov_b32 m0, s66
	s_add_u32 s100, s54, s36
	s_addc_u32 s101, s55, s37
	global_load_lds_dwordx4 v0, s[100:101]
	s_mov_b32 m0, s67
	s_nop 0
	global_load_lds_dwordx4 v146, s[100:101]
	ds_read_b128 v[152:155], v165 offset:49152
	ds_read_b128 v[166:169], v165 offset:50176
	ds_read_b128 v[170:173], v165 offset:51200
	ds_read_b128 v[174:177], v165 offset:52224
	ds_read_b128 v[178:181], v165 offset:53248
	ds_read_b128 v[182:185], v165 offset:54272
	ds_read_b128 v[186:189], v165 offset:55296
	ds_read_b128 v[190:193], v165 offset:56320
	s_waitcnt vmcnt(4)
	s_waitcnt lgkmcnt(0)
	s_barrier
	v_mfma_f32_16x16x32_bf16 v[62:65], v[66:69], v[152:155], v[62:65]
	v_mfma_f32_16x16x32_bf16 v[58:61], v[74:77], v[152:155], v[58:61]
	v_mfma_f32_16x16x32_bf16 v[46:49], v[66:69], v[170:173], v[46:49]
	v_mfma_f32_16x16x32_bf16 v[42:45], v[74:77], v[170:173], v[42:45]
	v_mfma_f32_16x16x32_bf16 v[30:33], v[66:69], v[178:181], v[30:33]
	v_mfma_f32_16x16x32_bf16 v[26:29], v[74:77], v[178:181], v[26:29]
	v_mfma_f32_16x16x32_bf16 v[22:25], v[66:69], v[186:189], v[22:25]
	v_mfma_f32_16x16x32_bf16 v[14:17], v[74:77], v[186:189], v[14:17]
	v_mfma_f32_16x16x32_bf16 v[62:65], v[70:73], v[166:169], v[62:65]
	v_mfma_f32_16x16x32_bf16 v[58:61], v[78:81], v[166:169], v[58:61]
	v_mfma_f32_16x16x32_bf16 v[46:49], v[70:73], v[174:177], v[46:49]
	v_mfma_f32_16x16x32_bf16 v[42:45], v[78:81], v[174:177], v[42:45]
	v_mfma_f32_16x16x32_bf16 v[30:33], v[70:73], v[182:185], v[30:33]
	v_mfma_f32_16x16x32_bf16 v[26:29], v[78:81], v[182:185], v[26:29]
	v_mfma_f32_16x16x32_bf16 v[22:25], v[70:73], v[190:193], v[22:25]
	v_mfma_f32_16x16x32_bf16 v[14:17], v[78:81], v[190:193], v[14:17]
	s_add_u32 s28, s52, 0x200080
	s_addc_u32 s29, s53, 0
	s_add_i32 s38, s39, s60
	s_mov_b32 m0, s38
	s_nop 0
	global_load_lds_dwordx4 v0, s[28:29]
	s_add_i32 m0, s38, 0x2000
	s_nop 0
	global_load_lds_dwordx4 v146, s[28:29]
	v_mfma_f32_16x16x32_bf16 v[54:57], v[194:197], v[152:155], v[54:57]
	v_mfma_f32_16x16x32_bf16 v[50:53], v[202:205], v[152:155], v[50:53]
	v_mfma_f32_16x16x32_bf16 v[38:41], v[194:197], v[170:173], v[38:41]
	v_mfma_f32_16x16x32_bf16 v[34:37], v[202:205], v[170:173], v[34:37]
	v_mfma_f32_16x16x32_bf16 v[18:21], v[194:197], v[178:181], v[18:21]
	v_mfma_f32_16x16x32_bf16 v[10:13], v[202:205], v[178:181], v[10:13]
	v_mfma_f32_16x16x32_bf16 v[6:9], v[194:197], v[186:189], v[6:9]
	v_mfma_f32_16x16x32_bf16 v[2:5], v[202:205], v[186:189], v[2:5]
	v_mfma_f32_16x16x32_bf16 v[54:57], v[198:201], v[166:169], v[54:57]
	v_mfma_f32_16x16x32_bf16 v[50:53], v[210:213], v[166:169], v[50:53]
	v_mfma_f32_16x16x32_bf16 v[38:41], v[198:201], v[174:177], v[38:41]
	v_mfma_f32_16x16x32_bf16 v[34:37], v[210:213], v[174:177], v[34:37]
	v_mfma_f32_16x16x32_bf16 v[18:21], v[198:201], v[182:185], v[18:21]
	v_mfma_f32_16x16x32_bf16 v[10:13], v[210:213], v[182:185], v[10:13]
	v_mfma_f32_16x16x32_bf16 v[6:9], v[198:201], v[190:193], v[6:9]
	v_mfma_f32_16x16x32_bf16 v[2:5], v[210:213], v[190:193], v[2:5]
	s_add_i32 s75, s75, 2
	s_add_u32 s73, s73, 0x100
	s_addc_u32 s74, s74, 0
	s_cmpk_gt_u32 s75, 0x7d
	s_mov_b64 s[28:29], s[50:51]
	s_barrier
	s_cbranch_scc0 .LBB0_44
	s_cmp_lt_i32 s8, 64
	s_cselect_b64 s[50:51], -1, 0
	s_cmp_gt_i32 s8, 63
	s_cbranch_scc0 .LBB0_35
	s_mov_b64 s[52:53], 0x18000
	s_mov_b64 s[28:29], s[46:47]
	s_branch .LBB0_36

; #define PG8_STAGE(bufoff, gbase, voff) do { _Pragma("unroll") for (int _i = 0; _i < 2; ++_i) \
;         __builtin_amdgcn_global_load_lds((const unsigned*)((const char*)(gbase) + (voff)[_i]), (LAS unsigned*)(lds + (bufoff) + ldsw + _i * 8192), 16, 0, 0); } while (0)
; #define PG8_LDA(dst, b, h) do { _Pragma("unroll") for (int m = 0; m < 4; ++m) _Pragma("unroll") for (int k = 0; k < 2; ++k) dst[m][k] = *(const LAS bf16x8*)(lds + PG8_SA(b, h) + aoff + m * 2048 + k * 1024); } while (0)
; #define PG8_LDB(dst, b, h) do { _Pragma("unroll") for (int n = 0; n < 2; ++n) _Pragma("unroll") for (int k = 0; k < 2; ++k) dst[n][k] = *(const LAS bf16x8*)(lds + PG8_SB(b, h) + boff + n * 2048 + k * 1024); } while (0)
; #define PG8_MMA(ai, bj, At, Bt) do { __builtin_amdgcn_s_setprio(1); _Pragma("unroll") for (int m = 0; m < 4; ++m) _Pragma("unroll") for (int n = 0; n < 2; ++n) _Pragma("unroll") for (int k = 0; k < 2; ++k) \
;         acc[ai][bj][m][n] = __builtin_amdgcn_mfma_f32_16x16x32_bf16(Bt[n][k], At[m][k], acc[ai][bj][m][n], 0, 0, 0); __builtin_amdgcn_s_setprio(0); } while (0)
; #define PG8_WAIT_V(n) asm volatile("s_waitcnt vmcnt(" #n ")" ::: "memory")
; #define PG8_WAIT_L(n) asm volatile("s_waitcnt lgkmcnt(" #n ")" ::: "memory")
; template <class Epi, class Sched>
; __device__ __forceinline__ void gemm_phase(LAS unsigned char* lds, const Gemm g, const Sched& S, const Epi& E) {
;     ...
;         for (int t = 0; t < nt; t += 2) {
;             const bool last = (t == nt - 2);
;             const char* a1 = cA + (size_t)(t + 1) * kstep;
;             const char* a2 = last ? nA : cA + (size_t)(t + 2) * kstep; const char* b2 = last ? nB : cB + (size_t)(t + 2) * kstep;
;             const char* a3 = a2 + kstep; const char* b3 = b2 + kstep;
;             PG8_LDB(B0, 0, 0); PG8_SCHED; PG8_LDA(At, 0, 0); PG8_STAGE(PG8_SA(1, 1), a1 + hstep, voffA);
;             PG8_WAIT_L(8); PG8_BAR; PG8_WAIT_L(0); PG8_MMA(0, 0, At, B0); PG8_BAR; PG8_SCHED;
;             PG8_LDB(B1, 0, 1); PG8_STAGE(PG8_SB(0, 0), b2, voffB);
;             PG8_BAR; PG8_WAIT_L(0); PG8_MMA(0, 1, At, B1); PG8_BAR;
;             PG8_LDA(At, 0, 1); PG8_STAGE(PG8_SA(0, 0), a2, voffA);
;             PG8_BAR; PG8_WAIT_L(0); PG8_MMA(1, 0, At, B0); PG8_BAR; PG8_SCHED;
;             PG8_STAGE(PG8_SB(0, 1), b2 + hstep, voffB);
;             PG8_WAIT_V(6); PG8_BAR; PG8_MMA(1, 1, At, B1); PG8_BAR;
.LBB0_58:
	s_add_u32 s52, s50, 0x100
	s_addc_u32 s53, s51, 0
	s_cmp_eq_u32 s71, 28
	s_cselect_b32 s57, s11, s53
	s_cselect_b32 s56, s29, s52
	s_cselect_b32 s55, s41, s70
	s_cselect_b32 s54, s43, s69
	s_add_i32 m0, s25, 0xc000
	s_nop 0
	global_load_lds_dwordx4 v134, s[50:51]
	s_add_i32 m0, s25, 0xe000
	s_nop 0
	global_load_lds_dwordx4 v132, s[50:51]
	s_add_i32 s38, 0, 0x10000
	ds_read_b128 v[140:143], v226
	ds_read_b128 v[144:147], v226 offset:1024
	ds_read_b128 v[148:151], v226 offset:2048
	ds_read_b128 v[152:155], v226 offset:3072
	ds_read_b128 v[160:163], v139
	ds_read_b128 v[164:167], v139 offset:1024
	ds_read_b128 v[168:171], v139 offset:2048
	ds_read_b128 v[172:175], v139 offset:3072
	ds_read_b128 v[176:179], v139 offset:4096
	ds_read_b128 v[180:183], v139 offset:5120
	ds_read_b128 v[184:187], v139 offset:6144
	ds_read_b128 v[188:191], v139 offset:7168
	s_add_i32 s50, 0, 0x14000
	ds_read_b128 v[192:195], v226 offset:16384
	ds_read_b128 v[196:199], v226 offset:17408
	ds_read_b128 v[200:203], v226 offset:18432
	ds_read_b128 v[204:207], v226 offset:19456
	s_waitcnt lgkmcnt(4)
	s_barrier
	s_waitcnt lgkmcnt(0)
	v_mfma_f32_16x16x32_bf16 v[126:129], v[140:143], v[160:163], v[126:129]
	v_mfma_f32_16x16x32_bf16 v[122:125], v[148:151], v[160:163], v[122:125]
	v_mfma_f32_16x16x32_bf16 v[118:121], v[140:143], v[168:171], v[118:121]
	v_mfma_f32_16x16x32_bf16 v[114:117], v[148:151], v[168:171], v[114:117]
	v_mfma_f32_16x16x32_bf16 v[106:109], v[140:143], v[176:179], v[106:109]
	v_mfma_f32_16x16x32_bf16 v[98:101], v[148:151], v[176:179], v[98:101]
	v_mfma_f32_16x16x32_bf16 v[90:93], v[140:143], v[184:187], v[90:93]
	v_mfma_f32_16x16x32_bf16 v[82:85], v[148:151], v[184:187], v[82:85]
	v_mfma_f32_16x16x32_bf16 v[126:129], v[144:147], v[164:167], v[126:129]
	v_mfma_f32_16x16x32_bf16 v[122:125], v[152:155], v[164:167], v[122:125]
	v_mfma_f32_16x16x32_bf16 v[118:121], v[144:147], v[172:175], v[118:121]
	v_mfma_f32_16x16x32_bf16 v[114:117], v[152:155], v[172:175], v[114:117]
	v_mfma_f32_16x16x32_bf16 v[106:109], v[144:147], v[180:183], v[106:109]
	v_mfma_f32_16x16x32_bf16 v[98:101], v[152:155], v[180:183], v[98:101]
	v_mfma_f32_16x16x32_bf16 v[90:93], v[144:147], v[188:191], v[90:93]
	v_mfma_f32_16x16x32_bf16 v[82:85], v[152:155], v[188:191], v[82:85]
	v_mfma_f32_16x16x32_bf16 v[110:113], v[192:195], v[160:163], v[110:113]
	v_mfma_f32_16x16x32_bf16 v[102:105], v[200:203], v[160:163], v[102:105]
	v_mfma_f32_16x16x32_bf16 v[94:97], v[192:195], v[168:171], v[94:97]
	v_mfma_f32_16x16x32_bf16 v[86:89], v[200:203], v[168:171], v[86:89]
	v_mfma_f32_16x16x32_bf16 v[78:81], v[192:195], v[176:179], v[78:81]
	v_mfma_f32_16x16x32_bf16 v[74:77], v[200:203], v[176:179], v[74:77]
	v_mfma_f32_16x16x32_bf16 v[70:73], v[192:195], v[184:187], v[70:73]
	v_mfma_f32_16x16x32_bf16 v[66:69], v[200:203], v[184:187], v[66:69]
	v_mfma_f32_16x16x32_bf16 v[110:113], v[196:199], v[164:167], v[110:113]
	v_mfma_f32_16x16x32_bf16 v[102:105], v[204:207], v[164:167], v[102:105]
	v_mfma_f32_16x16x32_bf16 v[94:97], v[196:199], v[172:175], v[94:97]
	v_mfma_f32_16x16x32_bf16 v[86:89], v[204:207], v[172:175], v[86:89]
	v_mfma_f32_16x16x32_bf16 v[78:81], v[196:199], v[180:183], v[78:81]
	v_mfma_f32_16x16x32_bf16 v[74:77], v[204:207], v[180:183], v[74:77]
	v_mfma_f32_16x16x32_bf16 v[70:73], v[196:199], v[188:191], v[70:73]
	v_mfma_f32_16x16x32_bf16 v[66:69], v[204:207], v[188:191], v[66:69]
	s_barrier
	s_add_i32 s38, s38, s63
	s_mov_b32 m0, s38
	s_nop 0
	global_load_lds_dwordx4 v0, s[54:55]
	s_add_i32 m0, s38, 0x2000
	s_nop 0
	global_load_lds_dwordx4 v130, s[54:55]
	s_mov_b32 m0, s25
	s_nop 0
	global_load_lds_dwordx4 v0, s[56:57]
	s_mov_b32 m0, s27
	s_nop 0
	global_load_lds_dwordx4 v130, s[56:57]
	ds_read_b128 v[160:163], v139 offset:16384
	ds_read_b128 v[164:167], v139 offset:17408
	ds_read_b128 v[168:171], v139 offset:18432
	ds_read_b128 v[172:175], v139 offset:19456
	ds_read_b128 v[176:179], v139 offset:20480
	ds_read_b128 v[180:183], v139 offset:21504
	ds_read_b128 v[184:187], v139 offset:22528
	ds_read_b128 v[188:191], v139 offset:23552
	s_waitcnt vmcnt(4)
	s_waitcnt lgkmcnt(0)
	s_barrier
	v_mfma_f32_16x16x32_bf16 v[62:65], v[140:143], v[160:163], v[62:65]
	v_mfma_f32_16x16x32_bf16 v[58:61], v[148:151], v[160:163], v[58:61]
	v_mfma_f32_16x16x32_bf16 v[54:57], v[140:143], v[168:171], v[54:57]
	v_mfma_f32_16x16x32_bf16 v[50:53], v[148:151], v[168:171], v[50:53]
	v_mfma_f32_16x16x32_bf16 v[38:41], v[140:143], v[176:179], v[38:41]
	v_mfma_f32_16x16x32_bf16 v[34:37], v[148:151], v[176:179], v[34:37]
	v_mfma_f32_16x16x32_bf16 v[22:25], v[140:143], v[184:187], v[22:25]
	v_mfma_f32_16x16x32_bf16 v[18:21], v[148:151], v[184:187], v[18:21]
	v_mfma_f32_16x16x32_bf16 v[62:65], v[144:147], v[164:167], v[62:65]
	v_mfma_f32_16x16x32_bf16 v[58:61], v[152:155], v[164:167], v[58:61]
	v_mfma_f32_16x16x32_bf16 v[54:57], v[144:147], v[172:175], v[54:57]
	v_mfma_f32_16x16x32_bf16 v[50:53], v[152:155], v[172:175], v[50:53]
	v_mfma_f32_16x16x32_bf16 v[38:41], v[144:147], v[180:183], v[38:41]
	v_mfma_f32_16x16x32_bf16 v[34:37], v[152:155], v[180:183], v[34:37]
	v_mfma_f32_16x16x32_bf16 v[22:25], v[144:147], v[188:191], v[22:25]
	v_mfma_f32_16x16x32_bf16 v[18:21], v[152:155], v[188:191], v[18:21]
	s_add_u32 s38, s54, 0x200000
	s_addc_u32 s39, s55, 0
	s_add_i32 s50, s50, s63
	s_mov_b32 m0, s50
	s_nop 0
	global_load_lds_dwordx4 v0, s[38:39]
	s_add_i32 m0, s50, 0x2000
	s_nop 0
	global_load_lds_dwordx4 v130, s[38:39]
	v_mfma_f32_16x16x32_bf16 v[46:49], v[192:195], v[160:163], v[46:49]
	v_mfma_f32_16x16x32_bf16 v[42:45], v[200:203], v[160:163], v[42:45]
	v_mfma_f32_16x16x32_bf16 v[30:33], v[192:195], v[168:171], v[30:33]
	v_mfma_f32_16x16x32_bf16 v[26:29], v[200:203], v[168:171], v[26:29]
	v_mfma_f32_16x16x32_bf16 v[14:17], v[192:195], v[176:179], v[14:17]
	v_mfma_f32_16x16x32_bf16 v[10:13], v[200:203], v[176:179], v[10:13]
	v_mfma_f32_16x16x32_bf16 v[6:9], v[192:195], v[184:187], v[6:9]
	v_mfma_f32_16x16x32_bf16 v[2:5], v[200:203], v[184:187], v[2:5]
	v_mfma_f32_16x16x32_bf16 v[46:49], v[196:199], v[164:167], v[46:49]
	v_mfma_f32_16x16x32_bf16 v[42:45], v[204:207], v[164:167], v[42:45]
	v_mfma_f32_16x16x32_bf16 v[30:33], v[196:199], v[172:175], v[30:33]
	v_mfma_f32_16x16x32_bf16 v[26:29], v[204:207], v[172:175], v[26:29]
	v_mfma_f32_16x16x32_bf16 v[14:17], v[196:199], v[180:183], v[14:17]
	v_mfma_f32_16x16x32_bf16 v[10:13], v[204:207], v[180:183], v[10:13]
	v_mfma_f32_16x16x32_bf16 v[6:9], v[196:199], v[188:191], v[6:9]
	v_mfma_f32_16x16x32_bf16 v[2:5], v[204:207], v[188:191], v[2:5]
	s_barrier
; #define PG8_STAGE(bufoff, gbase, voff) do { _Pragma("unroll") for (int _i = 0; _i < 2; ++_i) \
;         __builtin_amdgcn_global_load_lds((const unsigned*)((const char*)(gbase) + (voff)[_i]), (LAS unsigned*)(lds + (bufoff) + ldsw + _i * 8192), 16, 0, 0); } while (0)
; #define PG8_LDA(dst, b, h) do { _Pragma("unroll") for (int m = 0; m < 4; ++m) _Pragma("unroll") for (int k = 0; k < 2; ++k) dst[m][k] = *(const LAS bf16x8*)(lds + PG8_SA(b, h) + aoff + m * 2048 + k * 1024); } while (0)
; #define PG8_LDB(dst, b, h) do { _Pragma("unroll") for (int n = 0; n < 2; ++n) _Pragma("unroll") for (int k = 0; k < 2; ++k) dst[n][k] = *(const LAS bf16x8*)(lds + PG8_SB(b, h) + boff + n * 2048 + k * 1024); } while (0)
; #define PG8_MMA(ai, bj, At, Bt) do { __builtin_amdgcn_s_setprio(1); _Pragma("unroll") for (int m = 0; m < 4; ++m) _Pragma("unroll") for (int n = 0; n < 2; ++n) _Pragma("unroll") for (int k = 0; k < 2; ++k) \
;         acc[ai][bj][m][n] = __builtin_amdgcn_mfma_f32_16x16x32_bf16(Bt[n][k], At[m][k], acc[ai][bj][m][n], 0, 0, 0); __builtin_amdgcn_s_setprio(0); } while (0)
; #define PG8_WAIT_L(n) asm volatile("s_waitcnt lgkmcnt(" #n ")" ::: "memory")
; #define PG8_BAR __builtin_amdgcn_s_barrier()
; #define PG8_SCHED __builtin_amdgcn_sched_barrier(0)
; template <class Epi, class Sched>
; __device__ __forceinline__ void gemm_phase(LAS unsigned char* lds, const Gemm g, const Sched& S, const Epi& E) {
;     ...
;             PG8_LDB(B0, 1, 0); PG8_SCHED; PG8_LDA(At, 1, 0); PG8_STAGE(PG8_SA(0, 1), a2 + hstep, voffA);
;             PG8_WAIT_L(8); PG8_BAR; PG8_WAIT_L(0); PG8_MMA(0, 0, At, B0); PG8_BAR; PG8_SCHED;
;             PG8_LDB(B1, 1, 1); PG8_STAGE(PG8_SB(1, 0), b3, voffB);
;             PG8_BAR; PG8_WAIT_L(0); PG8_MMA(0, 1, At, B1); PG8_BAR;
;             PG8_LDA(At, 1, 1); PG8_STAGE(PG8_SA(1, 0), a3, voffA);
;             PG8_BAR; PG8_WAIT_L(0); PG8_MMA(1, 0, At, B0); PG8_BAR; PG8_SCHED;
	s_add_u32 s38, s56, 0x200000
	s_addc_u32 s39, s57, 0
	s_mov_b32 m0, s64
	s_nop 0
	global_load_lds_dwordx4 v0, s[38:39]
	s_mov_b32 m0, s65
	s_nop 0
	global_load_lds_dwordx4 v130, s[38:39]
	s_add_i32 s50, 0, 0x18000
	ds_read_b128 v[140:143], v226 offset:32768
	ds_read_b128 v[144:147], v226 offset:33792
	ds_read_b128 v[148:151], v226 offset:34816
	ds_read_b128 v[152:155], v226 offset:35840
	ds_read_b128 v[160:163], v139 offset:32768
	ds_read_b128 v[164:167], v139 offset:33792
	ds_read_b128 v[168:171], v139 offset:34816
	ds_read_b128 v[172:175], v139 offset:35840
	ds_read_b128 v[176:179], v139 offset:36864
	ds_read_b128 v[180:183], v139 offset:37888
	ds_read_b128 v[184:187], v139 offset:38912
	ds_read_b128 v[188:191], v139 offset:39936
	s_add_i32 s51, 0, 0x1c000
	ds_read_b128 v[192:195], v226 offset:49152
	ds_read_b128 v[196:199], v226 offset:50176
	ds_read_b128 v[200:203], v226 offset:51200
	ds_read_b128 v[204:207], v226 offset:52224
	s_waitcnt lgkmcnt(4)
	s_barrier
	s_waitcnt lgkmcnt(0)
	v_mfma_f32_16x16x32_bf16 v[126:129], v[140:143], v[160:163], v[126:129]
	v_mfma_f32_16x16x32_bf16 v[122:125], v[148:151], v[160:163], v[122:125]
	v_mfma_f32_16x16x32_bf16 v[118:121], v[140:143], v[168:171], v[118:121]
	v_mfma_f32_16x16x32_bf16 v[114:117], v[148:151], v[168:171], v[114:117]
	v_mfma_f32_16x16x32_bf16 v[106:109], v[140:143], v[176:179], v[106:109]
	v_mfma_f32_16x16x32_bf16 v[98:101], v[148:151], v[176:179], v[98:101]
	v_mfma_f32_16x16x32_bf16 v[90:93], v[140:143], v[184:187], v[90:93]
	v_mfma_f32_16x16x32_bf16 v[82:85], v[148:151], v[184:187], v[82:85]
	v_mfma_f32_16x16x32_bf16 v[126:129], v[144:147], v[164:167], v[126:129]
	v_mfma_f32_16x16x32_bf16 v[122:125], v[152:155], v[164:167], v[122:125]
	v_mfma_f32_16x16x32_bf16 v[118:121], v[144:147], v[172:175], v[118:121]
	v_mfma_f32_16x16x32_bf16 v[114:117], v[152:155], v[172:175], v[114:117]
	v_mfma_f32_16x16x32_bf16 v[106:109], v[144:147], v[180:183], v[106:109]
	v_mfma_f32_16x16x32_bf16 v[98:101], v[152:155], v[180:183], v[98:101]
	v_mfma_f32_16x16x32_bf16 v[90:93], v[144:147], v[188:191], v[90:93]
	v_mfma_f32_16x16x32_bf16 v[82:85], v[152:155], v[188:191], v[82:85]
	v_mfma_f32_16x16x32_bf16 v[110:113], v[192:195], v[160:163], v[110:113]
	v_mfma_f32_16x16x32_bf16 v[102:105], v[200:203], v[160:163], v[102:105]
	v_mfma_f32_16x16x32_bf16 v[94:97], v[192:195], v[168:171], v[94:97]
	v_mfma_f32_16x16x32_bf16 v[86:89], v[200:203], v[168:171], v[86:89]
	v_mfma_f32_16x16x32_bf16 v[78:81], v[192:195], v[176:179], v[78:81]
	v_mfma_f32_16x16x32_bf16 v[74:77], v[200:203], v[176:179], v[74:77]
	v_mfma_f32_16x16x32_bf16 v[70:73], v[192:195], v[184:187], v[70:73]
	v_mfma_f32_16x16x32_bf16 v[66:69], v[200:203], v[184:187], v[66:69]
	v_mfma_f32_16x16x32_bf16 v[110:113], v[196:199], v[164:167], v[110:113]
	v_mfma_f32_16x16x32_bf16 v[102:105], v[204:207], v[164:167], v[102:105]
	v_mfma_f32_16x16x32_bf16 v[94:97], v[196:199], v[172:175], v[94:97]
	v_mfma_f32_16x16x32_bf16 v[86:89], v[204:207], v[172:175], v[86:89]
	v_mfma_f32_16x16x32_bf16 v[78:81], v[196:199], v[180:183], v[78:81]
	v_mfma_f32_16x16x32_bf16 v[74:77], v[204:207], v[180:183], v[74:77]
	v_mfma_f32_16x16x32_bf16 v[70:73], v[196:199], v[188:191], v[70:73]
	v_mfma_f32_16x16x32_bf16 v[66:69], v[204:207], v[188:191], v[66:69]
	s_barrier
	s_add_i32 s38, s50, s63
	s_add_u32 s100, s54, s36
	s_addc_u32 s101, s55, s37
	s_mov_b32 m0, s38
	s_nop 0
	global_load_lds_dwordx4 v0, s[100:101]
	s_add_i32 m0, s38, 0x2000
	s_nop 0
	global_load_lds_dwordx4 v130, s[100:101]
	s_mov_b32 m0, s66
	s_add_u32 s100, s56, s36
	s_addc_u32 s101, s57, s37
	global_load_lds_dwordx4 v0, s[100:101]
	s_mov_b32 m0, s67
	s_nop 0
	global_load_lds_dwordx4 v130, s[100:101]
	ds_read_b128 v[160:163], v139 offset:49152
	ds_read_b128 v[164:167], v139 offset:50176
	ds_read_b128 v[168:171], v139 offset:51200
	ds_read_b128 v[172:175], v139 offset:52224
	ds_read_b128 v[176:179], v139 offset:53248
	ds_read_b128 v[180:183], v139 offset:54272
	ds_read_b128 v[184:187], v139 offset:55296
	ds_read_b128 v[188:191], v139 offset:56320
	s_waitcnt vmcnt(4)
	s_waitcnt lgkmcnt(0)
	s_barrier
; #define PG8_STAGE(bufoff, gbase, voff) do { _Pragma("unroll") for (int _i = 0; _i < 2; ++_i) \
;         __builtin_amdgcn_global_load_lds((const unsigned*)((const char*)(gbase) + (voff)[_i]), (LAS unsigned*)(lds + (bufoff) + ldsw + _i * 8192), 16, 0, 0); } while (0)
; #define PG8_MMA(ai, bj, At, Bt) do { __builtin_amdgcn_s_setprio(1); _Pragma("unroll") for (int m = 0; m < 4; ++m) _Pragma("unroll") for (int n = 0; n < 2; ++n) _Pragma("unroll") for (int k = 0; k < 2; ++k) \
;         acc[ai][bj][m][n] = __builtin_amdgcn_mfma_f32_16x16x32_bf16(Bt[n][k], At[m][k], acc[ai][bj][m][n], 0, 0, 0); __builtin_amdgcn_s_setprio(0); } while (0)
; #define PG8_WAIT_V(n) asm volatile("s_waitcnt vmcnt(" #n ")" ::: "memory")
; #define PG8_BAR __builtin_amdgcn_s_barrier()
;     __device__ __forceinline__ void operator()(const f32x4 (&acc)[2][2][4][2], const Unit& u, int wr, int wc, int fr, int fq) const {
;         const int row0 = u.pm * BM + wr * 64 + fr, col0 = u.pn * BM + wc * 32 + 4 * fq;
;         float* base = part + (size_t)u.ks * Mp * ldc;
; #pragma unroll
;         for (int ai = 0; ai < 2; ++ai)
; #pragma unroll
;             for (int m = 0; m < 4; ++m) { float* rowp = base + (size_t)(row0 + ai * HALF + m * 16) * ldc + col0;
; #pragma unroll
;                 for (int bj = 0; bj < 2; ++bj)
; #pragma unroll
;                     for (int n = 0; n < 2; ++n) *(f32x4*)(rowp + bj * HALF + n * 16) = acc[ai][bj][m][n]; }
; template <class Epi, class Sched>
; __device__ __forceinline__ void gemm_phase(LAS unsigned char* lds, const Gemm g, const Sched& S, const Epi& E) {
;     ...
;             PG8_STAGE(PG8_SB(1, 1), b3 + hstep, voffB);
;             PG8_WAIT_V(6); PG8_BAR; PG8_MMA(1, 1, At, B1); PG8_BAR;
	v_mfma_f32_16x16x32_bf16 v[62:65], v[140:143], v[160:163], v[62:65]
	v_mfma_f32_16x16x32_bf16 v[58:61], v[148:151], v[160:163], v[58:61]
	v_mfma_f32_16x16x32_bf16 v[54:57], v[140:143], v[168:171], v[54:57]
	v_mfma_f32_16x16x32_bf16 v[50:53], v[148:151], v[168:171], v[50:53]
	v_mfma_f32_16x16x32_bf16 v[38:41], v[140:143], v[176:179], v[38:41]
	v_mfma_f32_16x16x32_bf16 v[34:37], v[148:151], v[176:179], v[34:37]
	v_mfma_f32_16x16x32_bf16 v[22:25], v[140:143], v[184:187], v[22:25]
	v_mfma_f32_16x16x32_bf16 v[18:21], v[148:151], v[184:187], v[18:21]
	v_mfma_f32_16x16x32_bf16 v[62:65], v[144:147], v[164:167], v[62:65]
	v_mfma_f32_16x16x32_bf16 v[58:61], v[152:155], v[164:167], v[58:61]
	v_mfma_f32_16x16x32_bf16 v[54:57], v[144:147], v[172:175], v[54:57]
	v_mfma_f32_16x16x32_bf16 v[50:53], v[152:155], v[172:175], v[50:53]
	v_mfma_f32_16x16x32_bf16 v[38:41], v[144:147], v[180:183], v[38:41]
	v_mfma_f32_16x16x32_bf16 v[34:37], v[152:155], v[180:183], v[34:37]
	v_mfma_f32_16x16x32_bf16 v[22:25], v[144:147], v[188:191], v[22:25]
	v_mfma_f32_16x16x32_bf16 v[18:21], v[152:155], v[188:191], v[18:21]
	s_add_u32 s38, s54, 0x200080
	s_addc_u32 s39, s55, 0
	s_add_i32 s50, s51, s63
	s_mov_b32 m0, s50
	s_nop 0
	global_load_lds_dwordx4 v0, s[38:39]
	s_add_i32 m0, s50, 0x2000
	s_nop 0
	global_load_lds_dwordx4 v130, s[38:39]
	v_mfma_f32_16x16x32_bf16 v[46:49], v[192:195], v[160:163], v[46:49]
	v_mfma_f32_16x16x32_bf16 v[42:45], v[200:203], v[160:163], v[42:45]
	v_mfma_f32_16x16x32_bf16 v[30:33], v[192:195], v[168:171], v[30:33]
	v_mfma_f32_16x16x32_bf16 v[26:29], v[200:203], v[168:171], v[26:29]
	v_mfma_f32_16x16x32_bf16 v[14:17], v[192:195], v[176:179], v[14:17]
	v_mfma_f32_16x16x32_bf16 v[10:13], v[200:203], v[176:179], v[10:13]
	v_mfma_f32_16x16x32_bf16 v[6:9], v[192:195], v[184:187], v[6:9]
	v_mfma_f32_16x16x32_bf16 v[2:5], v[200:203], v[184:187], v[2:5]
	v_mfma_f32_16x16x32_bf16 v[46:49], v[196:199], v[164:167], v[46:49]
	v_mfma_f32_16x16x32_bf16 v[42:45], v[204:207], v[164:167], v[42:45]
	v_mfma_f32_16x16x32_bf16 v[30:33], v[196:199], v[172:175], v[30:33]
	v_mfma_f32_16x16x32_bf16 v[26:29], v[204:207], v[172:175], v[26:29]
	v_mfma_f32_16x16x32_bf16 v[14:17], v[196:199], v[180:183], v[14:17]
	v_mfma_f32_16x16x32_bf16 v[10:13], v[204:207], v[180:183], v[10:13]
	v_mfma_f32_16x16x32_bf16 v[6:9], v[196:199], v[188:191], v[6:9]
	v_mfma_f32_16x16x32_bf16 v[2:5], v[204:207], v[188:191], v[2:5]
	s_add_i32 s71, s71, 2
	s_add_u32 s69, s69, 0x100
	s_addc_u32 s70, s70, 0
	s_cmp_gt_u32 s71, 29
	s_mov_b64 s[50:51], s[52:53]
	s_barrier
	s_cbranch_scc0 .LBB0_58
	s_ashr_i32 s11, s10, 31
	s_lshl_b64 s[10:11], s[10:11], 24
	v_lshl_or_b32 v140, s26, 8, v138
	s_add_u32 s10, s8, s10
	v_lshl_add_u32 v142, s24, 8, v136
	s_addc_u32 s11, s9, s11
	v_ashrrev_i32_e32 v141, 31, v140
	v_ashrrev_i32_e32 v143, 31, v142
	v_lshl_add_u64 v[140:141], v[140:141], 2, s[10:11]
	v_lshlrev_b64 v[144:145], 13, v[142:143]
	v_lshl_add_u64 v[144:145], v[140:141], 0, v[144:145]
	global_store_dwordx4 v[144:145], v[126:129], off
	global_store_dwordx4 v[144:145], v[122:125], off offset:64
	global_store_dwordx4 v[144:145], v[110:113], off offset:512
	global_store_dwordx4 v[144:145], v[102:105], off offset:576
	s_mov_b64 s[10:11], 0x100000
	s_mov_b32 s26, s40
	v_or_b32_e32 v102, 16, v142
	v_ashrrev_i32_e32 v103, 31, v102
	v_lshlrev_b64 v[102:103], 13, v[102:103]
	v_lshl_add_u64 v[102:103], v[140:141], 0, v[102:103]
	global_store_dwordx4 v[102:103], v[118:121], off
	global_store_dwordx4 v[102:103], v[114:117], off offset:64
	global_store_dwordx4 v[102:103], v[94:97], off offset:512
	global_store_dwordx4 v[102:103], v[86:89], off offset:576
	s_mov_b32 s24, s42
	s_mov_b64 s[52:53], s[48:49]
	v_or_b32_e32 v86, 32, v142
	v_ashrrev_i32_e32 v87, 31, v86
	v_lshlrev_b64 v[86:87], 13, v[86:87]
	v_lshl_add_u64 v[86:87], v[140:141], 0, v[86:87]
	global_store_dwordx4 v[86:87], v[106:109], off
	global_store_dwordx4 v[86:87], v[98:101], off offset:64
	global_store_dwordx4 v[86:87], v[78:81], off offset:512
	global_store_dwordx4 v[86:87], v[74:77], off offset:576
	s_mov_b64 s[50:51], s[46:47]
	s_nop 0
	v_or_b32_e32 v74, 48, v142
	v_ashrrev_i32_e32 v75, 31, v74
	v_lshlrev_b64 v[74:75], 13, v[74:75]
	v_lshl_add_u64 v[74:75], v[140:141], 0, v[74:75]
	global_store_dwordx4 v[74:75], v[90:93], off
	global_store_dwordx4 v[74:75], v[82:85], off offset:64
	global_store_dwordx4 v[74:75], v[70:73], off offset:512
	global_store_dwordx4 v[74:75], v[66:69], off offset:576
	s_nop 1
	v_add_co_u32_e32 v68, vcc, s93, v144
	v_lshl_add_u64 v[66:67], v[144:145], 0, s[10:11]
	s_nop 0
	v_addc_co_u32_e32 v69, vcc, 0, v145, vcc
	s_mov_b64 s[10:11], 0x120000
	global_store_dwordx4 v[68:69], v[62:65], off
	global_store_dwordx4 v[66:67], v[58:61], off offset:64
	global_store_dwordx4 v[66:67], v[46:49], off offset:512
	global_store_dwordx4 v[66:67], v[42:45], off offset:576
	s_nop 1
	v_lshl_add_u64 v[42:43], v[144:145], 0, s[10:11]
	s_mov_b32 s10, 0x120000
	v_add_co_u32_e32 v44, vcc, s10, v144
	s_mov_b64 s[10:11], 0x140000
	s_nop 0
	v_addc_co_u32_e32 v45, vcc, 0, v145, vcc
	global_store_dwordx4 v[44:45], v[54:57], off
	global_store_dwordx4 v[42:43], v[50:53], off offset:64
	global_store_dwordx4 v[42:43], v[30:33], off offset:512
	global_store_dwordx4 v[42:43], v[26:29], off offset:576
	s_nop 1
	v_lshl_add_u64 v[26:27], v[144:145], 0, s[10:11]
	s_mov_b32 s10, 0x140000
	v_add_co_u32_e32 v28, vcc, s10, v144
	s_mov_b64 s[10:11], 0x160000
	s_nop 0
	v_addc_co_u32_e32 v29, vcc, 0, v145, vcc
	global_store_dwordx4 v[28:29], v[38:41], off
	global_store_dwordx4 v[26:27], v[34:37], off offset:64
	global_store_dwordx4 v[26:27], v[14:17], off offset:512
	global_store_dwordx4 v[26:27], v[10:13], off offset:576
	s_nop 1
	v_add_co_u32_e32 v12, vcc, 0x160000, v144
	v_lshl_add_u64 v[10:11], v[144:145], 0, s[10:11]
	s_nop 0
	v_addc_co_u32_e32 v13, vcc, 0, v145, vcc
	s_and_b64 vcc, exec, s[44:45]
	s_mov_b32 s10, s28
	global_store_dwordx4 v[12:13], v[22:25], off
	global_store_dwordx4 v[10:11], v[18:21], off offset:64
	global_store_dwordx4 v[10:11], v[6:9], off offset:512
	global_store_dwordx4 v[10:11], v[2:5], off offset:576
	s_cbranch_vccz .LBB0_55
	s_waitcnt vmcnt(0)
	s_cmpk_gt_u32 s60, 0xff
	s_cbranch_scc1 .LBB0_62
	s_barrier

; #define PG8_STAGE(bufoff, gbase, voff) do { _Pragma("unroll") for (int _i = 0; _i < 2; ++_i) \
;         __builtin_amdgcn_global_load_lds((const unsigned*)((const char*)(gbase) + (voff)[_i]), (LAS unsigned*)(lds + (bufoff) + ldsw + _i * 8192), 16, 0, 0); } while (0)
; #define PG8_LDA(dst, b, h) do { _Pragma("unroll") for (int m = 0; m < 4; ++m) _Pragma("unroll") for (int k = 0; k < 2; ++k) dst[m][k] = *(const LAS bf16x8*)(lds + PG8_SA(b, h) + aoff + m * 2048 + k * 1024); } while (0)
; #define PG8_LDB(dst, b, h) do { _Pragma("unroll") for (int n = 0; n < 2; ++n) _Pragma("unroll") for (int k = 0; k < 2; ++k) dst[n][k] = *(const LAS bf16x8*)(lds + PG8_SB(b, h) + boff + n * 2048 + k * 1024); } while (0)
; #define PG8_MMA(ai, bj, At, Bt) do { __builtin_amdgcn_s_setprio(1); _Pragma("unroll") for (int m = 0; m < 4; ++m) _Pragma("unroll") for (int n = 0; n < 2; ++n) _Pragma("unroll") for (int k = 0; k < 2; ++k) \
;         acc[ai][bj][m][n] = __builtin_amdgcn_mfma_f32_16x16x32_bf16(Bt[n][k], At[m][k], acc[ai][bj][m][n], 0, 0, 0); __builtin_amdgcn_s_setprio(0); } while (0)
; #define PG8_WAIT_V(n) asm volatile("s_waitcnt vmcnt(" #n ")" ::: "memory")
; #define PG8_WAIT_L(n) asm volatile("s_waitcnt lgkmcnt(" #n ")" ::: "memory")
; template <class Epi, class Sched>
; __device__ __forceinline__ void gemm_phase(LAS unsigned char* lds, const Gemm g, const Sched& S, const Epi& E) {
;     ...
;         for (int t = 0; t < nt; t += 2) {
;             const bool last = (t == nt - 2);
;             const char* a1 = cA + (size_t)(t + 1) * kstep;
;             const char* a2 = last ? nA : cA + (size_t)(t + 2) * kstep; const char* b2 = last ? nB : cB + (size_t)(t + 2) * kstep;
;             const char* a3 = a2 + kstep; const char* b3 = b2 + kstep;
;             PG8_LDB(B0, 0, 0); PG8_SCHED; PG8_LDA(At, 0, 0); PG8_STAGE(PG8_SA(1, 1), a1 + hstep, voffA);
;             PG8_WAIT_L(8); PG8_BAR; PG8_WAIT_L(0); PG8_MMA(0, 0, At, B0); PG8_BAR; PG8_SCHED;
;             PG8_LDB(B1, 0, 1); PG8_STAGE(PG8_SB(0, 0), b2, voffB);
;             PG8_BAR; PG8_WAIT_L(0); PG8_MMA(0, 1, At, B1); PG8_BAR;
;             PG8_LDA(At, 0, 1); PG8_STAGE(PG8_SA(0, 0), a2, voffA);
;             PG8_BAR; PG8_WAIT_L(0); PG8_MMA(1, 0, At, B0); PG8_BAR; PG8_SCHED;
;             PG8_STAGE(PG8_SB(0, 1), b2 + hstep, voffB);
;             PG8_WAIT_V(6); PG8_BAR; PG8_MMA(1, 1, At, B1); PG8_BAR;
.LBB0_73:
	s_add_u32 s38, s46, 0xfff80080
	s_addc_u32 s39, s47, -1
	s_cmp_eq_u32 s73, 28
	s_cselect_b32 s51, s29, s39
	s_cselect_b32 s50, s69, s38
	s_cselect_b32 s49, s27, s72
	s_cselect_b32 s48, s70, s71
	s_add_i32 m0, s9, 0xc000
	s_nop 0
	global_load_lds_dwordx4 v138, s[46:47]
	s_add_i32 m0, s9, 0xe000
	s_nop 0
	global_load_lds_dwordx4 v136, s[46:47]
	s_add_i32 s74, 0, 0x10000
	ds_read_b128 v[146:149], v226
	ds_read_b128 v[150:153], v226 offset:1024
	ds_read_b128 v[154:157], v226 offset:2048
	ds_read_b128 v[160:163], v226 offset:3072
	ds_read_b128 v[164:167], v145
	ds_read_b128 v[168:171], v145 offset:1024
	ds_read_b128 v[172:175], v145 offset:2048
	ds_read_b128 v[176:179], v145 offset:3072
	ds_read_b128 v[180:183], v145 offset:4096
	ds_read_b128 v[184:187], v145 offset:5120
	ds_read_b128 v[188:191], v145 offset:6144
	ds_read_b128 v[192:195], v145 offset:7168
	s_add_i32 s75, 0, 0x14000
	ds_read_b128 v[196:199], v226 offset:16384
	ds_read_b128 v[200:203], v226 offset:17408
	ds_read_b128 v[204:207], v226 offset:18432
	ds_read_b128 v[210:213], v226 offset:19456
	s_waitcnt lgkmcnt(4)
	s_barrier
	s_waitcnt lgkmcnt(0)
	v_mfma_f32_16x16x32_bf16 v[126:129], v[146:149], v[164:167], v[126:129]
	v_mfma_f32_16x16x32_bf16 v[122:125], v[154:157], v[164:167], v[122:125]
	v_mfma_f32_16x16x32_bf16 v[110:113], v[146:149], v[172:175], v[110:113]
	v_mfma_f32_16x16x32_bf16 v[106:109], v[154:157], v[172:175], v[106:109]
	v_mfma_f32_16x16x32_bf16 v[94:97], v[146:149], v[180:183], v[94:97]
	v_mfma_f32_16x16x32_bf16 v[90:93], v[154:157], v[180:183], v[90:93]
	v_mfma_f32_16x16x32_bf16 v[78:81], v[146:149], v[188:191], v[78:81]
	v_mfma_f32_16x16x32_bf16 v[74:77], v[154:157], v[188:191], v[74:77]
	v_mfma_f32_16x16x32_bf16 v[126:129], v[150:153], v[168:171], v[126:129]
	v_mfma_f32_16x16x32_bf16 v[122:125], v[160:163], v[168:171], v[122:125]
	v_mfma_f32_16x16x32_bf16 v[110:113], v[150:153], v[176:179], v[110:113]
	v_mfma_f32_16x16x32_bf16 v[106:109], v[160:163], v[176:179], v[106:109]
	v_mfma_f32_16x16x32_bf16 v[94:97], v[150:153], v[184:187], v[94:97]
	v_mfma_f32_16x16x32_bf16 v[90:93], v[160:163], v[184:187], v[90:93]
	v_mfma_f32_16x16x32_bf16 v[78:81], v[150:153], v[192:195], v[78:81]
	v_mfma_f32_16x16x32_bf16 v[74:77], v[160:163], v[192:195], v[74:77]
	v_mfma_f32_16x16x32_bf16 v[118:121], v[196:199], v[164:167], v[118:121]
	v_mfma_f32_16x16x32_bf16 v[114:117], v[204:207], v[164:167], v[114:117]
	v_mfma_f32_16x16x32_bf16 v[102:105], v[196:199], v[172:175], v[102:105]
	v_mfma_f32_16x16x32_bf16 v[98:101], v[204:207], v[172:175], v[98:101]
	v_mfma_f32_16x16x32_bf16 v[86:89], v[196:199], v[180:183], v[86:89]
	v_mfma_f32_16x16x32_bf16 v[82:85], v[204:207], v[180:183], v[82:85]
	v_mfma_f32_16x16x32_bf16 v[70:73], v[196:199], v[188:191], v[70:73]
	v_mfma_f32_16x16x32_bf16 v[66:69], v[204:207], v[188:191], v[66:69]
	v_mfma_f32_16x16x32_bf16 v[118:121], v[200:203], v[168:171], v[118:121]
	v_mfma_f32_16x16x32_bf16 v[114:117], v[210:213], v[168:171], v[114:117]
	v_mfma_f32_16x16x32_bf16 v[102:105], v[200:203], v[176:179], v[102:105]
	v_mfma_f32_16x16x32_bf16 v[98:101], v[210:213], v[176:179], v[98:101]
	v_mfma_f32_16x16x32_bf16 v[86:89], v[200:203], v[184:187], v[86:89]
	v_mfma_f32_16x16x32_bf16 v[82:85], v[210:213], v[184:187], v[82:85]
	v_mfma_f32_16x16x32_bf16 v[70:73], v[200:203], v[192:195], v[70:73]
	v_mfma_f32_16x16x32_bf16 v[66:69], v[210:213], v[192:195], v[66:69]
	s_barrier
	s_add_i32 s38, s74, s56
	s_mov_b32 m0, s38
	s_nop 0
	global_load_lds_dwordx4 v0, s[48:49]
	s_add_i32 m0, s38, 0x2000
	s_nop 0
	global_load_lds_dwordx4 v130, s[48:49]
	s_mov_b32 m0, s9
	s_nop 0
	global_load_lds_dwordx4 v134, s[50:51]
	s_mov_b32 m0, s60
	s_nop 0
	global_load_lds_dwordx4 v132, s[50:51]
	ds_read_b128 v[164:167], v145 offset:16384
	ds_read_b128 v[168:171], v145 offset:17408
	ds_read_b128 v[172:175], v145 offset:18432
	ds_read_b128 v[176:179], v145 offset:19456
	ds_read_b128 v[180:183], v145 offset:20480
	ds_read_b128 v[184:187], v145 offset:21504
	ds_read_b128 v[188:191], v145 offset:22528
	ds_read_b128 v[192:195], v145 offset:23552
	s_waitcnt vmcnt(4)
	s_waitcnt lgkmcnt(0)
	s_barrier
	v_mfma_f32_16x16x32_bf16 v[62:65], v[146:149], v[164:167], v[62:65]
	v_mfma_f32_16x16x32_bf16 v[58:61], v[154:157], v[164:167], v[58:61]
	v_mfma_f32_16x16x32_bf16 v[46:49], v[146:149], v[172:175], v[46:49]
	v_mfma_f32_16x16x32_bf16 v[42:45], v[154:157], v[172:175], v[42:45]
	v_mfma_f32_16x16x32_bf16 v[30:33], v[146:149], v[180:183], v[30:33]
	v_mfma_f32_16x16x32_bf16 v[26:29], v[154:157], v[180:183], v[26:29]
	v_mfma_f32_16x16x32_bf16 v[14:17], v[146:149], v[188:191], v[14:17]
	v_mfma_f32_16x16x32_bf16 v[10:13], v[154:157], v[188:191], v[10:13]
	v_mfma_f32_16x16x32_bf16 v[62:65], v[150:153], v[168:171], v[62:65]
	v_mfma_f32_16x16x32_bf16 v[58:61], v[160:163], v[168:171], v[58:61]
	v_mfma_f32_16x16x32_bf16 v[46:49], v[150:153], v[176:179], v[46:49]
	v_mfma_f32_16x16x32_bf16 v[42:45], v[160:163], v[176:179], v[42:45]
	v_mfma_f32_16x16x32_bf16 v[30:33], v[150:153], v[184:187], v[30:33]
	v_mfma_f32_16x16x32_bf16 v[26:29], v[160:163], v[184:187], v[26:29]
	v_mfma_f32_16x16x32_bf16 v[14:17], v[150:153], v[192:195], v[14:17]
	v_mfma_f32_16x16x32_bf16 v[10:13], v[160:163], v[192:195], v[10:13]
	s_add_u32 s38, s48, 0x80000
	s_addc_u32 s39, s49, 0
	s_add_i32 s74, s75, s56
	s_mov_b32 m0, s74
	s_nop 0
	global_load_lds_dwordx4 v0, s[38:39]
	s_add_i32 m0, s74, 0x2000
	s_nop 0
	global_load_lds_dwordx4 v130, s[38:39]
	v_mfma_f32_16x16x32_bf16 v[54:57], v[196:199], v[164:167], v[54:57]
	v_mfma_f32_16x16x32_bf16 v[50:53], v[204:207], v[164:167], v[50:53]
	v_mfma_f32_16x16x32_bf16 v[38:41], v[196:199], v[172:175], v[38:41]
	v_mfma_f32_16x16x32_bf16 v[34:37], v[204:207], v[172:175], v[34:37]
	v_mfma_f32_16x16x32_bf16 v[22:25], v[196:199], v[180:183], v[22:25]
	v_mfma_f32_16x16x32_bf16 v[18:21], v[204:207], v[180:183], v[18:21]
	v_mfma_f32_16x16x32_bf16 v[6:9], v[196:199], v[188:191], v[6:9]
	v_mfma_f32_16x16x32_bf16 v[2:5], v[204:207], v[188:191], v[2:5]
	v_mfma_f32_16x16x32_bf16 v[54:57], v[200:203], v[168:171], v[54:57]
	v_mfma_f32_16x16x32_bf16 v[50:53], v[210:213], v[168:171], v[50:53]
	v_mfma_f32_16x16x32_bf16 v[38:41], v[200:203], v[176:179], v[38:41]
	v_mfma_f32_16x16x32_bf16 v[34:37], v[210:213], v[176:179], v[34:37]
	v_mfma_f32_16x16x32_bf16 v[22:25], v[200:203], v[184:187], v[22:25]
	v_mfma_f32_16x16x32_bf16 v[18:21], v[210:213], v[184:187], v[18:21]
	v_mfma_f32_16x16x32_bf16 v[6:9], v[200:203], v[192:195], v[6:9]
	v_mfma_f32_16x16x32_bf16 v[2:5], v[210:213], v[192:195], v[2:5]
	s_barrier
; #define PG8_STAGE(bufoff, gbase, voff) do { _Pragma("unroll") for (int _i = 0; _i < 2; ++_i) \
;         __builtin_amdgcn_global_load_lds((const unsigned*)((const char*)(gbase) + (voff)[_i]), (LAS unsigned*)(lds + (bufoff) + ldsw + _i * 8192), 16, 0, 0); } while (0)
; #define PG8_LDA(dst, b, h) do { _Pragma("unroll") for (int m = 0; m < 4; ++m) _Pragma("unroll") for (int k = 0; k < 2; ++k) dst[m][k] = *(const LAS bf16x8*)(lds + PG8_SA(b, h) + aoff + m * 2048 + k * 1024); } while (0)
; #define PG8_LDB(dst, b, h) do { _Pragma("unroll") for (int n = 0; n < 2; ++n) _Pragma("unroll") for (int k = 0; k < 2; ++k) dst[n][k] = *(const LAS bf16x8*)(lds + PG8_SB(b, h) + boff + n * 2048 + k * 1024); } while (0)
; #define PG8_MMA(ai, bj, At, Bt) do { __builtin_amdgcn_s_setprio(1); _Pragma("unroll") for (int m = 0; m < 4; ++m) _Pragma("unroll") for (int n = 0; n < 2; ++n) _Pragma("unroll") for (int k = 0; k < 2; ++k) \
;         acc[ai][bj][m][n] = __builtin_amdgcn_mfma_f32_16x16x32_bf16(Bt[n][k], At[m][k], acc[ai][bj][m][n], 0, 0, 0); __builtin_amdgcn_s_setprio(0); } while (0)
; #define PG8_WAIT_V(n) asm volatile("s_waitcnt vmcnt(" #n ")" ::: "memory")
; #define PG8_WAIT_L(n) asm volatile("s_waitcnt lgkmcnt(" #n ")" ::: "memory")
; #define PG8_BAR __builtin_amdgcn_s_barrier()
; #define PG8_SCHED __builtin_amdgcn_sched_barrier(0)
; template <class Epi, class Sched>
; __device__ __forceinline__ void gemm_phase(LAS unsigned char* lds, const Gemm g, const Sched& S, const Epi& E) {
;     ...
;             PG8_LDB(B0, 1, 0); PG8_SCHED; PG8_LDA(At, 1, 0); PG8_STAGE(PG8_SA(0, 1), a2 + hstep, voffA);
;             PG8_WAIT_L(8); PG8_BAR; PG8_WAIT_L(0); PG8_MMA(0, 0, At, B0); PG8_BAR; PG8_SCHED;
;             PG8_LDB(B1, 1, 1); PG8_STAGE(PG8_SB(1, 0), b3, voffB);
;             PG8_BAR; PG8_WAIT_L(0); PG8_MMA(0, 1, At, B1); PG8_BAR;
;             PG8_LDA(At, 1, 1); PG8_STAGE(PG8_SA(1, 0), a3, voffA);
;             PG8_BAR; PG8_WAIT_L(0); PG8_MMA(1, 0, At, B0); PG8_BAR; PG8_SCHED;
;             PG8_STAGE(PG8_SB(1, 1), b3 + hstep, voffB);
;             PG8_WAIT_V(6); PG8_BAR; PG8_MMA(1, 1, At, B1); PG8_BAR;
	s_add_u32 s38, s50, 0x80000
	s_addc_u32 s39, s51, 0
	s_mov_b32 m0, s61
	s_nop 0
	global_load_lds_dwordx4 v134, s[38:39]
	s_mov_b32 m0, s62
	s_nop 0
	global_load_lds_dwordx4 v132, s[38:39]
	s_add_i32 s74, 0, 0x18000
	ds_read_b128 v[146:149], v226 offset:32768
	ds_read_b128 v[150:153], v226 offset:33792
	ds_read_b128 v[154:157], v226 offset:34816
	ds_read_b128 v[160:163], v226 offset:35840
	ds_read_b128 v[164:167], v145 offset:32768
	ds_read_b128 v[168:171], v145 offset:33792
	ds_read_b128 v[172:175], v145 offset:34816
	ds_read_b128 v[176:179], v145 offset:35840
	ds_read_b128 v[180:183], v145 offset:36864
	ds_read_b128 v[184:187], v145 offset:37888
	ds_read_b128 v[188:191], v145 offset:38912
	ds_read_b128 v[192:195], v145 offset:39936
	s_nop 0
	ds_read_b128 v[196:199], v226 offset:49152
	ds_read_b128 v[200:203], v226 offset:50176
	ds_read_b128 v[204:207], v226 offset:51200
	ds_read_b128 v[210:213], v226 offset:52224
	s_waitcnt lgkmcnt(4)
	s_barrier
	s_waitcnt lgkmcnt(0)
	v_mfma_f32_16x16x32_bf16 v[126:129], v[146:149], v[164:167], v[126:129]
	v_mfma_f32_16x16x32_bf16 v[122:125], v[154:157], v[164:167], v[122:125]
	v_mfma_f32_16x16x32_bf16 v[110:113], v[146:149], v[172:175], v[110:113]
	v_mfma_f32_16x16x32_bf16 v[106:109], v[154:157], v[172:175], v[106:109]
	v_mfma_f32_16x16x32_bf16 v[94:97], v[146:149], v[180:183], v[94:97]
	v_mfma_f32_16x16x32_bf16 v[90:93], v[154:157], v[180:183], v[90:93]
	v_mfma_f32_16x16x32_bf16 v[78:81], v[146:149], v[188:191], v[78:81]
	v_mfma_f32_16x16x32_bf16 v[74:77], v[154:157], v[188:191], v[74:77]
	v_mfma_f32_16x16x32_bf16 v[126:129], v[150:153], v[168:171], v[126:129]
	v_mfma_f32_16x16x32_bf16 v[122:125], v[160:163], v[168:171], v[122:125]
	v_mfma_f32_16x16x32_bf16 v[110:113], v[150:153], v[176:179], v[110:113]
	v_mfma_f32_16x16x32_bf16 v[106:109], v[160:163], v[176:179], v[106:109]
	v_mfma_f32_16x16x32_bf16 v[94:97], v[150:153], v[184:187], v[94:97]
	v_mfma_f32_16x16x32_bf16 v[90:93], v[160:163], v[184:187], v[90:93]
	v_mfma_f32_16x16x32_bf16 v[78:81], v[150:153], v[192:195], v[78:81]
	v_mfma_f32_16x16x32_bf16 v[74:77], v[160:163], v[192:195], v[74:77]
	v_mfma_f32_16x16x32_bf16 v[118:121], v[196:199], v[164:167], v[118:121]
	v_mfma_f32_16x16x32_bf16 v[114:117], v[204:207], v[164:167], v[114:117]
	v_mfma_f32_16x16x32_bf16 v[102:105], v[196:199], v[172:175], v[102:105]
	v_mfma_f32_16x16x32_bf16 v[98:101], v[204:207], v[172:175], v[98:101]
	v_mfma_f32_16x16x32_bf16 v[86:89], v[196:199], v[180:183], v[86:89]
	v_mfma_f32_16x16x32_bf16 v[82:85], v[204:207], v[180:183], v[82:85]
	v_mfma_f32_16x16x32_bf16 v[70:73], v[196:199], v[188:191], v[70:73]
	v_mfma_f32_16x16x32_bf16 v[66:69], v[204:207], v[188:191], v[66:69]
	v_mfma_f32_16x16x32_bf16 v[118:121], v[200:203], v[168:171], v[118:121]
	v_mfma_f32_16x16x32_bf16 v[114:117], v[210:213], v[168:171], v[114:117]
	v_mfma_f32_16x16x32_bf16 v[102:105], v[200:203], v[176:179], v[102:105]
	v_mfma_f32_16x16x32_bf16 v[98:101], v[210:213], v[176:179], v[98:101]
	v_mfma_f32_16x16x32_bf16 v[86:89], v[200:203], v[184:187], v[86:89]
	v_mfma_f32_16x16x32_bf16 v[82:85], v[210:213], v[184:187], v[82:85]
	v_mfma_f32_16x16x32_bf16 v[70:73], v[200:203], v[192:195], v[70:73]
	v_mfma_f32_16x16x32_bf16 v[66:69], v[210:213], v[192:195], v[66:69]
	s_barrier
	s_add_i32 s38, s74, s56
	s_add_u32 s100, s48, s36
	s_addc_u32 s101, s49, s37
	s_mov_b32 m0, s38
	s_nop 0
	global_load_lds_dwordx4 v0, s[100:101]
	s_add_i32 m0, s38, 0x2000
	s_nop 0
	global_load_lds_dwordx4 v130, s[100:101]
	s_mov_b32 m0, s64
	s_add_u32 s100, s50, s36
	s_addc_u32 s101, s51, s37
	global_load_lds_dwordx4 v134, s[100:101]
	s_mov_b32 m0, s65
	s_nop 0
	global_load_lds_dwordx4 v132, s[100:101]
	ds_read_b128 v[164:167], v145 offset:49152
	ds_read_b128 v[168:171], v145 offset:50176
	ds_read_b128 v[172:175], v145 offset:51200
	ds_read_b128 v[176:179], v145 offset:52224
	ds_read_b128 v[180:183], v145 offset:53248
	ds_read_b128 v[184:187], v145 offset:54272
	ds_read_b128 v[188:191], v145 offset:55296
	ds_read_b128 v[192:195], v145 offset:56320
	s_waitcnt vmcnt(4)
	s_waitcnt lgkmcnt(0)
	s_barrier
	v_mfma_f32_16x16x32_bf16 v[62:65], v[146:149], v[164:167], v[62:65]
	v_mfma_f32_16x16x32_bf16 v[58:61], v[154:157], v[164:167], v[58:61]
	v_mfma_f32_16x16x32_bf16 v[46:49], v[146:149], v[172:175], v[46:49]
	v_mfma_f32_16x16x32_bf16 v[42:45], v[154:157], v[172:175], v[42:45]
	v_mfma_f32_16x16x32_bf16 v[30:33], v[146:149], v[180:183], v[30:33]
	v_mfma_f32_16x16x32_bf16 v[26:29], v[154:157], v[180:183], v[26:29]
	v_mfma_f32_16x16x32_bf16 v[14:17], v[146:149], v[188:191], v[14:17]
	v_mfma_f32_16x16x32_bf16 v[10:13], v[154:157], v[188:191], v[10:13]
	v_mfma_f32_16x16x32_bf16 v[62:65], v[150:153], v[168:171], v[62:65]
	v_mfma_f32_16x16x32_bf16 v[58:61], v[160:163], v[168:171], v[58:61]
	v_mfma_f32_16x16x32_bf16 v[46:49], v[150:153], v[176:179], v[46:49]
	v_mfma_f32_16x16x32_bf16 v[42:45], v[160:163], v[176:179], v[42:45]
	v_mfma_f32_16x16x32_bf16 v[30:33], v[150:153], v[184:187], v[30:33]
	v_mfma_f32_16x16x32_bf16 v[26:29], v[160:163], v[184:187], v[26:29]
	v_mfma_f32_16x16x32_bf16 v[14:17], v[150:153], v[192:195], v[14:17]
	v_mfma_f32_16x16x32_bf16 v[10:13], v[160:163], v[192:195], v[10:13]
	s_add_u32 s38, s48, 0x80080
	s_addc_u32 s39, s49, 0
	s_add_i32 s48, s56, 0x1c000
	s_mov_b32 m0, s48
	s_nop 0
	global_load_lds_dwordx4 v0, s[38:39]
	s_add_i32 m0, s48, 0x2000
	s_nop 0
	global_load_lds_dwordx4 v130, s[38:39]
	v_mfma_f32_16x16x32_bf16 v[54:57], v[196:199], v[164:167], v[54:57]
	v_mfma_f32_16x16x32_bf16 v[50:53], v[204:207], v[164:167], v[50:53]
	v_mfma_f32_16x16x32_bf16 v[38:41], v[196:199], v[172:175], v[38:41]
	v_mfma_f32_16x16x32_bf16 v[34:37], v[204:207], v[172:175], v[34:37]
	v_mfma_f32_16x16x32_bf16 v[22:25], v[196:199], v[180:183], v[22:25]
	v_mfma_f32_16x16x32_bf16 v[18:21], v[204:207], v[180:183], v[18:21]
	v_mfma_f32_16x16x32_bf16 v[6:9], v[196:199], v[188:191], v[6:9]
	v_mfma_f32_16x16x32_bf16 v[2:5], v[204:207], v[188:191], v[2:5]
	v_mfma_f32_16x16x32_bf16 v[54:57], v[200:203], v[168:171], v[54:57]
	v_mfma_f32_16x16x32_bf16 v[50:53], v[210:213], v[168:171], v[50:53]
	v_mfma_f32_16x16x32_bf16 v[38:41], v[200:203], v[176:179], v[38:41]
	v_mfma_f32_16x16x32_bf16 v[34:37], v[210:213], v[176:179], v[34:37]
	v_mfma_f32_16x16x32_bf16 v[22:25], v[200:203], v[184:187], v[22:25]
	v_mfma_f32_16x16x32_bf16 v[18:21], v[210:213], v[184:187], v[18:21]
	v_mfma_f32_16x16x32_bf16 v[6:9], v[200:203], v[192:195], v[6:9]
	v_mfma_f32_16x16x32_bf16 v[2:5], v[210:213], v[192:195], v[2:5]
	s_add_i32 s73, s73, 2
	s_add_u32 s71, s71, 0x100
	s_addc_u32 s72, s72, 0
	s_add_u32 s46, s46, 0x100
	s_addc_u32 s47, s47, 0
	s_cmp_gt_u32 s73, 29
	s_barrier
; __device__ __forceinline__ unsigned cvt_pk_bf16(float lo, float hi) { unsigned r; asm("v_cvt_pk_bf16_f32 %0, %1, %2" : "=v"(r) : "v"(lo), "v"(hi)); return r; }
;     __device__ __forceinline__ void operator()(const f32x4 (&acc)[2][2][4][2], const Unit& u, int wr, int wc, int fr, int fq) const {
;         const int row0 = u.pm * BM + wr * 64 + fr, col0 = u.pn * BM + wc * 32 + 8 * fq;
; #pragma unroll
;         for (int ai = 0; ai < 2; ++ai)
; #pragma unroll
;             for (int m = 0; m < 4; ++m) { bf16_t* rowp = O + (size_t)(row0 + ai * HALF + m * 16) * ldc + col0;
; #pragma unroll
;                 for (int bj = 0; bj < 2; ++bj) { f32x4 v0 = acc[ai][bj][m][0], v1 = acc[ai][bj][m][1];
;                     if (ACT == 1) {
; #pragma unroll
;                         for (int j = 0; j < 4; ++j) { float a = fmaxf(v0[j], 0.f), b = fmaxf(v1[j], 0.f); v0[j] = a * a; v1[j] = b * b; } }
;                     u32x4 w; w.x = cvt_pk_bf16(v0[0], v0[1]); w.y = cvt_pk_bf16(v0[2], v0[3]); w.z = cvt_pk_bf16(v1[0], v1[1]); w.w = cvt_pk_bf16(v1[2], v1[3]);
;                     if (ACT == 1) __builtin_nontemporal_store(w, (u32x4*)(rowp + bj * HALF));
;                     else *(u32x4*)(rowp + bj * HALF) = w; } }
	s_cbranch_scc0 .LBB0_73
	v_lshl_add_u32 v146, s8, 8, v142
	v_max_f32_e32 v122, v122, v122
	v_ashrrev_i32_e32 v147, 31, v146
	v_max_f32_e32 v122, 0, v122
	v_max_f32_e32 v123, v123, v123
	v_max_f32_e32 v124, v124, v124
	v_lshl_or_b32 v140, s68, 8, v144
	v_lshlrev_b64 v[148:149], 14, v[146:147]
	v_mul_f32_e32 v147, v122, v122
	v_max_f32_e32 v122, v127, v127
	v_max_f32_e32 v123, 0, v123
	v_max_f32_e32 v124, 0, v124
	v_ashrrev_i32_e32 v141, 31, v140
	v_max_f32_e32 v126, v126, v126
	v_max_f32_e32 v122, 0, v122
	v_mul_f32_e32 v127, v123, v123
	v_max_f32_e32 v123, v128, v128
	v_mul_f32_e32 v128, v124, v124
	v_max_f32_e32 v124, v129, v129
	v_max_f32_e32 v125, v125, v125
	v_lshl_add_u64 v[148:149], s[24:25], 0, v[148:149]
	v_lshlrev_b64 v[150:151], 1, v[140:141]
	v_max_f32_e32 v126, 0, v126
	v_mul_f32_e32 v122, v122, v122
	v_max_f32_e32 v123, 0, v123
	v_max_f32_e32 v124, 0, v124
	v_max_f32_e32 v125, 0, v125
	v_max_f32_e32 v114, v114, v114
	v_lshl_add_u64 v[140:141], v[148:149], 0, v[150:151]
	v_mul_f32_e32 v126, v126, v126
	v_mul_f32_e32 v123, v123, v123
	v_mul_f32_e32 v124, v124, v124
	v_mul_f32_e32 v125, v125, v125
	v_cvt_pk_bf16_f32 v122, v126, v122
	v_max_f32_e32 v114, 0, v114
	v_max_f32_e32 v115, v115, v115
	v_max_f32_e32 v116, v116, v116
	v_cvt_pk_bf16_f32 v123, v123, v124
	v_cvt_pk_bf16_f32 v124, v147, v127
	v_cvt_pk_bf16_f32 v125, v128, v125
	global_store_dwordx4 v[140:141], v[122:125], off nt
	v_max_f32_e32 v115, 0, v115
	v_max_f32_e32 v116, 0, v116
	v_mul_f32_e32 v122, v114, v114
	v_max_f32_e32 v114, v119, v119
	v_max_f32_e32 v118, v118, v118
	v_max_f32_e32 v114, 0, v114
	v_mul_f32_e32 v119, v115, v115
	v_max_f32_e32 v115, v120, v120
	v_mul_f32_e32 v120, v116, v116
	v_max_f32_e32 v116, v121, v121
	v_max_f32_e32 v117, v117, v117
	v_max_f32_e32 v118, 0, v118
	v_mul_f32_e32 v114, v114, v114
	v_max_f32_e32 v115, 0, v115
	v_max_f32_e32 v116, 0, v116
	v_max_f32_e32 v117, 0, v117
	v_mul_f32_e32 v118, v118, v118
	v_mul_f32_e32 v115, v115, v115
	v_mul_f32_e32 v116, v116, v116
	v_mul_f32_e32 v117, v117, v117
	v_cvt_pk_bf16_f32 v114, v118, v114
	v_max_f32_e32 v106, v106, v106
	v_cvt_pk_bf16_f32 v115, v115, v116
	v_cvt_pk_bf16_f32 v116, v122, v119
	v_cvt_pk_bf16_f32 v117, v120, v117
	global_store_dwordx4 v[140:141], v[114:117], off offset:256 nt
	v_max_f32_e32 v106, 0, v106
	v_max_f32_e32 v107, v107, v107
	v_or_b32_e32 v114, 16, v146
	v_max_f32_e32 v108, v108, v108
	v_ashrrev_i32_e32 v115, 31, v114
	v_mul_f32_e32 v116, v106, v106
	v_max_f32_e32 v106, v111, v111
	v_max_f32_e32 v107, 0, v107
	v_max_f32_e32 v108, 0, v108
	v_lshlrev_b64 v[114:115], 14, v[114:115]
	v_max_f32_e32 v110, v110, v110
	v_max_f32_e32 v106, 0, v106
	v_mul_f32_e32 v111, v107, v107
	v_max_f32_e32 v107, v112, v112
	v_mul_f32_e32 v112, v108, v108
	v_max_f32_e32 v108, v113, v113
	v_max_f32_e32 v109, v109, v109
	v_lshl_add_u64 v[114:115], s[24:25], 0, v[114:115]
	v_max_f32_e32 v110, 0, v110
	v_mul_f32_e32 v106, v106, v106
	v_max_f32_e32 v107, 0, v107
	v_max_f32_e32 v108, 0, v108
	v_max_f32_e32 v109, 0, v109
	v_max_f32_e32 v98, v98, v98
	v_lshl_add_u64 v[114:115], v[114:115], 0, v[150:151]
	v_mul_f32_e32 v110, v110, v110
	v_mul_f32_e32 v107, v107, v107
	v_mul_f32_e32 v108, v108, v108
	v_mul_f32_e32 v109, v109, v109
	v_cvt_pk_bf16_f32 v106, v110, v106
	v_max_f32_e32 v98, 0, v98
	v_max_f32_e32 v99, v99, v99
	v_max_f32_e32 v100, v100, v100
	v_cvt_pk_bf16_f32 v107, v107, v108
	v_cvt_pk_bf16_f32 v108, v116, v111
	v_cvt_pk_bf16_f32 v109, v112, v109
	global_store_dwordx4 v[114:115], v[106:109], off nt
	v_max_f32_e32 v99, 0, v99
	v_max_f32_e32 v100, 0, v100
	v_mul_f32_e32 v106, v98, v98
	v_max_f32_e32 v98, v103, v103
	v_max_f32_e32 v102, v102, v102
	v_max_f32_e32 v98, 0, v98
	v_mul_f32_e32 v103, v99, v99
	v_max_f32_e32 v99, v104, v104
	v_mul_f32_e32 v104, v100, v100
	v_max_f32_e32 v100, v105, v105
	v_max_f32_e32 v101, v101, v101
	v_max_f32_e32 v102, 0, v102
	v_mul_f32_e32 v98, v98, v98
	v_max_f32_e32 v99, 0, v99
	v_max_f32_e32 v100, 0, v100
	v_max_f32_e32 v101, 0, v101
	v_mul_f32_e32 v102, v102, v102
	v_mul_f32_e32 v99, v99, v99
	v_mul_f32_e32 v100, v100, v100
	v_mul_f32_e32 v101, v101, v101
	v_cvt_pk_bf16_f32 v98, v102, v98
	v_max_f32_e32 v90, v90, v90
	v_cvt_pk_bf16_f32 v99, v99, v100
	v_cvt_pk_bf16_f32 v100, v106, v103
	v_cvt_pk_bf16_f32 v101, v104, v101
	global_store_dwordx4 v[114:115], v[98:101], off offset:256 nt
	v_max_f32_e32 v90, 0, v90
	v_max_f32_e32 v91, v91, v91
	v_or_b32_e32 v98, 32, v146
	v_max_f32_e32 v92, v92, v92
	v_ashrrev_i32_e32 v99, 31, v98
	v_mul_f32_e32 v100, v90, v90
	v_max_f32_e32 v90, v95, v95
	v_max_f32_e32 v91, 0, v91
	v_max_f32_e32 v92, 0, v92
	v_lshlrev_b64 v[98:99], 14, v[98:99]
	v_max_f32_e32 v94, v94, v94
	v_max_f32_e32 v90, 0, v90
	v_mul_f32_e32 v95, v91, v91
	v_max_f32_e32 v91, v96, v96
	v_mul_f32_e32 v96, v92, v92
	v_max_f32_e32 v92, v97, v97
	v_max_f32_e32 v93, v93, v93
	v_lshl_add_u64 v[98:99], s[24:25], 0, v[98:99]
	v_max_f32_e32 v94, 0, v94
	v_mul_f32_e32 v90, v90, v90
	v_max_f32_e32 v91, 0, v91
	v_max_f32_e32 v92, 0, v92
	v_max_f32_e32 v93, 0, v93
	v_max_f32_e32 v82, v82, v82
	v_lshl_add_u64 v[98:99], v[98:99], 0, v[150:151]
	v_mul_f32_e32 v94, v94, v94
	v_mul_f32_e32 v91, v91, v91
	v_mul_f32_e32 v92, v92, v92
	v_mul_f32_e32 v93, v93, v93
	v_cvt_pk_bf16_f32 v90, v94, v90
	v_max_f32_e32 v82, 0, v82
	v_max_f32_e32 v83, v83, v83
	v_max_f32_e32 v84, v84, v84
	v_cvt_pk_bf16_f32 v91, v91, v92
	v_cvt_pk_bf16_f32 v92, v100, v95
	v_cvt_pk_bf16_f32 v93, v96, v93
	global_store_dwordx4 v[98:99], v[90:93], off nt
	v_max_f32_e32 v83, 0, v83
	v_max_f32_e32 v84, 0, v84
	v_mul_f32_e32 v90, v82, v82
	v_max_f32_e32 v82, v87, v87
	v_max_f32_e32 v86, v86, v86
; __device__ __forceinline__ unsigned cvt_pk_bf16(float lo, float hi) { unsigned r; asm("v_cvt_pk_bf16_f32 %0, %1, %2" : "=v"(r) : "v"(lo), "v"(hi)); return r; }
;     __device__ __forceinline__ void operator()(const f32x4 (&acc)[2][2][4][2], const Unit& u, int wr, int wc, int fr, int fq) const {
;     ...
;             for (int m = 0; m < 4; ++m) { bf16_t* rowp = O + (size_t)(row0 + ai * HALF + m * 16) * ldc + col0;
; #pragma unroll
;                 for (int bj = 0; bj < 2; ++bj) { f32x4 v0 = acc[ai][bj][m][0], v1 = acc[ai][bj][m][1];
;                     if (ACT == 1) {
; #pragma unroll
;                         for (int j = 0; j < 4; ++j) { float a = fmaxf(v0[j], 0.f), b = fmaxf(v1[j], 0.f); v0[j] = a * a; v1[j] = b * b; } }
;                     u32x4 w; w.x = cvt_pk_bf16(v0[0], v0[1]); w.y = cvt_pk_bf16(v0[2], v0[3]); w.z = cvt_pk_bf16(v1[0], v1[1]); w.w = cvt_pk_bf16(v1[2], v1[3]);
;                     if (ACT == 1) __builtin_nontemporal_store(w, (u32x4*)(rowp + bj * HALF));
;                     else *(u32x4*)(rowp + bj * HALF) = w; } }
	v_max_f32_e32 v82, 0, v82
	v_mul_f32_e32 v87, v83, v83
	v_max_f32_e32 v83, v88, v88
	v_mul_f32_e32 v88, v84, v84
	v_max_f32_e32 v84, v89, v89
	v_max_f32_e32 v85, v85, v85
	v_max_f32_e32 v86, 0, v86
	v_mul_f32_e32 v82, v82, v82
	v_max_f32_e32 v83, 0, v83
	v_max_f32_e32 v84, 0, v84
	v_max_f32_e32 v85, 0, v85
	v_mul_f32_e32 v86, v86, v86
	v_mul_f32_e32 v83, v83, v83
	v_mul_f32_e32 v84, v84, v84
	v_mul_f32_e32 v85, v85, v85
	v_cvt_pk_bf16_f32 v82, v86, v82
	v_max_f32_e32 v74, v74, v74
	v_cvt_pk_bf16_f32 v83, v83, v84
	v_cvt_pk_bf16_f32 v84, v90, v87
	v_cvt_pk_bf16_f32 v85, v88, v85
	global_store_dwordx4 v[98:99], v[82:85], off offset:256 nt
	v_max_f32_e32 v74, 0, v74
	v_max_f32_e32 v75, v75, v75
	v_or_b32_e32 v82, 48, v146
	v_max_f32_e32 v76, v76, v76
	v_ashrrev_i32_e32 v83, 31, v82
	v_mul_f32_e32 v84, v74, v74
	v_max_f32_e32 v74, v79, v79
	v_max_f32_e32 v75, 0, v75
	v_max_f32_e32 v76, 0, v76
	v_lshlrev_b64 v[82:83], 14, v[82:83]
	v_max_f32_e32 v78, v78, v78
	v_max_f32_e32 v74, 0, v74
	v_mul_f32_e32 v79, v75, v75
	v_max_f32_e32 v75, v80, v80
	v_mul_f32_e32 v80, v76, v76
	v_max_f32_e32 v76, v81, v81
	v_max_f32_e32 v77, v77, v77
	v_lshl_add_u64 v[82:83], s[24:25], 0, v[82:83]
	v_max_f32_e32 v78, 0, v78
	v_mul_f32_e32 v74, v74, v74
	v_max_f32_e32 v75, 0, v75
	v_max_f32_e32 v76, 0, v76
	v_max_f32_e32 v77, 0, v77
	v_max_f32_e32 v66, v66, v66
	v_max_f32_e32 v67, v67, v67
	v_max_f32_e32 v68, v68, v68
	v_lshl_add_u64 v[82:83], v[82:83], 0, v[150:151]
	v_mul_f32_e32 v78, v78, v78
	v_mul_f32_e32 v75, v75, v75
	v_mul_f32_e32 v76, v76, v76
	v_mul_f32_e32 v77, v77, v77
	v_cvt_pk_bf16_f32 v74, v78, v74
	v_max_f32_e32 v66, 0, v66
	v_max_f32_e32 v67, 0, v67
	v_max_f32_e32 v68, 0, v68
	v_cvt_pk_bf16_f32 v75, v75, v76
	v_cvt_pk_bf16_f32 v76, v84, v79
	v_cvt_pk_bf16_f32 v77, v80, v77
	global_store_dwordx4 v[82:83], v[74:77], off nt
	v_max_f32_e32 v69, v69, v69
	v_max_f32_e32 v70, v70, v70
	v_mul_f32_e32 v74, v66, v66
	v_max_f32_e32 v66, v71, v71
	v_mul_f32_e32 v71, v67, v67
	v_max_f32_e32 v67, v72, v72
	v_mul_f32_e32 v72, v68, v68
	v_max_f32_e32 v68, v73, v73
	v_max_f32_e32 v67, 0, v67
	v_max_f32_e32 v68, 0, v68
	v_max_f32_e32 v66, 0, v66
	v_mul_f32_e32 v67, v67, v67
	v_max_f32_e32 v69, 0, v69
	v_mul_f32_e32 v68, v68, v68
	v_max_f32_e32 v58, v58, v58
	v_max_f32_e32 v70, 0, v70
	v_mul_f32_e32 v66, v66, v66
	v_mul_f32_e32 v69, v69, v69
	v_cvt_pk_bf16_f32 v67, v67, v68
	v_cvt_pk_bf16_f32 v68, v74, v71
	v_max_f32_e32 v58, 0, v58
	v_max_f32_e32 v59, v59, v59
	v_max_f32_e32 v60, v60, v60
	v_mul_f32_e32 v70, v70, v70
	v_cvt_pk_bf16_f32 v66, v70, v66
	v_cvt_pk_bf16_f32 v69, v72, v69
	global_store_dwordx4 v[82:83], v[66:69], off offset:256 nt
	v_max_f32_e32 v62, v62, v62
	v_max_f32_e32 v59, 0, v59
	v_mul_f32_e32 v68, v58, v58
	v_max_f32_e32 v58, v63, v63
	v_max_f32_e32 v60, 0, v60
	v_max_f32_e32 v62, 0, v62
	v_max_f32_e32 v58, 0, v58
	v_mul_f32_e32 v63, v59, v59
	v_max_f32_e32 v59, v64, v64
	v_mul_f32_e32 v64, v60, v60
	v_max_f32_e32 v60, v65, v65
	v_mul_f32_e32 v62, v62, v62
	v_mul_f32_e32 v58, v58, v58
	v_max_f32_e32 v59, 0, v59
	v_max_f32_e32 v60, 0, v60
	v_max_f32_e32 v61, v61, v61
	s_mov_b32 s8, 0x200000
	v_mul_f32_e32 v59, v59, v59
	v_max_f32_e32 v61, 0, v61
	v_mul_f32_e32 v60, v60, v60
	v_cvt_pk_bf16_f32 v58, v62, v58
	v_add_co_u32_e32 v62, vcc, s8, v140
	v_max_f32_e32 v50, v50, v50
	v_max_f32_e32 v51, v51, v51
	v_max_f32_e32 v52, v52, v52
	v_mul_f32_e32 v61, v61, v61
	v_cvt_pk_bf16_f32 v59, v59, v60
	v_cvt_pk_bf16_f32 v60, v68, v63
	v_addc_co_u32_e32 v63, vcc, 0, v141, vcc
	v_max_f32_e32 v50, 0, v50
	v_max_f32_e32 v51, 0, v51
	v_max_f32_e32 v52, 0, v52
	v_cvt_pk_bf16_f32 v61, v64, v61
	global_store_dwordx4 v[62:63], v[58:61], off nt
	v_max_f32_e32 v53, v53, v53
	s_mov_b64 s[38:39], 0x200000
	v_mul_f32_e32 v58, v50, v50
	v_max_f32_e32 v50, v55, v55
	v_mul_f32_e32 v55, v51, v51
	v_max_f32_e32 v51, v56, v56
	v_mul_f32_e32 v56, v52, v52
	v_max_f32_e32 v52, v57, v57
	v_max_f32_e32 v51, 0, v51
	v_max_f32_e32 v52, 0, v52
	v_max_f32_e32 v54, v54, v54
	v_max_f32_e32 v50, 0, v50
	v_mul_f32_e32 v51, v51, v51
	v_max_f32_e32 v53, 0, v53
	v_mul_f32_e32 v52, v52, v52
	v_max_f32_e32 v42, v42, v42
	v_lshl_add_u64 v[66:67], v[140:141], 0, s[38:39]
	v_max_f32_e32 v54, 0, v54
	v_mul_f32_e32 v50, v50, v50
	v_mul_f32_e32 v53, v53, v53
	v_cvt_pk_bf16_f32 v51, v51, v52
	v_cvt_pk_bf16_f32 v52, v58, v55
	v_max_f32_e32 v42, 0, v42
	v_max_f32_e32 v43, v43, v43
	v_max_f32_e32 v44, v44, v44
	v_mul_f32_e32 v54, v54, v54
	v_cvt_pk_bf16_f32 v50, v54, v50
	v_cvt_pk_bf16_f32 v53, v56, v53
	global_store_dwordx4 v[66:67], v[50:53], off offset:256 nt
	v_max_f32_e32 v46, v46, v46
	v_max_f32_e32 v43, 0, v43
	v_mul_f32_e32 v52, v42, v42
	v_max_f32_e32 v42, v47, v47
	v_max_f32_e32 v44, 0, v44
	v_max_f32_e32 v46, 0, v46
	v_max_f32_e32 v42, 0, v42
	v_mul_f32_e32 v47, v43, v43
	v_max_f32_e32 v43, v48, v48
	v_mul_f32_e32 v48, v44, v44
	v_max_f32_e32 v44, v49, v49
	v_mul_f32_e32 v46, v46, v46
	v_mul_f32_e32 v42, v42, v42
	v_max_f32_e32 v43, 0, v43
	v_max_f32_e32 v44, 0, v44
	v_max_f32_e32 v45, v45, v45
	s_mov_b32 s8, 0x240000
	v_mul_f32_e32 v43, v43, v43
	v_max_f32_e32 v45, 0, v45
	v_mul_f32_e32 v44, v44, v44
	v_cvt_pk_bf16_f32 v42, v46, v42
; __device__ __forceinline__ unsigned cvt_pk_bf16(float lo, float hi) { unsigned r; asm("v_cvt_pk_bf16_f32 %0, %1, %2" : "=v"(r) : "v"(lo), "v"(hi)); return r; }
;     __device__ __forceinline__ void operator()(const f32x4 (&acc)[2][2][4][2], const Unit& u, int wr, int wc, int fr, int fq) const {
;     ...
;             for (int m = 0; m < 4; ++m) { bf16_t* rowp = O + (size_t)(row0 + ai * HALF + m * 16) * ldc + col0;
; #pragma unroll
;                 for (int bj = 0; bj < 2; ++bj) { f32x4 v0 = acc[ai][bj][m][0], v1 = acc[ai][bj][m][1];
;                     if (ACT == 1) {
; #pragma unroll
;                         for (int j = 0; j < 4; ++j) { float a = fmaxf(v0[j], 0.f), b = fmaxf(v1[j], 0.f); v0[j] = a * a; v1[j] = b * b; } }
;                     u32x4 w; w.x = cvt_pk_bf16(v0[0], v0[1]); w.y = cvt_pk_bf16(v0[2], v0[3]); w.z = cvt_pk_bf16(v1[0], v1[1]); w.w = cvt_pk_bf16(v1[2], v1[3]);
;                     if (ACT == 1) __builtin_nontemporal_store(w, (u32x4*)(rowp + bj * HALF));
;                     else *(u32x4*)(rowp + bj * HALF) = w; } }
	v_add_co_u32_e32 v46, vcc, s8, v140
	v_max_f32_e32 v34, v34, v34
	v_max_f32_e32 v35, v35, v35
	v_max_f32_e32 v36, v36, v36
	v_mul_f32_e32 v45, v45, v45
	v_cvt_pk_bf16_f32 v43, v43, v44
	v_cvt_pk_bf16_f32 v44, v52, v47
	v_addc_co_u32_e32 v47, vcc, 0, v141, vcc
	v_max_f32_e32 v34, 0, v34
	v_max_f32_e32 v35, 0, v35
	v_max_f32_e32 v36, 0, v36
	v_cvt_pk_bf16_f32 v45, v48, v45
	global_store_dwordx4 v[46:47], v[42:45], off nt
	v_max_f32_e32 v37, v37, v37
	s_mov_b64 s[38:39], 0x240000
	v_mul_f32_e32 v42, v34, v34
	v_max_f32_e32 v34, v39, v39
	v_mul_f32_e32 v39, v35, v35
	v_max_f32_e32 v35, v40, v40
	v_mul_f32_e32 v40, v36, v36
	v_max_f32_e32 v36, v41, v41
	v_max_f32_e32 v35, 0, v35
	v_max_f32_e32 v36, 0, v36
	v_max_f32_e32 v38, v38, v38
	v_max_f32_e32 v34, 0, v34
	v_mul_f32_e32 v35, v35, v35
	v_max_f32_e32 v37, 0, v37
	v_mul_f32_e32 v36, v36, v36
	v_max_f32_e32 v26, v26, v26
	v_lshl_add_u64 v[50:51], v[140:141], 0, s[38:39]
	v_max_f32_e32 v38, 0, v38
	v_mul_f32_e32 v34, v34, v34
	v_mul_f32_e32 v37, v37, v37
	v_cvt_pk_bf16_f32 v35, v35, v36
	v_cvt_pk_bf16_f32 v36, v42, v39
	v_max_f32_e32 v26, 0, v26
	v_max_f32_e32 v27, v27, v27
	v_max_f32_e32 v28, v28, v28
	v_mul_f32_e32 v38, v38, v38
	v_cvt_pk_bf16_f32 v34, v38, v34
	v_cvt_pk_bf16_f32 v37, v40, v37
	global_store_dwordx4 v[50:51], v[34:37], off offset:256 nt
	v_max_f32_e32 v30, v30, v30
	v_max_f32_e32 v27, 0, v27
	v_mul_f32_e32 v36, v26, v26
	v_max_f32_e32 v26, v31, v31
	v_max_f32_e32 v28, 0, v28
	v_max_f32_e32 v30, 0, v30
	v_max_f32_e32 v26, 0, v26
	v_mul_f32_e32 v31, v27, v27
	v_max_f32_e32 v27, v32, v32
	v_mul_f32_e32 v32, v28, v28
	v_max_f32_e32 v28, v33, v33
	v_mul_f32_e32 v30, v30, v30
	v_mul_f32_e32 v26, v26, v26
	v_max_f32_e32 v27, 0, v27
	v_max_f32_e32 v28, 0, v28
	v_max_f32_e32 v29, v29, v29
	s_mov_b32 s8, 0x280000
	v_mul_f32_e32 v27, v27, v27
	v_max_f32_e32 v29, 0, v29
	v_mul_f32_e32 v28, v28, v28
	v_cvt_pk_bf16_f32 v26, v30, v26
	v_add_co_u32_e32 v30, vcc, s8, v140
	v_max_f32_e32 v18, v18, v18
	v_max_f32_e32 v19, v19, v19
	v_max_f32_e32 v20, v20, v20
	v_mul_f32_e32 v29, v29, v29
	v_cvt_pk_bf16_f32 v27, v27, v28
	v_cvt_pk_bf16_f32 v28, v36, v31
	v_addc_co_u32_e32 v31, vcc, 0, v141, vcc
	v_max_f32_e32 v18, 0, v18
	v_max_f32_e32 v19, 0, v19
	v_max_f32_e32 v20, 0, v20
	v_cvt_pk_bf16_f32 v29, v32, v29
	global_store_dwordx4 v[30:31], v[26:29], off nt
	v_max_f32_e32 v21, v21, v21
	s_mov_b64 s[38:39], 0x280000
	v_mul_f32_e32 v26, v18, v18
	v_max_f32_e32 v18, v23, v23
	v_mul_f32_e32 v23, v19, v19
	v_max_f32_e32 v19, v24, v24
	v_mul_f32_e32 v24, v20, v20
	v_max_f32_e32 v20, v25, v25
	v_max_f32_e32 v19, 0, v19
	v_max_f32_e32 v20, 0, v20
	v_max_f32_e32 v22, v22, v22
	v_max_f32_e32 v18, 0, v18
	v_mul_f32_e32 v19, v19, v19
	v_max_f32_e32 v21, 0, v21
	v_mul_f32_e32 v20, v20, v20
	v_max_f32_e32 v10, v10, v10
	v_lshl_add_u64 v[34:35], v[140:141], 0, s[38:39]
	v_max_f32_e32 v22, 0, v22
	v_mul_f32_e32 v18, v18, v18
	v_mul_f32_e32 v21, v21, v21
	v_cvt_pk_bf16_f32 v19, v19, v20
	v_cvt_pk_bf16_f32 v20, v26, v23
	v_max_f32_e32 v10, 0, v10
	v_max_f32_e32 v11, v11, v11
	v_max_f32_e32 v12, v12, v12
	v_mul_f32_e32 v22, v22, v22
	v_cvt_pk_bf16_f32 v18, v22, v18
	v_cvt_pk_bf16_f32 v21, v24, v21
	global_store_dwordx4 v[34:35], v[18:21], off offset:256 nt
	v_max_f32_e32 v14, v14, v14
	v_max_f32_e32 v11, 0, v11
	v_mul_f32_e32 v20, v10, v10
	v_max_f32_e32 v10, v15, v15
	v_max_f32_e32 v12, 0, v12
	v_max_f32_e32 v14, 0, v14
	v_max_f32_e32 v10, 0, v10
	v_mul_f32_e32 v15, v11, v11
	v_max_f32_e32 v11, v16, v16
	v_mul_f32_e32 v16, v12, v12
	v_max_f32_e32 v12, v17, v17
	v_mul_f32_e32 v14, v14, v14
	v_mul_f32_e32 v10, v10, v10
	v_max_f32_e32 v11, 0, v11
	v_max_f32_e32 v12, 0, v12
	v_max_f32_e32 v13, v13, v13
	s_mov_b32 s8, 0x2c0000
	v_mul_f32_e32 v11, v11, v11
	v_max_f32_e32 v13, 0, v13
	v_mul_f32_e32 v12, v12, v12
	v_cvt_pk_bf16_f32 v10, v14, v10
	v_add_co_u32_e32 v14, vcc, s8, v140
	v_max_f32_e32 v2, v2, v2
	v_max_f32_e32 v3, v3, v3
	v_max_f32_e32 v4, v4, v4
	v_mul_f32_e32 v13, v13, v13
	v_cvt_pk_bf16_f32 v11, v11, v12
	v_cvt_pk_bf16_f32 v12, v20, v15
	v_addc_co_u32_e32 v15, vcc, 0, v141, vcc
	v_max_f32_e32 v2, 0, v2
	v_max_f32_e32 v3, 0, v3
	v_max_f32_e32 v4, 0, v4
	v_cvt_pk_bf16_f32 v13, v16, v13
	global_store_dwordx4 v[14:15], v[10:13], off nt
	v_max_f32_e32 v5, v5, v5
	s_mov_b64 s[38:39], 0x2c0000
	v_mul_f32_e32 v10, v2, v2
	v_max_f32_e32 v2, v7, v7
	v_mul_f32_e32 v7, v3, v3
	v_max_f32_e32 v3, v8, v8
	v_mul_f32_e32 v8, v4, v4
	v_max_f32_e32 v4, v9, v9
	v_max_f32_e32 v6, v6, v6
	v_max_f32_e32 v2, 0, v2
	v_max_f32_e32 v3, 0, v3
	v_max_f32_e32 v4, 0, v4
	v_max_f32_e32 v5, 0, v5
	v_lshl_add_u64 v[18:19], v[140:141], 0, s[38:39]
	v_max_f32_e32 v6, 0, v6
	v_mul_f32_e32 v2, v2, v2
	v_mul_f32_e32 v3, v3, v3
	v_mul_f32_e32 v4, v4, v4
	v_mul_f32_e32 v5, v5, v5
	s_and_b64 vcc, exec, s[40:41]
	s_mov_b32 s68, s26
	s_mov_b32 s8, s28
	s_mov_b64 s[46:47], s[44:45]
	s_mov_b64 s[48:49], s[42:43]
	v_mul_f32_e32 v6, v6, v6
	v_cvt_pk_bf16_f32 v2, v6, v2
	v_cvt_pk_bf16_f32 v3, v3, v4
	v_cvt_pk_bf16_f32 v4, v10, v7
	v_cvt_pk_bf16_f32 v5, v8, v5
	global_store_dwordx4 v[18:19], v[2:5], off offset:256 nt
	s_cbranch_vccz .LBB0_70
	s_waitcnt vmcnt(0)
	s_cmpk_gt_u32 s52, 0xff
	s_cbranch_scc1 .LBB0_77
	s_barrier

; #define PG8_STAGE(bufoff, gbase, voff) do { _Pragma("unroll") for (int _i = 0; _i < 2; ++_i) \
;         __builtin_amdgcn_global_load_lds((const unsigned*)((const char*)(gbase) + (voff)[_i]), (LAS unsigned*)(lds + (bufoff) + ldsw + _i * 8192), 16, 0, 0); } while (0)
; #define PG8_LDA(dst, b, h) do { _Pragma("unroll") for (int m = 0; m < 4; ++m) _Pragma("unroll") for (int k = 0; k < 2; ++k) dst[m][k] = *(const LAS bf16x8*)(lds + PG8_SA(b, h) + aoff + m * 2048 + k * 1024); } while (0)
; #define PG8_LDB(dst, b, h) do { _Pragma("unroll") for (int n = 0; n < 2; ++n) _Pragma("unroll") for (int k = 0; k < 2; ++k) dst[n][k] = *(const LAS bf16x8*)(lds + PG8_SB(b, h) + boff + n * 2048 + k * 1024); } while (0)
; #define PG8_MMA(ai, bj, At, Bt) do { __builtin_amdgcn_s_setprio(1); _Pragma("unroll") for (int m = 0; m < 4; ++m) _Pragma("unroll") for (int n = 0; n < 2; ++n) _Pragma("unroll") for (int k = 0; k < 2; ++k) \
;         acc[ai][bj][m][n] = __builtin_amdgcn_mfma_f32_16x16x32_bf16(Bt[n][k], At[m][k], acc[ai][bj][m][n], 0, 0, 0); __builtin_amdgcn_s_setprio(0); } while (0)
; #define PG8_WAIT_V(n) asm volatile("s_waitcnt vmcnt(" #n ")" ::: "memory")
; #define PG8_WAIT_L(n) asm volatile("s_waitcnt lgkmcnt(" #n ")" ::: "memory")
; template <class Epi, class Sched>
; __device__ __forceinline__ void gemm_phase(LAS unsigned char* lds, const Gemm g, const Sched& S, const Epi& E) {
;     ...
;         for (int t = 0; t < nt; t += 2) {
;             const bool last = (t == nt - 2);
;             const char* a1 = cA + (size_t)(t + 1) * kstep;
;             const char* a2 = last ? nA : cA + (size_t)(t + 2) * kstep; const char* b2 = last ? nB : cB + (size_t)(t + 2) * kstep;
;             const char* a3 = a2 + kstep; const char* b3 = b2 + kstep;
;             PG8_LDB(B0, 0, 0); PG8_SCHED; PG8_LDA(At, 0, 0); PG8_STAGE(PG8_SA(1, 1), a1 + hstep, voffA);
;             PG8_WAIT_L(8); PG8_BAR; PG8_WAIT_L(0); PG8_MMA(0, 0, At, B0); PG8_BAR; PG8_SCHED;
;             PG8_LDB(B1, 0, 1); PG8_STAGE(PG8_SB(0, 0), b2, voffB);
;             PG8_BAR; PG8_WAIT_L(0); PG8_MMA(0, 1, At, B1); PG8_BAR;
;             PG8_LDA(At, 0, 1); PG8_STAGE(PG8_SA(0, 0), a2, voffA);
;             PG8_BAR; PG8_WAIT_L(0); PG8_MMA(1, 0, At, B0); PG8_BAR; PG8_SCHED;
;             PG8_STAGE(PG8_SB(0, 1), b2 + hstep, voffB);
;             PG8_WAIT_V(6); PG8_BAR; PG8_MMA(1, 1, At, B1); PG8_BAR;
.LBB0_99:
	s_add_u32 s56, s28, 0x100
	s_addc_u32 s57, s29, 0
	s_cmp_eq_u32 s81, 28
	s_cselect_b32 s61, s51, s57
	s_cselect_b32 s60, s77, s56
	s_cselect_b32 s59, s49, s80
	s_cselect_b32 s58, s78, s79
	s_add_i32 m0, s9, 0xc000
	s_nop 0
	global_load_lds_dwordx4 v150, s[28:29]
	s_add_i32 m0, s9, 0xe000
	s_nop 0
	global_load_lds_dwordx4 v148, s[28:29]
	s_add_i32 s38, 0, 0x10000
	ds_read_b128 v[98:101], v226
	ds_read_b128 v[102:105], v226 offset:1024
	ds_read_b128 v[106:109], v226 offset:2048
	ds_read_b128 v[110:113], v226 offset:3072
	ds_read_b128 v[152:155], v171
	ds_read_b128 v[160:163], v171 offset:1024
	ds_read_b128 v[164:167], v171 offset:2048
	ds_read_b128 v[172:175], v171 offset:3072
	ds_read_b128 v[176:179], v171 offset:4096
	ds_read_b128 v[180:183], v171 offset:5120
	ds_read_b128 v[184:187], v171 offset:6144
	ds_read_b128 v[188:191], v171 offset:7168
	s_add_i32 s39, 0, 0x14000
	ds_read_b128 v[192:195], v226 offset:16384
	ds_read_b128 v[196:199], v226 offset:17408
	ds_read_b128 v[200:203], v226 offset:18432
	ds_read_b128 v[204:207], v226 offset:19456
	s_waitcnt lgkmcnt(4)
	s_barrier
	s_waitcnt lgkmcnt(0)
	v_mfma_f32_16x16x32_bf16 v[142:145], v[98:101], v[152:155], v[142:145]
	v_mfma_f32_16x16x32_bf16 v[138:141], v[106:109], v[152:155], v[138:141]
	v_mfma_f32_16x16x32_bf16 v[126:129], v[98:101], v[164:167], v[126:129]
	v_mfma_f32_16x16x32_bf16 v[122:125], v[106:109], v[164:167], v[122:125]
	v_mfma_f32_16x16x32_bf16 v[94:97], v[98:101], v[176:179], v[94:97]
	v_mfma_f32_16x16x32_bf16 v[90:93], v[106:109], v[176:179], v[90:93]
	v_mfma_f32_16x16x32_bf16 v[86:89], v[98:101], v[184:187], v[86:89]
	v_mfma_f32_16x16x32_bf16 v[82:85], v[106:109], v[184:187], v[82:85]
	v_mfma_f32_16x16x32_bf16 v[142:145], v[102:105], v[160:163], v[142:145]
	v_mfma_f32_16x16x32_bf16 v[138:141], v[110:113], v[160:163], v[138:141]
	v_mfma_f32_16x16x32_bf16 v[126:129], v[102:105], v[172:175], v[126:129]
	v_mfma_f32_16x16x32_bf16 v[122:125], v[110:113], v[172:175], v[122:125]
	v_mfma_f32_16x16x32_bf16 v[94:97], v[102:105], v[180:183], v[94:97]
	v_mfma_f32_16x16x32_bf16 v[90:93], v[110:113], v[180:183], v[90:93]
	v_mfma_f32_16x16x32_bf16 v[86:89], v[102:105], v[188:191], v[86:89]
	v_mfma_f32_16x16x32_bf16 v[82:85], v[110:113], v[188:191], v[82:85]
	v_mfma_f32_16x16x32_bf16 v[134:137], v[192:195], v[152:155], v[134:137]
	v_mfma_f32_16x16x32_bf16 v[130:133], v[200:203], v[152:155], v[130:133]
	v_mfma_f32_16x16x32_bf16 v[118:121], v[192:195], v[164:167], v[118:121]
	v_mfma_f32_16x16x32_bf16 v[114:117], v[200:203], v[164:167], v[114:117]
	v_mfma_f32_16x16x32_bf16 v[78:81], v[192:195], v[176:179], v[78:81]
	v_mfma_f32_16x16x32_bf16 v[74:77], v[200:203], v[176:179], v[74:77]
	v_mfma_f32_16x16x32_bf16 v[70:73], v[192:195], v[184:187], v[70:73]
	v_mfma_f32_16x16x32_bf16 v[66:69], v[200:203], v[184:187], v[66:69]
	v_mfma_f32_16x16x32_bf16 v[134:137], v[196:199], v[160:163], v[134:137]
	v_mfma_f32_16x16x32_bf16 v[130:133], v[204:207], v[160:163], v[130:133]
	v_mfma_f32_16x16x32_bf16 v[118:121], v[196:199], v[172:175], v[118:121]
	v_mfma_f32_16x16x32_bf16 v[114:117], v[204:207], v[172:175], v[114:117]
	v_mfma_f32_16x16x32_bf16 v[78:81], v[196:199], v[180:183], v[78:81]
	v_mfma_f32_16x16x32_bf16 v[74:77], v[204:207], v[180:183], v[74:77]
	v_mfma_f32_16x16x32_bf16 v[70:73], v[196:199], v[188:191], v[70:73]
	v_mfma_f32_16x16x32_bf16 v[66:69], v[204:207], v[188:191], v[66:69]
	s_barrier
	s_add_i32 s28, s38, s67
	s_mov_b32 m0, s28
	s_nop 0
	global_load_lds_dwordx4 v0, s[58:59]
	s_add_i32 m0, s28, 0x2000
	s_nop 0
	global_load_lds_dwordx4 v146, s[58:59]
	s_mov_b32 m0, s9
	s_nop 0
	global_load_lds_dwordx4 v0, s[60:61]
	s_mov_b32 m0, s68
	s_nop 0
	global_load_lds_dwordx4 v146, s[60:61]
	ds_read_b128 v[152:155], v171 offset:16384
	ds_read_b128 v[160:163], v171 offset:17408
	ds_read_b128 v[164:167], v171 offset:18432
	ds_read_b128 v[172:175], v171 offset:19456
	ds_read_b128 v[176:179], v171 offset:20480
	ds_read_b128 v[180:183], v171 offset:21504
	ds_read_b128 v[184:187], v171 offset:22528
	ds_read_b128 v[188:191], v171 offset:23552
	s_waitcnt vmcnt(4)
	s_waitcnt lgkmcnt(0)
	s_barrier
	v_mfma_f32_16x16x32_bf16 v[62:65], v[98:101], v[152:155], v[62:65]
	v_mfma_f32_16x16x32_bf16 v[58:61], v[106:109], v[152:155], v[58:61]
	v_mfma_f32_16x16x32_bf16 v[46:49], v[98:101], v[164:167], v[46:49]
	v_mfma_f32_16x16x32_bf16 v[42:45], v[106:109], v[164:167], v[42:45]
	v_mfma_f32_16x16x32_bf16 v[30:33], v[98:101], v[176:179], v[30:33]
	v_mfma_f32_16x16x32_bf16 v[26:29], v[106:109], v[176:179], v[26:29]
	v_mfma_f32_16x16x32_bf16 v[22:25], v[98:101], v[184:187], v[22:25]
	v_mfma_f32_16x16x32_bf16 v[18:21], v[106:109], v[184:187], v[18:21]
	v_mfma_f32_16x16x32_bf16 v[62:65], v[102:105], v[160:163], v[62:65]
	v_mfma_f32_16x16x32_bf16 v[58:61], v[110:113], v[160:163], v[58:61]
	v_mfma_f32_16x16x32_bf16 v[46:49], v[102:105], v[172:175], v[46:49]
	v_mfma_f32_16x16x32_bf16 v[42:45], v[110:113], v[172:175], v[42:45]
	v_mfma_f32_16x16x32_bf16 v[30:33], v[102:105], v[180:183], v[30:33]
	v_mfma_f32_16x16x32_bf16 v[26:29], v[110:113], v[180:183], v[26:29]
	v_mfma_f32_16x16x32_bf16 v[22:25], v[102:105], v[188:191], v[22:25]
	v_mfma_f32_16x16x32_bf16 v[18:21], v[110:113], v[188:191], v[18:21]
	s_add_u32 s28, s58, 0x80000
	s_addc_u32 s29, s59, 0
	s_add_i32 s38, s39, s67
	s_mov_b32 m0, s38
	s_nop 0
	global_load_lds_dwordx4 v0, s[28:29]
	s_add_i32 m0, s38, 0x2000
	s_nop 0
	global_load_lds_dwordx4 v146, s[28:29]
	v_mfma_f32_16x16x32_bf16 v[54:57], v[192:195], v[152:155], v[54:57]
	v_mfma_f32_16x16x32_bf16 v[50:53], v[200:203], v[152:155], v[50:53]
	v_mfma_f32_16x16x32_bf16 v[38:41], v[192:195], v[164:167], v[38:41]
	v_mfma_f32_16x16x32_bf16 v[34:37], v[200:203], v[164:167], v[34:37]
	v_mfma_f32_16x16x32_bf16 v[14:17], v[192:195], v[176:179], v[14:17]
	v_mfma_f32_16x16x32_bf16 v[10:13], v[200:203], v[176:179], v[10:13]
	v_mfma_f32_16x16x32_bf16 v[6:9], v[192:195], v[184:187], v[6:9]
	v_mfma_f32_16x16x32_bf16 v[2:5], v[200:203], v[184:187], v[2:5]
	v_mfma_f32_16x16x32_bf16 v[54:57], v[196:199], v[160:163], v[54:57]
	v_mfma_f32_16x16x32_bf16 v[50:53], v[204:207], v[160:163], v[50:53]
	v_mfma_f32_16x16x32_bf16 v[38:41], v[196:199], v[172:175], v[38:41]
	v_mfma_f32_16x16x32_bf16 v[34:37], v[204:207], v[172:175], v[34:37]
	v_mfma_f32_16x16x32_bf16 v[14:17], v[196:199], v[180:183], v[14:17]
	v_mfma_f32_16x16x32_bf16 v[10:13], v[204:207], v[180:183], v[10:13]
	v_mfma_f32_16x16x32_bf16 v[6:9], v[196:199], v[188:191], v[6:9]
	v_mfma_f32_16x16x32_bf16 v[2:5], v[204:207], v[188:191], v[2:5]
	s_barrier
; #define PG8_STAGE(bufoff, gbase, voff) do { _Pragma("unroll") for (int _i = 0; _i < 2; ++_i) \
;         __builtin_amdgcn_global_load_lds((const unsigned*)((const char*)(gbase) + (voff)[_i]), (LAS unsigned*)(lds + (bufoff) + ldsw + _i * 8192), 16, 0, 0); } while (0)
; #define PG8_LDA(dst, b, h) do { _Pragma("unroll") for (int m = 0; m < 4; ++m) _Pragma("unroll") for (int k = 0; k < 2; ++k) dst[m][k] = *(const LAS bf16x8*)(lds + PG8_SA(b, h) + aoff + m * 2048 + k * 1024); } while (0)
; #define PG8_LDB(dst, b, h) do { _Pragma("unroll") for (int n = 0; n < 2; ++n) _Pragma("unroll") for (int k = 0; k < 2; ++k) dst[n][k] = *(const LAS bf16x8*)(lds + PG8_SB(b, h) + boff + n * 2048 + k * 1024); } while (0)
; #define PG8_WAIT_V(n) asm volatile("s_waitcnt vmcnt(" #n ")" ::: "memory")
; #define PG8_WAIT_L(n) asm volatile("s_waitcnt lgkmcnt(" #n ")" ::: "memory")
; #define PG8_BAR __builtin_amdgcn_s_barrier()
; #define PG8_SCHED __builtin_amdgcn_sched_barrier(0)
; template <class Epi, class Sched>
; __device__ __forceinline__ void gemm_phase(LAS unsigned char* lds, const Gemm g, const Sched& S, const Epi& E) {
;     ...
;             PG8_LDB(B0, 0, 0); PG8_SCHED; PG8_LDA(At, 0, 0); PG8_STAGE(PG8_SA(1, 1), a1 + hstep, voffA);
;             PG8_WAIT_L(8); PG8_BAR; PG8_WAIT_L(0); PG8_MMA(0, 0, At, B0); PG8_BAR; PG8_SCHED;
;             PG8_LDB(B1, 0, 1); PG8_STAGE(PG8_SB(0, 0), b2, voffB);
;             PG8_BAR; PG8_WAIT_L(0); PG8_MMA(0, 1, At, B1); PG8_BAR;
;             PG8_LDA(At, 0, 1); PG8_STAGE(PG8_SA(0, 0), a2, voffA);
;             PG8_BAR; PG8_WAIT_L(0); PG8_MMA(1, 0, At, B0); PG8_BAR; PG8_SCHED;
;             PG8_STAGE(PG8_SB(0, 1), b2 + hstep, voffB);
;             PG8_WAIT_V(6); PG8_BAR; PG8_MMA(1, 1, At, B1); PG8_BAR;
;             PG8_LDB(B0, 1, 0); PG8_SCHED; PG8_LDA(At, 1, 0); PG8_STAGE(PG8_SA(0, 1), a2 + hstep, voffA);
;             PG8_WAIT_L(8); PG8_BAR; PG8_WAIT_L(0); PG8_MMA(0, 0, At, B0); PG8_BAR; PG8_SCHED;
;             PG8_LDB(B1, 1, 1); PG8_STAGE(PG8_SB(1, 0), b3, voffB);
;             PG8_BAR; PG8_WAIT_L(0); PG8_MMA(0, 1, At, B1); PG8_BAR;
;             PG8_LDA(At, 1, 1); PG8_STAGE(PG8_SA(1, 0), a3, voffA);
;             PG8_BAR; PG8_WAIT_L(0); PG8_MMA(1, 0, At, B0); PG8_BAR; PG8_SCHED;
;             PG8_STAGE(PG8_SB(1, 1), b3 + hstep, voffB);
;             PG8_WAIT_V(6); PG8_BAR; PG8_MMA(1, 1, At, B1); PG8_BAR;
	s_add_u32 s28, s60, 0x80000
	s_addc_u32 s29, s61, 0
	s_mov_b32 m0, s69
	s_nop 0
	global_load_lds_dwordx4 v0, s[28:29]
	s_mov_b32 m0, s70
	s_nop 0
	global_load_lds_dwordx4 v146, s[28:29]
	s_add_i32 s38, 0, 0x18000
	ds_read_b128 v[98:101], v226 offset:32768
	ds_read_b128 v[102:105], v226 offset:33792
	ds_read_b128 v[106:109], v226 offset:34816
	ds_read_b128 v[110:113], v226 offset:35840
	ds_read_b128 v[152:155], v171 offset:32768
	ds_read_b128 v[160:163], v171 offset:33792
	ds_read_b128 v[164:167], v171 offset:34816
	ds_read_b128 v[172:175], v171 offset:35840
	ds_read_b128 v[176:179], v171 offset:36864
	ds_read_b128 v[180:183], v171 offset:37888
	ds_read_b128 v[184:187], v171 offset:38912
	ds_read_b128 v[188:191], v171 offset:39936
	s_add_i32 s39, 0, 0x1c000
	ds_read_b128 v[192:195], v226 offset:49152
	ds_read_b128 v[196:199], v226 offset:50176
	ds_read_b128 v[200:203], v226 offset:51200
	ds_read_b128 v[204:207], v226 offset:52224
	s_waitcnt lgkmcnt(4)
	s_barrier
	s_waitcnt lgkmcnt(0)
	v_mfma_f32_16x16x32_bf16 v[142:145], v[98:101], v[152:155], v[142:145]
	v_mfma_f32_16x16x32_bf16 v[138:141], v[106:109], v[152:155], v[138:141]
	v_mfma_f32_16x16x32_bf16 v[126:129], v[98:101], v[164:167], v[126:129]
	v_mfma_f32_16x16x32_bf16 v[122:125], v[106:109], v[164:167], v[122:125]
	v_mfma_f32_16x16x32_bf16 v[94:97], v[98:101], v[176:179], v[94:97]
	v_mfma_f32_16x16x32_bf16 v[90:93], v[106:109], v[176:179], v[90:93]
	v_mfma_f32_16x16x32_bf16 v[86:89], v[98:101], v[184:187], v[86:89]
	v_mfma_f32_16x16x32_bf16 v[82:85], v[106:109], v[184:187], v[82:85]
	v_mfma_f32_16x16x32_bf16 v[142:145], v[102:105], v[160:163], v[142:145]
	v_mfma_f32_16x16x32_bf16 v[138:141], v[110:113], v[160:163], v[138:141]
	v_mfma_f32_16x16x32_bf16 v[126:129], v[102:105], v[172:175], v[126:129]
	v_mfma_f32_16x16x32_bf16 v[122:125], v[110:113], v[172:175], v[122:125]
	v_mfma_f32_16x16x32_bf16 v[94:97], v[102:105], v[180:183], v[94:97]
	v_mfma_f32_16x16x32_bf16 v[90:93], v[110:113], v[180:183], v[90:93]
	v_mfma_f32_16x16x32_bf16 v[86:89], v[102:105], v[188:191], v[86:89]
	v_mfma_f32_16x16x32_bf16 v[82:85], v[110:113], v[188:191], v[82:85]
	v_mfma_f32_16x16x32_bf16 v[134:137], v[192:195], v[152:155], v[134:137]
	v_mfma_f32_16x16x32_bf16 v[130:133], v[200:203], v[152:155], v[130:133]
	v_mfma_f32_16x16x32_bf16 v[118:121], v[192:195], v[164:167], v[118:121]
	v_mfma_f32_16x16x32_bf16 v[114:117], v[200:203], v[164:167], v[114:117]
	v_mfma_f32_16x16x32_bf16 v[78:81], v[192:195], v[176:179], v[78:81]
	v_mfma_f32_16x16x32_bf16 v[74:77], v[200:203], v[176:179], v[74:77]
	v_mfma_f32_16x16x32_bf16 v[70:73], v[192:195], v[184:187], v[70:73]
	v_mfma_f32_16x16x32_bf16 v[66:69], v[200:203], v[184:187], v[66:69]
	v_mfma_f32_16x16x32_bf16 v[134:137], v[196:199], v[160:163], v[134:137]
	v_mfma_f32_16x16x32_bf16 v[130:133], v[204:207], v[160:163], v[130:133]
	v_mfma_f32_16x16x32_bf16 v[118:121], v[196:199], v[172:175], v[118:121]
	v_mfma_f32_16x16x32_bf16 v[114:117], v[204:207], v[172:175], v[114:117]
	v_mfma_f32_16x16x32_bf16 v[78:81], v[196:199], v[180:183], v[78:81]
	v_mfma_f32_16x16x32_bf16 v[74:77], v[204:207], v[180:183], v[74:77]
	v_mfma_f32_16x16x32_bf16 v[70:73], v[196:199], v[188:191], v[70:73]
	v_mfma_f32_16x16x32_bf16 v[66:69], v[204:207], v[188:191], v[66:69]
	s_barrier
	s_add_i32 s28, s38, s67
	s_add_u32 s100, s58, s36
	s_addc_u32 s101, s59, s37
	s_mov_b32 m0, s28
	s_nop 0
	global_load_lds_dwordx4 v0, s[100:101]
	s_add_i32 m0, s28, 0x2000
	s_nop 0
	global_load_lds_dwordx4 v146, s[100:101]
	s_mov_b32 m0, s72
	s_add_u32 s100, s60, s36
	s_addc_u32 s101, s61, s37
	global_load_lds_dwordx4 v0, s[100:101]
	s_mov_b32 m0, s73
	s_nop 0
	global_load_lds_dwordx4 v146, s[100:101]
	ds_read_b128 v[152:155], v171 offset:49152
	ds_read_b128 v[160:163], v171 offset:50176
	ds_read_b128 v[164:167], v171 offset:51200
	ds_read_b128 v[172:175], v171 offset:52224
	ds_read_b128 v[176:179], v171 offset:53248
	ds_read_b128 v[180:183], v171 offset:54272
	ds_read_b128 v[184:187], v171 offset:55296
	ds_read_b128 v[188:191], v171 offset:56320
	s_waitcnt vmcnt(4)
	s_waitcnt lgkmcnt(0)
	s_barrier
	v_mfma_f32_16x16x32_bf16 v[62:65], v[98:101], v[152:155], v[62:65]
	v_mfma_f32_16x16x32_bf16 v[58:61], v[106:109], v[152:155], v[58:61]
	v_mfma_f32_16x16x32_bf16 v[46:49], v[98:101], v[164:167], v[46:49]
	v_mfma_f32_16x16x32_bf16 v[42:45], v[106:109], v[164:167], v[42:45]
	v_mfma_f32_16x16x32_bf16 v[30:33], v[98:101], v[176:179], v[30:33]
	v_mfma_f32_16x16x32_bf16 v[26:29], v[106:109], v[176:179], v[26:29]
	v_mfma_f32_16x16x32_bf16 v[22:25], v[98:101], v[184:187], v[22:25]
	v_mfma_f32_16x16x32_bf16 v[18:21], v[106:109], v[184:187], v[18:21]
	v_mfma_f32_16x16x32_bf16 v[62:65], v[102:105], v[160:163], v[62:65]
	v_mfma_f32_16x16x32_bf16 v[58:61], v[110:113], v[160:163], v[58:61]
	v_mfma_f32_16x16x32_bf16 v[46:49], v[102:105], v[172:175], v[46:49]
	v_mfma_f32_16x16x32_bf16 v[42:45], v[110:113], v[172:175], v[42:45]
	v_mfma_f32_16x16x32_bf16 v[30:33], v[102:105], v[180:183], v[30:33]
	v_mfma_f32_16x16x32_bf16 v[26:29], v[110:113], v[180:183], v[26:29]
	v_mfma_f32_16x16x32_bf16 v[22:25], v[102:105], v[188:191], v[22:25]
	v_mfma_f32_16x16x32_bf16 v[18:21], v[110:113], v[188:191], v[18:21]
	s_add_u32 s28, s58, 0x80080
	s_addc_u32 s29, s59, 0
	s_add_i32 s38, s39, s67
	s_mov_b32 m0, s38
	s_nop 0
	global_load_lds_dwordx4 v0, s[28:29]
	s_add_i32 m0, s38, 0x2000
	s_nop 0
	global_load_lds_dwordx4 v146, s[28:29]
	v_mfma_f32_16x16x32_bf16 v[54:57], v[192:195], v[152:155], v[54:57]
	v_mfma_f32_16x16x32_bf16 v[50:53], v[200:203], v[152:155], v[50:53]
	v_mfma_f32_16x16x32_bf16 v[38:41], v[192:195], v[164:167], v[38:41]
	v_mfma_f32_16x16x32_bf16 v[34:37], v[200:203], v[164:167], v[34:37]
	v_mfma_f32_16x16x32_bf16 v[14:17], v[192:195], v[176:179], v[14:17]
	v_mfma_f32_16x16x32_bf16 v[10:13], v[200:203], v[176:179], v[10:13]
	v_mfma_f32_16x16x32_bf16 v[6:9], v[192:195], v[184:187], v[6:9]
	v_mfma_f32_16x16x32_bf16 v[2:5], v[200:203], v[184:187], v[2:5]
	v_mfma_f32_16x16x32_bf16 v[54:57], v[196:199], v[160:163], v[54:57]
	v_mfma_f32_16x16x32_bf16 v[50:53], v[204:207], v[160:163], v[50:53]
	v_mfma_f32_16x16x32_bf16 v[38:41], v[196:199], v[172:175], v[38:41]
	v_mfma_f32_16x16x32_bf16 v[34:37], v[204:207], v[172:175], v[34:37]
	v_mfma_f32_16x16x32_bf16 v[14:17], v[196:199], v[180:183], v[14:17]
	v_mfma_f32_16x16x32_bf16 v[10:13], v[204:207], v[180:183], v[10:13]
	v_mfma_f32_16x16x32_bf16 v[6:9], v[196:199], v[188:191], v[6:9]
	v_mfma_f32_16x16x32_bf16 v[2:5], v[204:207], v[188:191], v[2:5]
	s_add_i32 s81, s81, 2
	s_add_u32 s79, s79, 0x100
	s_addc_u32 s80, s80, 0
	s_cmp_gt_u32 s81, 29
	s_mov_b64 s[28:29], s[56:57]
	s_barrier
	s_cbranch_scc0 .LBB0_99
	s_cmp_lt_i32 s8, 64
	s_cselect_b64 s[58:59], -1, 0
	s_cmp_gt_i32 s8, 63
	s_cbranch_scc0 .LBB0_90
	s_mov_b64 s[60:61], 0x18000
	s_mov_b64 s[28:29], s[46:47]
	s_mov_b64 s[56:57], s[24:25]
	s_branch .LBB0_91

; #define PG8_STAGE(bufoff, gbase, voff) do { _Pragma("unroll") for (int _i = 0; _i < 2; ++_i) \
;         __builtin_amdgcn_global_load_lds((const unsigned*)((const char*)(gbase) + (voff)[_i]), (LAS unsigned*)(lds + (bufoff) + ldsw + _i * 8192), 16, 0, 0); } while (0)
; #define PG8_LDA(dst, b, h) do { _Pragma("unroll") for (int m = 0; m < 4; ++m) _Pragma("unroll") for (int k = 0; k < 2; ++k) dst[m][k] = *(const LAS bf16x8*)(lds + PG8_SA(b, h) + aoff + m * 2048 + k * 1024); } while (0)
; #define PG8_WAIT_V(n) asm volatile("s_waitcnt vmcnt(" #n ")" ::: "memory")
; #define PG8_WAIT_L(n) asm volatile("s_waitcnt lgkmcnt(" #n ")" ::: "memory")
; #define PG8_BAR __builtin_amdgcn_s_barrier()
; template <class Epi, class Sched>
; __device__ __forceinline__ void gemm_phase(LAS unsigned char* lds, const Gemm g, const Sched& S, const Epi& E) {
;     ...
;             const bool last = (t == nt - 2);
;             const char* a1 = cA + (size_t)(t + 1) * kstep;
;             const char* a2 = last ? nA : cA + (size_t)(t + 2) * kstep; const char* b2 = last ? nB : cB + (size_t)(t + 2) * kstep;
;             const char* a3 = a2 + kstep; const char* b3 = b2 + kstep;
;             PG8_LDB(B0, 0, 0); PG8_SCHED; PG8_LDA(At, 0, 0); PG8_STAGE(PG8_SA(1, 1), a1 + hstep, voffA);
;             PG8_WAIT_L(8); PG8_BAR; PG8_WAIT_L(0); PG8_MMA(0, 0, At, B0); PG8_BAR; PG8_SCHED;
;             PG8_LDB(B1, 0, 1); PG8_STAGE(PG8_SB(0, 0), b2, voffB);
;             PG8_BAR; PG8_WAIT_L(0); PG8_MMA(0, 1, At, B1); PG8_BAR;
;             PG8_LDA(At, 0, 1); PG8_STAGE(PG8_SA(0, 0), a2, voffA);
;             PG8_BAR; PG8_WAIT_L(0); PG8_MMA(1, 0, At, B0); PG8_BAR; PG8_SCHED;
;             PG8_STAGE(PG8_SB(0, 1), b2 + hstep, voffB);
;             PG8_WAIT_V(6); PG8_BAR; PG8_MMA(1, 1, At, B1); PG8_BAR;
;             PG8_LDB(B0, 1, 0); PG8_SCHED; PG8_LDA(At, 1, 0); PG8_STAGE(PG8_SA(0, 1), a2 + hstep, voffA);
;             PG8_WAIT_L(8); PG8_BAR; PG8_WAIT_L(0); PG8_MMA(0, 0, At, B0); PG8_BAR; PG8_SCHED;
;             PG8_LDB(B1, 1, 1); PG8_STAGE(PG8_SB(1, 0), b3, voffB);
;             PG8_BAR; PG8_WAIT_L(0); PG8_MMA(0, 1, At, B1); PG8_BAR;
;             PG8_LDA(At, 1, 1); PG8_STAGE(PG8_SA(1, 0), a3, voffA);
;             PG8_BAR; PG8_WAIT_L(0); PG8_MMA(1, 0, At, B0); PG8_BAR; PG8_SCHED;
;             PG8_STAGE(PG8_SB(1, 1), b3 + hstep, voffB);
;             PG8_WAIT_V(6); PG8_BAR; PG8_MMA(1, 1, At, B1); PG8_BAR;
.LBB0_113:
	s_add_u32 s54, s52, 0x100
	s_addc_u32 s55, s53, 0
	s_cmp_eq_u32 s73, 4
	s_cselect_b32 s59, s11, s55
	s_cselect_b32 s58, s29, s54
	s_cselect_b32 s57, s41, s72
	s_cselect_b32 s56, s45, s71
	s_add_i32 m0, s25, 0xc000
	s_nop 0
	global_load_lds_dwordx4 v134, s[52:53]
	s_add_i32 m0, s25, 0xe000
	s_nop 0
	global_load_lds_dwordx4 v132, s[52:53]
	s_add_i32 s38, 0, 0x10000
	ds_read_b128 v[140:143], v226
	ds_read_b128 v[144:147], v226 offset:1024
	ds_read_b128 v[148:151], v226 offset:2048
	ds_read_b128 v[152:155], v226 offset:3072
	ds_read_b128 v[160:163], v139
	ds_read_b128 v[164:167], v139 offset:1024
	ds_read_b128 v[168:171], v139 offset:2048
	ds_read_b128 v[172:175], v139 offset:3072
	ds_read_b128 v[176:179], v139 offset:4096
	ds_read_b128 v[180:183], v139 offset:5120
	ds_read_b128 v[184:187], v139 offset:6144
	ds_read_b128 v[188:191], v139 offset:7168
	s_add_i32 s52, 0, 0x14000
	ds_read_b128 v[192:195], v226 offset:16384
	ds_read_b128 v[196:199], v226 offset:17408
	ds_read_b128 v[200:203], v226 offset:18432
	ds_read_b128 v[204:207], v226 offset:19456
	s_waitcnt lgkmcnt(4)
	s_barrier
	s_waitcnt lgkmcnt(0)
	v_mfma_f32_16x16x32_bf16 v[126:129], v[140:143], v[160:163], v[126:129]
	v_mfma_f32_16x16x32_bf16 v[122:125], v[148:151], v[160:163], v[122:125]
	v_mfma_f32_16x16x32_bf16 v[118:121], v[140:143], v[168:171], v[118:121]
	v_mfma_f32_16x16x32_bf16 v[114:117], v[148:151], v[168:171], v[114:117]
	v_mfma_f32_16x16x32_bf16 v[106:109], v[140:143], v[176:179], v[106:109]
	v_mfma_f32_16x16x32_bf16 v[98:101], v[148:151], v[176:179], v[98:101]
	v_mfma_f32_16x16x32_bf16 v[90:93], v[140:143], v[184:187], v[90:93]
	v_mfma_f32_16x16x32_bf16 v[82:85], v[148:151], v[184:187], v[82:85]
	v_mfma_f32_16x16x32_bf16 v[126:129], v[144:147], v[164:167], v[126:129]
	v_mfma_f32_16x16x32_bf16 v[122:125], v[152:155], v[164:167], v[122:125]
	v_mfma_f32_16x16x32_bf16 v[118:121], v[144:147], v[172:175], v[118:121]
	v_mfma_f32_16x16x32_bf16 v[114:117], v[152:155], v[172:175], v[114:117]
	v_mfma_f32_16x16x32_bf16 v[106:109], v[144:147], v[180:183], v[106:109]
	v_mfma_f32_16x16x32_bf16 v[98:101], v[152:155], v[180:183], v[98:101]
	v_mfma_f32_16x16x32_bf16 v[90:93], v[144:147], v[188:191], v[90:93]
	v_mfma_f32_16x16x32_bf16 v[82:85], v[152:155], v[188:191], v[82:85]
	v_mfma_f32_16x16x32_bf16 v[110:113], v[192:195], v[160:163], v[110:113]
	v_mfma_f32_16x16x32_bf16 v[102:105], v[200:203], v[160:163], v[102:105]
	v_mfma_f32_16x16x32_bf16 v[94:97], v[192:195], v[168:171], v[94:97]
	v_mfma_f32_16x16x32_bf16 v[86:89], v[200:203], v[168:171], v[86:89]
	v_mfma_f32_16x16x32_bf16 v[78:81], v[192:195], v[176:179], v[78:81]
	v_mfma_f32_16x16x32_bf16 v[74:77], v[200:203], v[176:179], v[74:77]
	v_mfma_f32_16x16x32_bf16 v[70:73], v[192:195], v[184:187], v[70:73]
	v_mfma_f32_16x16x32_bf16 v[66:69], v[200:203], v[184:187], v[66:69]
	v_mfma_f32_16x16x32_bf16 v[110:113], v[196:199], v[164:167], v[110:113]
	v_mfma_f32_16x16x32_bf16 v[102:105], v[204:207], v[164:167], v[102:105]
	v_mfma_f32_16x16x32_bf16 v[94:97], v[196:199], v[172:175], v[94:97]
	v_mfma_f32_16x16x32_bf16 v[86:89], v[204:207], v[172:175], v[86:89]
	v_mfma_f32_16x16x32_bf16 v[78:81], v[196:199], v[180:183], v[78:81]
	v_mfma_f32_16x16x32_bf16 v[74:77], v[204:207], v[180:183], v[74:77]
	v_mfma_f32_16x16x32_bf16 v[70:73], v[196:199], v[188:191], v[70:73]
	v_mfma_f32_16x16x32_bf16 v[66:69], v[204:207], v[188:191], v[66:69]
	s_barrier
	s_add_i32 s38, s38, s65
	s_mov_b32 m0, s38
	s_nop 0
	global_load_lds_dwordx4 v0, s[56:57]
	s_add_i32 m0, s38, 0x2000
	s_nop 0
	global_load_lds_dwordx4 v130, s[56:57]
	s_mov_b32 m0, s25
	s_nop 0
	global_load_lds_dwordx4 v0, s[58:59]
	s_mov_b32 m0, s27
	s_nop 0
	global_load_lds_dwordx4 v130, s[58:59]
	ds_read_b128 v[160:163], v139 offset:16384
	ds_read_b128 v[164:167], v139 offset:17408
	ds_read_b128 v[168:171], v139 offset:18432
	ds_read_b128 v[172:175], v139 offset:19456
	ds_read_b128 v[176:179], v139 offset:20480
	ds_read_b128 v[180:183], v139 offset:21504
	ds_read_b128 v[184:187], v139 offset:22528
	ds_read_b128 v[188:191], v139 offset:23552
	s_waitcnt vmcnt(4)
	s_waitcnt lgkmcnt(0)
	s_barrier
	v_mfma_f32_16x16x32_bf16 v[62:65], v[140:143], v[160:163], v[62:65]
	v_mfma_f32_16x16x32_bf16 v[58:61], v[148:151], v[160:163], v[58:61]
	v_mfma_f32_16x16x32_bf16 v[54:57], v[140:143], v[168:171], v[54:57]
	v_mfma_f32_16x16x32_bf16 v[50:53], v[148:151], v[168:171], v[50:53]
	v_mfma_f32_16x16x32_bf16 v[38:41], v[140:143], v[176:179], v[38:41]
	v_mfma_f32_16x16x32_bf16 v[34:37], v[148:151], v[176:179], v[34:37]
	v_mfma_f32_16x16x32_bf16 v[22:25], v[140:143], v[184:187], v[22:25]
	v_mfma_f32_16x16x32_bf16 v[18:21], v[148:151], v[184:187], v[18:21]
	v_mfma_f32_16x16x32_bf16 v[62:65], v[144:147], v[164:167], v[62:65]
	v_mfma_f32_16x16x32_bf16 v[58:61], v[152:155], v[164:167], v[58:61]
	v_mfma_f32_16x16x32_bf16 v[54:57], v[144:147], v[172:175], v[54:57]
	v_mfma_f32_16x16x32_bf16 v[50:53], v[152:155], v[172:175], v[50:53]
	v_mfma_f32_16x16x32_bf16 v[38:41], v[144:147], v[180:183], v[38:41]
	v_mfma_f32_16x16x32_bf16 v[34:37], v[152:155], v[180:183], v[34:37]
	v_mfma_f32_16x16x32_bf16 v[22:25], v[144:147], v[188:191], v[22:25]
	v_mfma_f32_16x16x32_bf16 v[18:21], v[152:155], v[188:191], v[18:21]
	s_add_u32 s38, s56, 0x80000
	s_addc_u32 s39, s57, 0
	s_add_i32 s52, s52, s65
	s_mov_b32 m0, s52
	s_nop 0
	global_load_lds_dwordx4 v0, s[38:39]
	s_add_i32 m0, s52, 0x2000
	s_nop 0
	global_load_lds_dwordx4 v130, s[38:39]
	v_mfma_f32_16x16x32_bf16 v[46:49], v[192:195], v[160:163], v[46:49]
	v_mfma_f32_16x16x32_bf16 v[42:45], v[200:203], v[160:163], v[42:45]
	v_mfma_f32_16x16x32_bf16 v[30:33], v[192:195], v[168:171], v[30:33]
	v_mfma_f32_16x16x32_bf16 v[26:29], v[200:203], v[168:171], v[26:29]
	v_mfma_f32_16x16x32_bf16 v[14:17], v[192:195], v[176:179], v[14:17]
	v_mfma_f32_16x16x32_bf16 v[10:13], v[200:203], v[176:179], v[10:13]
	v_mfma_f32_16x16x32_bf16 v[6:9], v[192:195], v[184:187], v[6:9]
	v_mfma_f32_16x16x32_bf16 v[2:5], v[200:203], v[184:187], v[2:5]
	v_mfma_f32_16x16x32_bf16 v[46:49], v[196:199], v[164:167], v[46:49]
	v_mfma_f32_16x16x32_bf16 v[42:45], v[204:207], v[164:167], v[42:45]
	v_mfma_f32_16x16x32_bf16 v[30:33], v[196:199], v[172:175], v[30:33]
	v_mfma_f32_16x16x32_bf16 v[26:29], v[204:207], v[172:175], v[26:29]
	v_mfma_f32_16x16x32_bf16 v[14:17], v[196:199], v[180:183], v[14:17]
	v_mfma_f32_16x16x32_bf16 v[10:13], v[204:207], v[180:183], v[10:13]
	v_mfma_f32_16x16x32_bf16 v[6:9], v[196:199], v[188:191], v[6:9]
	v_mfma_f32_16x16x32_bf16 v[2:5], v[204:207], v[188:191], v[2:5]
	s_barrier
; #define PG8_STAGE(bufoff, gbase, voff) do { _Pragma("unroll") for (int _i = 0; _i < 2; ++_i) \
;         __builtin_amdgcn_global_load_lds((const unsigned*)((const char*)(gbase) + (voff)[_i]), (LAS unsigned*)(lds + (bufoff) + ldsw + _i * 8192), 16, 0, 0); } while (0)
; #define PG8_LDA(dst, b, h) do { _Pragma("unroll") for (int m = 0; m < 4; ++m) _Pragma("unroll") for (int k = 0; k < 2; ++k) dst[m][k] = *(const LAS bf16x8*)(lds + PG8_SA(b, h) + aoff + m * 2048 + k * 1024); } while (0)
; #define PG8_LDB(dst, b, h) do { _Pragma("unroll") for (int n = 0; n < 2; ++n) _Pragma("unroll") for (int k = 0; k < 2; ++k) dst[n][k] = *(const LAS bf16x8*)(lds + PG8_SB(b, h) + boff + n * 2048 + k * 1024); } while (0)
; #define PG8_WAIT_V(n) asm volatile("s_waitcnt vmcnt(" #n ")" ::: "memory")
; #define PG8_WAIT_L(n) asm volatile("s_waitcnt lgkmcnt(" #n ")" ::: "memory")
; #define PG8_BAR __builtin_amdgcn_s_barrier()
; #define PG8_SCHED __builtin_amdgcn_sched_barrier(0)
; template <class Epi, class Sched>
; __device__ __forceinline__ void gemm_phase(LAS unsigned char* lds, const Gemm g, const Sched& S, const Epi& E) {
;     ...
;             PG8_LDB(B0, 0, 0); PG8_SCHED; PG8_LDA(At, 0, 0); PG8_STAGE(PG8_SA(1, 1), a1 + hstep, voffA);
;             PG8_WAIT_L(8); PG8_BAR; PG8_WAIT_L(0); PG8_MMA(0, 0, At, B0); PG8_BAR; PG8_SCHED;
;             PG8_LDB(B1, 0, 1); PG8_STAGE(PG8_SB(0, 0), b2, voffB);
;             PG8_BAR; PG8_WAIT_L(0); PG8_MMA(0, 1, At, B1); PG8_BAR;
;             PG8_LDA(At, 0, 1); PG8_STAGE(PG8_SA(0, 0), a2, voffA);
;             PG8_BAR; PG8_WAIT_L(0); PG8_MMA(1, 0, At, B0); PG8_BAR; PG8_SCHED;
;             PG8_STAGE(PG8_SB(0, 1), b2 + hstep, voffB);
;             PG8_WAIT_V(6); PG8_BAR; PG8_MMA(1, 1, At, B1); PG8_BAR;
;             PG8_LDB(B0, 1, 0); PG8_SCHED; PG8_LDA(At, 1, 0); PG8_STAGE(PG8_SA(0, 1), a2 + hstep, voffA);
;             PG8_WAIT_L(8); PG8_BAR; PG8_WAIT_L(0); PG8_MMA(0, 0, At, B0); PG8_BAR; PG8_SCHED;
;             PG8_LDB(B1, 1, 1); PG8_STAGE(PG8_SB(1, 0), b3, voffB);
;             PG8_BAR; PG8_WAIT_L(0); PG8_MMA(0, 1, At, B1); PG8_BAR;
;             PG8_LDA(At, 1, 1); PG8_STAGE(PG8_SA(1, 0), a3, voffA);
;             PG8_BAR; PG8_WAIT_L(0); PG8_MMA(1, 0, At, B0); PG8_BAR; PG8_SCHED;
;             PG8_STAGE(PG8_SB(1, 1), b3 + hstep, voffB);
;             PG8_WAIT_V(6); PG8_BAR; PG8_MMA(1, 1, At, B1); PG8_BAR;
	s_add_u32 s38, s58, 0x80000
	s_addc_u32 s39, s59, 0
	s_mov_b32 m0, s66
	s_nop 0
	global_load_lds_dwordx4 v0, s[38:39]
	s_mov_b32 m0, s67
	s_nop 0
	global_load_lds_dwordx4 v130, s[38:39]
	s_add_i32 s52, 0, 0x18000
	ds_read_b128 v[140:143], v226 offset:32768
	ds_read_b128 v[144:147], v226 offset:33792
	ds_read_b128 v[148:151], v226 offset:34816
	ds_read_b128 v[152:155], v226 offset:35840
	ds_read_b128 v[160:163], v139 offset:32768
	ds_read_b128 v[164:167], v139 offset:33792
	ds_read_b128 v[168:171], v139 offset:34816
	ds_read_b128 v[172:175], v139 offset:35840
	ds_read_b128 v[176:179], v139 offset:36864
	ds_read_b128 v[180:183], v139 offset:37888
	ds_read_b128 v[184:187], v139 offset:38912
	ds_read_b128 v[188:191], v139 offset:39936
	s_add_i32 s53, 0, 0x1c000
	ds_read_b128 v[192:195], v226 offset:49152
	ds_read_b128 v[196:199], v226 offset:50176
	ds_read_b128 v[200:203], v226 offset:51200
	ds_read_b128 v[204:207], v226 offset:52224
	s_waitcnt lgkmcnt(4)
	s_barrier
	s_waitcnt lgkmcnt(0)
	v_mfma_f32_16x16x32_bf16 v[126:129], v[140:143], v[160:163], v[126:129]
	v_mfma_f32_16x16x32_bf16 v[122:125], v[148:151], v[160:163], v[122:125]
	v_mfma_f32_16x16x32_bf16 v[118:121], v[140:143], v[168:171], v[118:121]
	v_mfma_f32_16x16x32_bf16 v[114:117], v[148:151], v[168:171], v[114:117]
	v_mfma_f32_16x16x32_bf16 v[106:109], v[140:143], v[176:179], v[106:109]
	v_mfma_f32_16x16x32_bf16 v[98:101], v[148:151], v[176:179], v[98:101]
	v_mfma_f32_16x16x32_bf16 v[90:93], v[140:143], v[184:187], v[90:93]
	v_mfma_f32_16x16x32_bf16 v[82:85], v[148:151], v[184:187], v[82:85]
	v_mfma_f32_16x16x32_bf16 v[126:129], v[144:147], v[164:167], v[126:129]
	v_mfma_f32_16x16x32_bf16 v[122:125], v[152:155], v[164:167], v[122:125]
	v_mfma_f32_16x16x32_bf16 v[118:121], v[144:147], v[172:175], v[118:121]
	v_mfma_f32_16x16x32_bf16 v[114:117], v[152:155], v[172:175], v[114:117]
	v_mfma_f32_16x16x32_bf16 v[106:109], v[144:147], v[180:183], v[106:109]
	v_mfma_f32_16x16x32_bf16 v[98:101], v[152:155], v[180:183], v[98:101]
	v_mfma_f32_16x16x32_bf16 v[90:93], v[144:147], v[188:191], v[90:93]
	v_mfma_f32_16x16x32_bf16 v[82:85], v[152:155], v[188:191], v[82:85]
	v_mfma_f32_16x16x32_bf16 v[110:113], v[192:195], v[160:163], v[110:113]
	v_mfma_f32_16x16x32_bf16 v[102:105], v[200:203], v[160:163], v[102:105]
	v_mfma_f32_16x16x32_bf16 v[94:97], v[192:195], v[168:171], v[94:97]
	v_mfma_f32_16x16x32_bf16 v[86:89], v[200:203], v[168:171], v[86:89]
	v_mfma_f32_16x16x32_bf16 v[78:81], v[192:195], v[176:179], v[78:81]
	v_mfma_f32_16x16x32_bf16 v[74:77], v[200:203], v[176:179], v[74:77]
	v_mfma_f32_16x16x32_bf16 v[70:73], v[192:195], v[184:187], v[70:73]
	v_mfma_f32_16x16x32_bf16 v[66:69], v[200:203], v[184:187], v[66:69]
	v_mfma_f32_16x16x32_bf16 v[110:113], v[196:199], v[164:167], v[110:113]
	v_mfma_f32_16x16x32_bf16 v[102:105], v[204:207], v[164:167], v[102:105]
	v_mfma_f32_16x16x32_bf16 v[94:97], v[196:199], v[172:175], v[94:97]
	v_mfma_f32_16x16x32_bf16 v[86:89], v[204:207], v[172:175], v[86:89]
	v_mfma_f32_16x16x32_bf16 v[78:81], v[196:199], v[180:183], v[78:81]
	v_mfma_f32_16x16x32_bf16 v[74:77], v[204:207], v[180:183], v[74:77]
	v_mfma_f32_16x16x32_bf16 v[70:73], v[196:199], v[188:191], v[70:73]
	v_mfma_f32_16x16x32_bf16 v[66:69], v[204:207], v[188:191], v[66:69]
	s_barrier
	s_add_i32 s38, s52, s65
	s_add_u32 s100, s56, s36
	s_addc_u32 s101, s57, s37
	s_mov_b32 m0, s38
	s_nop 0
	global_load_lds_dwordx4 v0, s[100:101]
	s_add_i32 m0, s38, 0x2000
	s_nop 0
	global_load_lds_dwordx4 v130, s[100:101]
	s_mov_b32 m0, s68
	s_add_u32 s100, s58, s36
	s_addc_u32 s101, s59, s37
	global_load_lds_dwordx4 v0, s[100:101]
	s_mov_b32 m0, s69
	s_nop 0
	global_load_lds_dwordx4 v130, s[100:101]
	ds_read_b128 v[160:163], v139 offset:49152
	ds_read_b128 v[164:167], v139 offset:50176
	ds_read_b128 v[168:171], v139 offset:51200
	ds_read_b128 v[172:175], v139 offset:52224
	ds_read_b128 v[176:179], v139 offset:53248
	ds_read_b128 v[180:183], v139 offset:54272
	ds_read_b128 v[184:187], v139 offset:55296
	ds_read_b128 v[188:191], v139 offset:56320
	s_waitcnt vmcnt(4)
	s_waitcnt lgkmcnt(0)
	s_barrier
; #define PG8_STAGE(bufoff, gbase, voff) do { _Pragma("unroll") for (int _i = 0; _i < 2; ++_i) \
;         __builtin_amdgcn_global_load_lds((const unsigned*)((const char*)(gbase) + (voff)[_i]), (LAS unsigned*)(lds + (bufoff) + ldsw + _i * 8192), 16, 0, 0); } while (0)
; #define PG8_MMA(ai, bj, At, Bt) do { __builtin_amdgcn_s_setprio(1); _Pragma("unroll") for (int m = 0; m < 4; ++m) _Pragma("unroll") for (int n = 0; n < 2; ++n) _Pragma("unroll") for (int k = 0; k < 2; ++k) \
;         acc[ai][bj][m][n] = __builtin_amdgcn_mfma_f32_16x16x32_bf16(Bt[n][k], At[m][k], acc[ai][bj][m][n], 0, 0, 0); __builtin_amdgcn_s_setprio(0); } while (0)
; #define PG8_WAIT_V(n) asm volatile("s_waitcnt vmcnt(" #n ")" ::: "memory")
; #define PG8_WAIT_L(n) asm volatile("s_waitcnt lgkmcnt(" #n ")" ::: "memory")
; #define PG8_BAR __builtin_amdgcn_s_barrier()
; #define PG8_SCHED __builtin_amdgcn_sched_barrier(0)
;     __device__ __forceinline__ void operator()(const f32x4 (&acc)[2][2][4][2], const Unit& u, int wr, int wc, int fr, int fq) const {
;         const int row0 = u.pm * BM + wr * 64 + fr, col0 = u.pn * BM + wc * 32 + 4 * fq;
;         float* base = part + (size_t)u.ks * Mp * ldc;
; #pragma unroll
;         for (int ai = 0; ai < 2; ++ai)
; #pragma unroll
;             for (int m = 0; m < 4; ++m) { float* rowp = base + (size_t)(row0 + ai * HALF + m * 16) * ldc + col0;
; #pragma unroll
;                 for (int bj = 0; bj < 2; ++bj)
; #pragma unroll
;                     for (int n = 0; n < 2; ++n) *(f32x4*)(rowp + bj * HALF + n * 16) = acc[ai][bj][m][n]; }
;     }
; template <class Epi, class Sched>
; __device__ __forceinline__ void gemm_phase(LAS unsigned char* lds, const Gemm g, const Sched& S, const Epi& E) {
;     ...
;             PG8_BAR; PG8_WAIT_L(0); PG8_MMA(1, 0, At, B0); PG8_BAR; PG8_SCHED;
;             PG8_STAGE(PG8_SB(1, 1), b3 + hstep, voffB);
;             PG8_WAIT_V(6); PG8_BAR; PG8_MMA(1, 1, At, B1); PG8_BAR;
	v_mfma_f32_16x16x32_bf16 v[62:65], v[140:143], v[160:163], v[62:65]
	v_mfma_f32_16x16x32_bf16 v[58:61], v[148:151], v[160:163], v[58:61]
	v_mfma_f32_16x16x32_bf16 v[54:57], v[140:143], v[168:171], v[54:57]
	v_mfma_f32_16x16x32_bf16 v[50:53], v[148:151], v[168:171], v[50:53]
	v_mfma_f32_16x16x32_bf16 v[38:41], v[140:143], v[176:179], v[38:41]
	v_mfma_f32_16x16x32_bf16 v[34:37], v[148:151], v[176:179], v[34:37]
	v_mfma_f32_16x16x32_bf16 v[22:25], v[140:143], v[184:187], v[22:25]
	v_mfma_f32_16x16x32_bf16 v[18:21], v[148:151], v[184:187], v[18:21]
	v_mfma_f32_16x16x32_bf16 v[62:65], v[144:147], v[164:167], v[62:65]
	v_mfma_f32_16x16x32_bf16 v[58:61], v[152:155], v[164:167], v[58:61]
	v_mfma_f32_16x16x32_bf16 v[54:57], v[144:147], v[172:175], v[54:57]
	v_mfma_f32_16x16x32_bf16 v[50:53], v[152:155], v[172:175], v[50:53]
	v_mfma_f32_16x16x32_bf16 v[38:41], v[144:147], v[180:183], v[38:41]
	v_mfma_f32_16x16x32_bf16 v[34:37], v[152:155], v[180:183], v[34:37]
	v_mfma_f32_16x16x32_bf16 v[22:25], v[144:147], v[188:191], v[22:25]
	v_mfma_f32_16x16x32_bf16 v[18:21], v[152:155], v[188:191], v[18:21]
	s_add_u32 s38, s56, 0x80080
	s_addc_u32 s39, s57, 0
	s_add_i32 s52, s53, s65
	s_mov_b32 m0, s52
	s_nop 0
	global_load_lds_dwordx4 v0, s[38:39]
	s_add_i32 m0, s52, 0x2000
	s_nop 0
	global_load_lds_dwordx4 v130, s[38:39]
	v_mfma_f32_16x16x32_bf16 v[46:49], v[192:195], v[160:163], v[46:49]
	v_mfma_f32_16x16x32_bf16 v[42:45], v[200:203], v[160:163], v[42:45]
	v_mfma_f32_16x16x32_bf16 v[30:33], v[192:195], v[168:171], v[30:33]
	v_mfma_f32_16x16x32_bf16 v[26:29], v[200:203], v[168:171], v[26:29]
	v_mfma_f32_16x16x32_bf16 v[14:17], v[192:195], v[176:179], v[14:17]
	v_mfma_f32_16x16x32_bf16 v[10:13], v[200:203], v[176:179], v[10:13]
	v_mfma_f32_16x16x32_bf16 v[6:9], v[192:195], v[184:187], v[6:9]
	v_mfma_f32_16x16x32_bf16 v[2:5], v[200:203], v[184:187], v[2:5]
	v_mfma_f32_16x16x32_bf16 v[46:49], v[196:199], v[164:167], v[46:49]
	v_mfma_f32_16x16x32_bf16 v[42:45], v[204:207], v[164:167], v[42:45]
	v_mfma_f32_16x16x32_bf16 v[30:33], v[196:199], v[172:175], v[30:33]
	v_mfma_f32_16x16x32_bf16 v[26:29], v[204:207], v[172:175], v[26:29]
	v_mfma_f32_16x16x32_bf16 v[14:17], v[196:199], v[180:183], v[14:17]
	v_mfma_f32_16x16x32_bf16 v[10:13], v[204:207], v[180:183], v[10:13]
	v_mfma_f32_16x16x32_bf16 v[6:9], v[196:199], v[188:191], v[6:9]
	v_mfma_f32_16x16x32_bf16 v[2:5], v[204:207], v[188:191], v[2:5]
	s_add_i32 s73, s73, 2
	s_add_u32 s71, s71, 0x100
	s_addc_u32 s72, s72, 0
	s_cmp_gt_u32 s73, 5
	s_mov_b64 s[52:53], s[54:55]
	s_barrier
	s_cbranch_scc0 .LBB0_113
	s_ashr_i32 s11, s10, 31
	s_lshl_b64 s[10:11], s[10:11], 24
	v_lshl_or_b32 v140, s26, 8, v138
	s_add_u32 s10, s8, s10
	v_lshl_add_u32 v142, s24, 8, v136
	s_addc_u32 s11, s9, s11
	v_ashrrev_i32_e32 v141, 31, v140
	v_ashrrev_i32_e32 v143, 31, v142
	v_lshl_add_u64 v[140:141], v[140:141], 2, s[10:11]
	v_lshlrev_b64 v[144:145], 13, v[142:143]
	v_lshl_add_u64 v[144:145], v[140:141], 0, v[144:145]
	global_store_dwordx4 v[144:145], v[126:129], off
	global_store_dwordx4 v[144:145], v[122:125], off offset:64
	global_store_dwordx4 v[144:145], v[110:113], off offset:512
	global_store_dwordx4 v[144:145], v[102:105], off offset:576
	s_mov_b64 s[10:11], 0x100000
	s_mov_b32 s26, s40
	v_or_b32_e32 v102, 16, v142
	v_ashrrev_i32_e32 v103, 31, v102
	v_lshlrev_b64 v[102:103], 13, v[102:103]
	v_lshl_add_u64 v[102:103], v[140:141], 0, v[102:103]
	global_store_dwordx4 v[102:103], v[118:121], off
	global_store_dwordx4 v[102:103], v[114:117], off offset:64
	global_store_dwordx4 v[102:103], v[94:97], off offset:512
	global_store_dwordx4 v[102:103], v[86:89], off offset:576
	s_mov_b32 s24, s44
	s_mov_b64 s[54:55], s[50:51]
	v_or_b32_e32 v86, 32, v142
	v_ashrrev_i32_e32 v87, 31, v86
	v_lshlrev_b64 v[86:87], 13, v[86:87]
	v_lshl_add_u64 v[86:87], v[140:141], 0, v[86:87]
	global_store_dwordx4 v[86:87], v[106:109], off
	global_store_dwordx4 v[86:87], v[98:101], off offset:64
	global_store_dwordx4 v[86:87], v[78:81], off offset:512
	global_store_dwordx4 v[86:87], v[74:77], off offset:576
	s_mov_b64 s[52:53], s[48:49]
	s_nop 0
	v_or_b32_e32 v74, 48, v142
	v_ashrrev_i32_e32 v75, 31, v74
	v_lshlrev_b64 v[74:75], 13, v[74:75]
	v_lshl_add_u64 v[74:75], v[140:141], 0, v[74:75]
	global_store_dwordx4 v[74:75], v[90:93], off
	global_store_dwordx4 v[74:75], v[82:85], off offset:64
	global_store_dwordx4 v[74:75], v[70:73], off offset:512
	global_store_dwordx4 v[74:75], v[66:69], off offset:576
	s_nop 1
	v_add_co_u32_e32 v68, vcc, s93, v144
	v_lshl_add_u64 v[66:67], v[144:145], 0, s[10:11]
	s_nop 0
	v_addc_co_u32_e32 v69, vcc, 0, v145, vcc
	s_mov_b64 s[10:11], 0x120000
	global_store_dwordx4 v[68:69], v[62:65], off
	global_store_dwordx4 v[66:67], v[58:61], off offset:64
	global_store_dwordx4 v[66:67], v[46:49], off offset:512
	global_store_dwordx4 v[66:67], v[42:45], off offset:576
	s_nop 1
	v_lshl_add_u64 v[42:43], v[144:145], 0, s[10:11]
	s_mov_b32 s10, 0x120000
	v_add_co_u32_e32 v44, vcc, s10, v144
	s_mov_b64 s[10:11], 0x140000
	s_nop 0
	v_addc_co_u32_e32 v45, vcc, 0, v145, vcc
	global_store_dwordx4 v[44:45], v[54:57], off
	global_store_dwordx4 v[42:43], v[50:53], off offset:64
	global_store_dwordx4 v[42:43], v[30:33], off offset:512
	global_store_dwordx4 v[42:43], v[26:29], off offset:576
	s_nop 1
	v_lshl_add_u64 v[26:27], v[144:145], 0, s[10:11]
	s_mov_b32 s10, 0x140000
	v_add_co_u32_e32 v28, vcc, s10, v144
	s_mov_b64 s[10:11], 0x160000
	s_nop 0
	v_addc_co_u32_e32 v29, vcc, 0, v145, vcc
	global_store_dwordx4 v[28:29], v[38:41], off
	global_store_dwordx4 v[26:27], v[34:37], off offset:64
	global_store_dwordx4 v[26:27], v[14:17], off offset:512
	global_store_dwordx4 v[26:27], v[10:13], off offset:576
	s_nop 1
	v_add_co_u32_e32 v12, vcc, 0x160000, v144
	v_lshl_add_u64 v[10:11], v[144:145], 0, s[10:11]
	s_nop 0
	v_addc_co_u32_e32 v13, vcc, 0, v145, vcc
	s_and_b64 vcc, exec, s[46:47]
	s_mov_b32 s10, s28
	global_store_dwordx4 v[12:13], v[22:25], off
	global_store_dwordx4 v[10:11], v[18:21], off offset:64
	global_store_dwordx4 v[10:11], v[6:9], off offset:512
	global_store_dwordx4 v[10:11], v[2:5], off offset:576
	s_cbranch_vccz .LBB0_110
	s_waitcnt vmcnt(0)
	s_cmpk_gt_u32 s60, 0xff
	s_cbranch_scc1 .LBB0_117
	s_barrier

; #define PG8_STAGE(bufoff, gbase, voff) do { _Pragma("unroll") for (int _i = 0; _i < 2; ++_i) \
;         __builtin_amdgcn_global_load_lds((const unsigned*)((const char*)(gbase) + (voff)[_i]), (LAS unsigned*)(lds + (bufoff) + ldsw + _i * 8192), 16, 0, 0); } while (0)
; #define PG8_LDA(dst, b, h) do { _Pragma("unroll") for (int m = 0; m < 4; ++m) _Pragma("unroll") for (int k = 0; k < 2; ++k) dst[m][k] = *(const LAS bf16x8*)(lds + PG8_SA(b, h) + aoff + m * 2048 + k * 1024); } while (0)
; #define PG8_WAIT_V(n) asm volatile("s_waitcnt vmcnt(" #n ")" ::: "memory")
; #define PG8_WAIT_L(n) asm volatile("s_waitcnt lgkmcnt(" #n ")" ::: "memory")
; #define PG8_BAR __builtin_amdgcn_s_barrier()
; template <class Epi, class Sched>
; __device__ __forceinline__ void gemm_phase(LAS unsigned char* lds, const Gemm g, const Sched& S, const Epi& E) {
;     ...
;             const bool last = (t == nt - 2);
;             const char* a1 = cA + (size_t)(t + 1) * kstep;
;             const char* a2 = last ? nA : cA + (size_t)(t + 2) * kstep; const char* b2 = last ? nB : cB + (size_t)(t + 2) * kstep;
;             const char* a3 = a2 + kstep; const char* b3 = b2 + kstep;
;             PG8_LDB(B0, 0, 0); PG8_SCHED; PG8_LDA(At, 0, 0); PG8_STAGE(PG8_SA(1, 1), a1 + hstep, voffA);
;             PG8_WAIT_L(8); PG8_BAR; PG8_WAIT_L(0); PG8_MMA(0, 0, At, B0); PG8_BAR; PG8_SCHED;
;             PG8_LDB(B1, 0, 1); PG8_STAGE(PG8_SB(0, 0), b2, voffB);
;             PG8_BAR; PG8_WAIT_L(0); PG8_MMA(0, 1, At, B1); PG8_BAR;
;             PG8_LDA(At, 0, 1); PG8_STAGE(PG8_SA(0, 0), a2, voffA);
;             PG8_BAR; PG8_WAIT_L(0); PG8_MMA(1, 0, At, B0); PG8_BAR; PG8_SCHED;
;             PG8_STAGE(PG8_SB(0, 1), b2 + hstep, voffB);
;             PG8_WAIT_V(6); PG8_BAR; PG8_MMA(1, 1, At, B1); PG8_BAR;
;             PG8_LDB(B0, 1, 0); PG8_SCHED; PG8_LDA(At, 1, 0); PG8_STAGE(PG8_SA(0, 1), a2 + hstep, voffA);
;             PG8_WAIT_L(8); PG8_BAR; PG8_WAIT_L(0); PG8_MMA(0, 0, At, B0); PG8_BAR; PG8_SCHED;
;             PG8_LDB(B1, 1, 1); PG8_STAGE(PG8_SB(1, 0), b3, voffB);
;             PG8_BAR; PG8_WAIT_L(0); PG8_MMA(0, 1, At, B1); PG8_BAR;
;             PG8_LDA(At, 1, 1); PG8_STAGE(PG8_SA(1, 0), a3, voffA);
;             PG8_BAR; PG8_WAIT_L(0); PG8_MMA(1, 0, At, B0); PG8_BAR; PG8_SCHED;
;             PG8_STAGE(PG8_SB(1, 1), b3 + hstep, voffB);
;             PG8_WAIT_V(6); PG8_BAR; PG8_MMA(1, 1, At, B1); PG8_BAR;
.LBB0_354:
	s_add_u32 s38, s50, 0xfff80080
	s_addc_u32 s39, s51, -1
	s_cmp_eq_u32 s70, 28
	s_cselect_b32 s55, s9, s39
	s_cselect_b32 s54, s66, s38
	s_cselect_b32 s53, s43, s69
	s_cselect_b32 s52, s67, s68
	s_add_i32 m0, s29, 0xc000
	s_nop 0
	global_load_lds_dwordx4 v138, s[50:51]
	s_add_i32 m0, s29, 0xe000
	s_nop 0
	global_load_lds_dwordx4 v136, s[50:51]
	s_add_i32 s71, 0, 0x10000
	ds_read_b128 v[140:143], v226
	ds_read_b128 v[148:151], v226 offset:1024
	ds_read_b128 v[152:155], v226 offset:2048
	ds_read_b128 v[160:163], v226 offset:3072
	ds_read_b128 v[164:167], v147
	ds_read_b128 v[168:171], v147 offset:1024
	ds_read_b128 v[172:175], v147 offset:2048
	ds_read_b128 v[176:179], v147 offset:3072
	ds_read_b128 v[180:183], v147 offset:4096
	ds_read_b128 v[184:187], v147 offset:5120
	ds_read_b128 v[188:191], v147 offset:6144
	ds_read_b128 v[192:195], v147 offset:7168
	s_add_i32 s38, 0, 0x14000
	ds_read_b128 v[196:199], v226 offset:16384
	ds_read_b128 v[200:203], v226 offset:17408
	ds_read_b128 v[204:207], v226 offset:18432
	ds_read_b128 v[210:213], v226 offset:19456
	s_waitcnt lgkmcnt(4)
	s_barrier
	s_waitcnt lgkmcnt(0)
	v_mfma_f32_16x16x32_bf16 v[126:129], v[140:143], v[164:167], v[126:129]
	v_mfma_f32_16x16x32_bf16 v[122:125], v[152:155], v[164:167], v[122:125]
	v_mfma_f32_16x16x32_bf16 v[118:121], v[140:143], v[172:175], v[118:121]
	v_mfma_f32_16x16x32_bf16 v[110:113], v[152:155], v[172:175], v[110:113]
	v_mfma_f32_16x16x32_bf16 v[102:105], v[140:143], v[180:183], v[102:105]
	v_mfma_f32_16x16x32_bf16 v[94:97], v[152:155], v[180:183], v[94:97]
	v_mfma_f32_16x16x32_bf16 v[86:89], v[140:143], v[188:191], v[86:89]
	v_mfma_f32_16x16x32_bf16 v[78:81], v[152:155], v[188:191], v[78:81]
	v_mfma_f32_16x16x32_bf16 v[126:129], v[148:151], v[168:171], v[126:129]
	v_mfma_f32_16x16x32_bf16 v[122:125], v[160:163], v[168:171], v[122:125]
	v_mfma_f32_16x16x32_bf16 v[118:121], v[148:151], v[176:179], v[118:121]
	v_mfma_f32_16x16x32_bf16 v[110:113], v[160:163], v[176:179], v[110:113]
	v_mfma_f32_16x16x32_bf16 v[102:105], v[148:151], v[184:187], v[102:105]
	v_mfma_f32_16x16x32_bf16 v[94:97], v[160:163], v[184:187], v[94:97]
	v_mfma_f32_16x16x32_bf16 v[86:89], v[148:151], v[192:195], v[86:89]
	v_mfma_f32_16x16x32_bf16 v[78:81], v[160:163], v[192:195], v[78:81]
	v_mfma_f32_16x16x32_bf16 v[114:117], v[196:199], v[164:167], v[114:117]
	v_mfma_f32_16x16x32_bf16 v[106:109], v[204:207], v[164:167], v[106:109]
	v_mfma_f32_16x16x32_bf16 v[98:101], v[196:199], v[172:175], v[98:101]
	v_mfma_f32_16x16x32_bf16 v[90:93], v[204:207], v[172:175], v[90:93]
	v_mfma_f32_16x16x32_bf16 v[82:85], v[196:199], v[180:183], v[82:85]
	v_mfma_f32_16x16x32_bf16 v[74:77], v[204:207], v[180:183], v[74:77]
	v_mfma_f32_16x16x32_bf16 v[70:73], v[196:199], v[188:191], v[70:73]
	v_mfma_f32_16x16x32_bf16 v[66:69], v[204:207], v[188:191], v[66:69]
	v_mfma_f32_16x16x32_bf16 v[114:117], v[200:203], v[168:171], v[114:117]
	v_mfma_f32_16x16x32_bf16 v[106:109], v[210:213], v[168:171], v[106:109]
	v_mfma_f32_16x16x32_bf16 v[98:101], v[200:203], v[176:179], v[98:101]
	v_mfma_f32_16x16x32_bf16 v[90:93], v[210:213], v[176:179], v[90:93]
	v_mfma_f32_16x16x32_bf16 v[82:85], v[200:203], v[184:187], v[82:85]
	v_mfma_f32_16x16x32_bf16 v[74:77], v[210:213], v[184:187], v[74:77]
	v_mfma_f32_16x16x32_bf16 v[70:73], v[200:203], v[192:195], v[70:73]
	v_mfma_f32_16x16x32_bf16 v[66:69], v[210:213], v[192:195], v[66:69]
	s_barrier
	s_add_i32 s39, s71, s56
	s_mov_b32 m0, s39
	s_nop 0
	global_load_lds_dwordx4 v0, s[52:53]
	s_add_i32 m0, s39, 0x2000
	s_nop 0
	global_load_lds_dwordx4 v134, s[52:53]
	s_mov_b32 m0, s29
	s_nop 0
	global_load_lds_dwordx4 v130, s[54:55]
	s_mov_b32 m0, s41
	s_nop 0
	global_load_lds_dwordx4 v132, s[54:55]
	ds_read_b128 v[164:167], v147 offset:16384
	ds_read_b128 v[168:171], v147 offset:17408
	ds_read_b128 v[172:175], v147 offset:18432
	ds_read_b128 v[176:179], v147 offset:19456
	ds_read_b128 v[180:183], v147 offset:20480
	ds_read_b128 v[184:187], v147 offset:21504
	ds_read_b128 v[188:191], v147 offset:22528
	ds_read_b128 v[192:195], v147 offset:23552
	s_waitcnt vmcnt(4)
	s_waitcnt lgkmcnt(0)
	s_barrier
	v_mfma_f32_16x16x32_bf16 v[62:65], v[140:143], v[164:167], v[62:65]
	v_mfma_f32_16x16x32_bf16 v[58:61], v[152:155], v[164:167], v[58:61]
	v_mfma_f32_16x16x32_bf16 v[54:57], v[140:143], v[172:175], v[54:57]
	v_mfma_f32_16x16x32_bf16 v[46:49], v[152:155], v[172:175], v[46:49]
	v_mfma_f32_16x16x32_bf16 v[38:41], v[140:143], v[180:183], v[38:41]
	v_mfma_f32_16x16x32_bf16 v[30:33], v[152:155], v[180:183], v[30:33]
	v_mfma_f32_16x16x32_bf16 v[22:25], v[140:143], v[188:191], v[22:25]
	v_mfma_f32_16x16x32_bf16 v[14:17], v[152:155], v[188:191], v[14:17]
	v_mfma_f32_16x16x32_bf16 v[62:65], v[148:151], v[168:171], v[62:65]
	v_mfma_f32_16x16x32_bf16 v[58:61], v[160:163], v[168:171], v[58:61]
	v_mfma_f32_16x16x32_bf16 v[54:57], v[148:151], v[176:179], v[54:57]
	v_mfma_f32_16x16x32_bf16 v[46:49], v[160:163], v[176:179], v[46:49]
	v_mfma_f32_16x16x32_bf16 v[38:41], v[148:151], v[184:187], v[38:41]
	v_mfma_f32_16x16x32_bf16 v[30:33], v[160:163], v[184:187], v[30:33]
	v_mfma_f32_16x16x32_bf16 v[22:25], v[148:151], v[192:195], v[22:25]
	v_mfma_f32_16x16x32_bf16 v[14:17], v[160:163], v[192:195], v[14:17]
	s_add_u32 s72, s52, 0x80000
	s_addc_u32 s73, s53, 0
	s_add_i32 s38, s38, s56
	s_mov_b32 m0, s38
	s_nop 0
	global_load_lds_dwordx4 v0, s[72:73]
	s_add_i32 m0, s38, 0x2000
	s_nop 0
	global_load_lds_dwordx4 v134, s[72:73]
	v_mfma_f32_16x16x32_bf16 v[50:53], v[196:199], v[164:167], v[50:53]
	v_mfma_f32_16x16x32_bf16 v[42:45], v[204:207], v[164:167], v[42:45]
	v_mfma_f32_16x16x32_bf16 v[34:37], v[196:199], v[172:175], v[34:37]
	v_mfma_f32_16x16x32_bf16 v[26:29], v[204:207], v[172:175], v[26:29]
	v_mfma_f32_16x16x32_bf16 v[18:21], v[196:199], v[180:183], v[18:21]
	v_mfma_f32_16x16x32_bf16 v[10:13], v[204:207], v[180:183], v[10:13]
	v_mfma_f32_16x16x32_bf16 v[6:9], v[196:199], v[188:191], v[6:9]
	v_mfma_f32_16x16x32_bf16 v[2:5], v[204:207], v[188:191], v[2:5]
	v_mfma_f32_16x16x32_bf16 v[50:53], v[200:203], v[168:171], v[50:53]
	v_mfma_f32_16x16x32_bf16 v[42:45], v[210:213], v[168:171], v[42:45]
	v_mfma_f32_16x16x32_bf16 v[34:37], v[200:203], v[176:179], v[34:37]
	v_mfma_f32_16x16x32_bf16 v[26:29], v[210:213], v[176:179], v[26:29]
	v_mfma_f32_16x16x32_bf16 v[18:21], v[200:203], v[184:187], v[18:21]
	v_mfma_f32_16x16x32_bf16 v[10:13], v[210:213], v[184:187], v[10:13]
	v_mfma_f32_16x16x32_bf16 v[6:9], v[200:203], v[192:195], v[6:9]
	v_mfma_f32_16x16x32_bf16 v[2:5], v[210:213], v[192:195], v[2:5]
	s_barrier
; #define PG8_STAGE(bufoff, gbase, voff) do { _Pragma("unroll") for (int _i = 0; _i < 2; ++_i) \
;         __builtin_amdgcn_global_load_lds((const unsigned*)((const char*)(gbase) + (voff)[_i]), (LAS unsigned*)(lds + (bufoff) + ldsw + _i * 8192), 16, 0, 0); } while (0)
; #define PG8_LDA(dst, b, h) do { _Pragma("unroll") for (int m = 0; m < 4; ++m) _Pragma("unroll") for (int k = 0; k < 2; ++k) dst[m][k] = *(const LAS bf16x8*)(lds + PG8_SA(b, h) + aoff + m * 2048 + k * 1024); } while (0)
; #define PG8_LDB(dst, b, h) do { _Pragma("unroll") for (int n = 0; n < 2; ++n) _Pragma("unroll") for (int k = 0; k < 2; ++k) dst[n][k] = *(const LAS bf16x8*)(lds + PG8_SB(b, h) + boff + n * 2048 + k * 1024); } while (0)
; #define PG8_WAIT_V(n) asm volatile("s_waitcnt vmcnt(" #n ")" ::: "memory")
; #define PG8_WAIT_L(n) asm volatile("s_waitcnt lgkmcnt(" #n ")" ::: "memory")
; #define PG8_BAR __builtin_amdgcn_s_barrier()
; #define PG8_SCHED __builtin_amdgcn_sched_barrier(0)
; template <class Epi, class Sched>
; __device__ __forceinline__ void gemm_phase(LAS unsigned char* lds, const Gemm g, const Sched& S, const Epi& E) {
;     ...
;             PG8_LDB(B0, 0, 0); PG8_SCHED; PG8_LDA(At, 0, 0); PG8_STAGE(PG8_SA(1, 1), a1 + hstep, voffA);
;             PG8_WAIT_L(8); PG8_BAR; PG8_WAIT_L(0); PG8_MMA(0, 0, At, B0); PG8_BAR; PG8_SCHED;
;             PG8_LDB(B1, 0, 1); PG8_STAGE(PG8_SB(0, 0), b2, voffB);
;             PG8_BAR; PG8_WAIT_L(0); PG8_MMA(0, 1, At, B1); PG8_BAR;
;             PG8_LDA(At, 0, 1); PG8_STAGE(PG8_SA(0, 0), a2, voffA);
;             PG8_BAR; PG8_WAIT_L(0); PG8_MMA(1, 0, At, B0); PG8_BAR; PG8_SCHED;
;             PG8_STAGE(PG8_SB(0, 1), b2 + hstep, voffB);
;             PG8_WAIT_V(6); PG8_BAR; PG8_MMA(1, 1, At, B1); PG8_BAR;
;             PG8_LDB(B0, 1, 0); PG8_SCHED; PG8_LDA(At, 1, 0); PG8_STAGE(PG8_SA(0, 1), a2 + hstep, voffA);
;             PG8_WAIT_L(8); PG8_BAR; PG8_WAIT_L(0); PG8_MMA(0, 0, At, B0); PG8_BAR; PG8_SCHED;
;             PG8_LDB(B1, 1, 1); PG8_STAGE(PG8_SB(1, 0), b3, voffB);
;             PG8_BAR; PG8_WAIT_L(0); PG8_MMA(0, 1, At, B1); PG8_BAR;
;             PG8_LDA(At, 1, 1); PG8_STAGE(PG8_SA(1, 0), a3, voffA);
;             PG8_BAR; PG8_WAIT_L(0); PG8_MMA(1, 0, At, B0); PG8_BAR; PG8_SCHED;
;             PG8_STAGE(PG8_SB(1, 1), b3 + hstep, voffB);
;             PG8_WAIT_V(6); PG8_BAR; PG8_MMA(1, 1, At, B1); PG8_BAR;
	s_add_u32 s54, s54, 0x80000
	s_addc_u32 s55, s55, 0
	s_mov_b32 m0, s57
	s_nop 0
	global_load_lds_dwordx4 v130, s[54:55]
	s_mov_b32 m0, s58
	s_nop 0
	global_load_lds_dwordx4 v132, s[54:55]
	s_add_i32 s38, 0, 0x18000
	ds_read_b128 v[140:143], v226 offset:32768
	ds_read_b128 v[148:151], v226 offset:33792
	ds_read_b128 v[152:155], v226 offset:34816
	ds_read_b128 v[160:163], v226 offset:35840
	ds_read_b128 v[164:167], v147 offset:32768
	ds_read_b128 v[168:171], v147 offset:33792
	ds_read_b128 v[172:175], v147 offset:34816
	ds_read_b128 v[176:179], v147 offset:35840
	ds_read_b128 v[180:183], v147 offset:36864
	ds_read_b128 v[184:187], v147 offset:37888
	ds_read_b128 v[188:191], v147 offset:38912
	ds_read_b128 v[192:195], v147 offset:39936
	s_add_i32 s39, 0, 0x1c000
	ds_read_b128 v[196:199], v226 offset:49152
	ds_read_b128 v[200:203], v226 offset:50176
	ds_read_b128 v[204:207], v226 offset:51200
	ds_read_b128 v[210:213], v226 offset:52224
	s_waitcnt lgkmcnt(4)
	s_barrier
	s_waitcnt lgkmcnt(0)
	v_mfma_f32_16x16x32_bf16 v[126:129], v[140:143], v[164:167], v[126:129]
	v_mfma_f32_16x16x32_bf16 v[122:125], v[152:155], v[164:167], v[122:125]
	v_mfma_f32_16x16x32_bf16 v[118:121], v[140:143], v[172:175], v[118:121]
	v_mfma_f32_16x16x32_bf16 v[110:113], v[152:155], v[172:175], v[110:113]
	v_mfma_f32_16x16x32_bf16 v[102:105], v[140:143], v[180:183], v[102:105]
	v_mfma_f32_16x16x32_bf16 v[94:97], v[152:155], v[180:183], v[94:97]
	v_mfma_f32_16x16x32_bf16 v[86:89], v[140:143], v[188:191], v[86:89]
	v_mfma_f32_16x16x32_bf16 v[78:81], v[152:155], v[188:191], v[78:81]
	v_mfma_f32_16x16x32_bf16 v[126:129], v[148:151], v[168:171], v[126:129]
	v_mfma_f32_16x16x32_bf16 v[122:125], v[160:163], v[168:171], v[122:125]
	v_mfma_f32_16x16x32_bf16 v[118:121], v[148:151], v[176:179], v[118:121]
	v_mfma_f32_16x16x32_bf16 v[110:113], v[160:163], v[176:179], v[110:113]
	v_mfma_f32_16x16x32_bf16 v[102:105], v[148:151], v[184:187], v[102:105]
	v_mfma_f32_16x16x32_bf16 v[94:97], v[160:163], v[184:187], v[94:97]
	v_mfma_f32_16x16x32_bf16 v[86:89], v[148:151], v[192:195], v[86:89]
	v_mfma_f32_16x16x32_bf16 v[78:81], v[160:163], v[192:195], v[78:81]
	v_mfma_f32_16x16x32_bf16 v[114:117], v[196:199], v[164:167], v[114:117]
	v_mfma_f32_16x16x32_bf16 v[106:109], v[204:207], v[164:167], v[106:109]
	v_mfma_f32_16x16x32_bf16 v[98:101], v[196:199], v[172:175], v[98:101]
	v_mfma_f32_16x16x32_bf16 v[90:93], v[204:207], v[172:175], v[90:93]
	v_mfma_f32_16x16x32_bf16 v[82:85], v[196:199], v[180:183], v[82:85]
	v_mfma_f32_16x16x32_bf16 v[74:77], v[204:207], v[180:183], v[74:77]
	v_mfma_f32_16x16x32_bf16 v[70:73], v[196:199], v[188:191], v[70:73]
	v_mfma_f32_16x16x32_bf16 v[66:69], v[204:207], v[188:191], v[66:69]
	v_mfma_f32_16x16x32_bf16 v[114:117], v[200:203], v[168:171], v[114:117]
	v_mfma_f32_16x16x32_bf16 v[106:109], v[210:213], v[168:171], v[106:109]
	v_mfma_f32_16x16x32_bf16 v[98:101], v[200:203], v[176:179], v[98:101]
	v_mfma_f32_16x16x32_bf16 v[90:93], v[210:213], v[176:179], v[90:93]
	v_mfma_f32_16x16x32_bf16 v[82:85], v[200:203], v[184:187], v[82:85]
	v_mfma_f32_16x16x32_bf16 v[74:77], v[210:213], v[184:187], v[74:77]
	v_mfma_f32_16x16x32_bf16 v[70:73], v[200:203], v[192:195], v[70:73]
	v_mfma_f32_16x16x32_bf16 v[66:69], v[210:213], v[192:195], v[66:69]
	s_barrier
	s_add_i32 s38, s38, s56
	s_add_u32 s100, s52, s36
	s_addc_u32 s101, s53, s37
	s_mov_b32 m0, s38
	s_nop 0
	global_load_lds_dwordx4 v0, s[100:101]
	s_add_i32 m0, s38, 0x2000
	s_nop 0
	global_load_lds_dwordx4 v134, s[100:101]
	s_mov_b32 m0, s59
	s_add_u32 s100, s54, s36
	s_addc_u32 s101, s55, s37
	s_sub_u32 s100, s100, 0x80000
	s_subb_u32 s101, s101, 0
	global_load_lds_dwordx4 v130, s[100:101]
	s_mov_b32 m0, s60
	s_nop 0
	global_load_lds_dwordx4 v132, s[100:101]
	ds_read_b128 v[164:167], v147 offset:49152
	ds_read_b128 v[168:171], v147 offset:50176
	ds_read_b128 v[172:175], v147 offset:51200
	ds_read_b128 v[176:179], v147 offset:52224
	ds_read_b128 v[180:183], v147 offset:53248
	ds_read_b128 v[184:187], v147 offset:54272
	ds_read_b128 v[188:191], v147 offset:55296
	ds_read_b128 v[192:195], v147 offset:56320
	s_waitcnt vmcnt(4)
	s_waitcnt lgkmcnt(0)
	s_barrier
	v_mfma_f32_16x16x32_bf16 v[62:65], v[140:143], v[164:167], v[62:65]
	v_mfma_f32_16x16x32_bf16 v[58:61], v[152:155], v[164:167], v[58:61]
	v_mfma_f32_16x16x32_bf16 v[54:57], v[140:143], v[172:175], v[54:57]
	v_mfma_f32_16x16x32_bf16 v[46:49], v[152:155], v[172:175], v[46:49]
	v_mfma_f32_16x16x32_bf16 v[38:41], v[140:143], v[180:183], v[38:41]
	v_mfma_f32_16x16x32_bf16 v[30:33], v[152:155], v[180:183], v[30:33]
	v_mfma_f32_16x16x32_bf16 v[22:25], v[140:143], v[188:191], v[22:25]
	v_mfma_f32_16x16x32_bf16 v[14:17], v[152:155], v[188:191], v[14:17]
	v_mfma_f32_16x16x32_bf16 v[62:65], v[148:151], v[168:171], v[62:65]
	v_mfma_f32_16x16x32_bf16 v[58:61], v[160:163], v[168:171], v[58:61]
	v_mfma_f32_16x16x32_bf16 v[54:57], v[148:151], v[176:179], v[54:57]
	v_mfma_f32_16x16x32_bf16 v[46:49], v[160:163], v[176:179], v[46:49]
	v_mfma_f32_16x16x32_bf16 v[38:41], v[148:151], v[184:187], v[38:41]
	v_mfma_f32_16x16x32_bf16 v[30:33], v[160:163], v[184:187], v[30:33]
	v_mfma_f32_16x16x32_bf16 v[22:25], v[148:151], v[192:195], v[22:25]
	v_mfma_f32_16x16x32_bf16 v[14:17], v[160:163], v[192:195], v[14:17]
	s_add_u32 s52, s52, 0x80080
	s_addc_u32 s53, s53, 0
	s_add_i32 s38, s39, s56
	s_mov_b32 m0, s38
	s_nop 0
	global_load_lds_dwordx4 v0, s[52:53]
	s_add_i32 m0, s38, 0x2000
	s_nop 0
	global_load_lds_dwordx4 v134, s[52:53]
	v_mfma_f32_16x16x32_bf16 v[50:53], v[196:199], v[164:167], v[50:53]
	v_mfma_f32_16x16x32_bf16 v[42:45], v[204:207], v[164:167], v[42:45]
	v_mfma_f32_16x16x32_bf16 v[34:37], v[196:199], v[172:175], v[34:37]
	v_mfma_f32_16x16x32_bf16 v[26:29], v[204:207], v[172:175], v[26:29]
	v_mfma_f32_16x16x32_bf16 v[18:21], v[196:199], v[180:183], v[18:21]
	v_mfma_f32_16x16x32_bf16 v[10:13], v[204:207], v[180:183], v[10:13]
	v_mfma_f32_16x16x32_bf16 v[6:9], v[196:199], v[188:191], v[6:9]
	v_mfma_f32_16x16x32_bf16 v[2:5], v[204:207], v[188:191], v[2:5]
	v_mfma_f32_16x16x32_bf16 v[50:53], v[200:203], v[168:171], v[50:53]
	v_mfma_f32_16x16x32_bf16 v[42:45], v[210:213], v[168:171], v[42:45]
	v_mfma_f32_16x16x32_bf16 v[34:37], v[200:203], v[176:179], v[34:37]
	v_mfma_f32_16x16x32_bf16 v[26:29], v[210:213], v[176:179], v[26:29]
	v_mfma_f32_16x16x32_bf16 v[18:21], v[200:203], v[184:187], v[18:21]
	v_mfma_f32_16x16x32_bf16 v[10:13], v[210:213], v[184:187], v[10:13]
	v_mfma_f32_16x16x32_bf16 v[6:9], v[200:203], v[192:195], v[6:9]
	v_mfma_f32_16x16x32_bf16 v[2:5], v[210:213], v[192:195], v[2:5]
	s_add_i32 s70, s70, 2
	s_add_u32 s68, s68, 0x100
	s_addc_u32 s69, s69, 0
	s_add_u32 s50, s50, 0x100
	s_addc_u32 s51, s51, 0
	s_cmp_gt_u32 s70, 29
	s_barrier
; __device__ __forceinline__ unsigned cvt_pk_bf16(float lo, float hi) { unsigned r; asm("v_cvt_pk_bf16_f32 %0, %1, %2" : "=v"(r) : "v"(lo), "v"(hi)); return r; }
;     __device__ __forceinline__ void operator()(const f32x4 (&acc)[2][2][4][2], const Unit& u, int wr, int wc, int fr, int fq) const {
;         const int row0 = u.pm * BM + wr * 64 + fr, col0 = u.pn * BM + wc * 32 + 8 * fq;
; #pragma unroll
;         for (int ai = 0; ai < 2; ++ai)
; #pragma unroll
;             for (int m = 0; m < 4; ++m) { bf16_t* rowp = O + (size_t)(row0 + ai * HALF + m * 16) * ldc + col0;
; #pragma unroll
;                 for (int bj = 0; bj < 2; ++bj) { f32x4 v0 = acc[ai][bj][m][0], v1 = acc[ai][bj][m][1];
;                     if (ACT == 1) {
; #pragma unroll
;                         for (int j = 0; j < 4; ++j) { float a = fmaxf(v0[j], 0.f), b = fmaxf(v1[j], 0.f); v0[j] = a * a; v1[j] = b * b; } }
;                     u32x4 w; w.x = cvt_pk_bf16(v0[0], v0[1]); w.y = cvt_pk_bf16(v0[2], v0[3]); w.z = cvt_pk_bf16(v1[0], v1[1]); w.w = cvt_pk_bf16(v1[2], v1[3]);
;                     if (ACT == 1) __builtin_nontemporal_store(w, (u32x4*)(rowp + bj * HALF));
;                     else *(u32x4*)(rowp + bj * HALF) = w; } }
;     }
	s_cbranch_scc0 .LBB0_354
	s_load_dwordx2 s[50:51], s[0:1], 0xc0
	v_lshl_add_u32 v150, s28, 8, v144
	v_lshl_or_b32 v142, s40, 8, v146
	v_ashrrev_i32_e32 v143, 31, v142
	v_cvt_pk_bf16_f32 v70, v70, v71
	s_waitcnt lgkmcnt(0)
	v_mov_b64_e32 v[140:141], s[50:51]
	v_cvt_pk_bf16_f32 v71, v72, v73
	v_cvt_pk_bf16_f32 v72, v66, v67
	v_add_u32_e32 v66, 0x80, v150
	v_mad_i64_i32 v[148:149], s[50:51], v150, s17, v[140:141]
	v_lshlrev_b64 v[142:143], 1, v[142:143]
	v_cvt_pk_bf16_f32 v114, v114, v115
	v_cvt_pk_bf16_f32 v115, v116, v117
	v_cvt_pk_bf16_f32 v116, v106, v107
	v_or_b32_e32 v106, 16, v150
	v_mad_i64_i32 v[66:67], s[50:51], v66, s17, v[140:141]
	v_cvt_pk_bf16_f32 v50, v50, v51
	v_cvt_pk_bf16_f32 v51, v52, v53
	v_cvt_pk_bf16_f32 v52, v42, v43
	v_add_u32_e32 v42, 0x90, v150
	v_lshl_add_u64 v[148:149], v[148:149], 0, v[142:143]
	v_mad_i64_i32 v[106:107], s[50:51], v106, s17, v[140:141]
	v_cvt_pk_bf16_f32 v98, v98, v99
	v_cvt_pk_bf16_f32 v99, v100, v101
	v_cvt_pk_bf16_f32 v100, v90, v91
	v_or_b32_e32 v90, 32, v150
	v_lshl_add_u64 v[66:67], v[66:67], 0, v[142:143]
	v_mad_i64_i32 v[42:43], s[50:51], v42, s17, v[140:141]
	v_cvt_pk_bf16_f32 v34, v34, v35
	v_cvt_pk_bf16_f32 v35, v36, v37
	v_cvt_pk_bf16_f32 v36, v26, v27
	v_add_u32_e32 v26, 0xa0, v150
	v_cvt_pk_bf16_f32 v117, v108, v109
	global_store_dwordx4 v[148:149], v[114:117], off offset:256
	v_mad_i64_i32 v[90:91], s[50:51], v90, s17, v[140:141]
	s_nop 0
	v_lshl_add_u64 v[114:115], v[106:107], 0, v[142:143]
	v_cvt_pk_bf16_f32 v82, v82, v83
	v_cvt_pk_bf16_f32 v83, v84, v85
	v_cvt_pk_bf16_f32 v84, v74, v75
	v_or_b32_e32 v74, 48, v150
	v_cvt_pk_bf16_f32 v53, v44, v45
	global_store_dwordx4 v[66:67], v[50:53], off offset:256
	v_mad_i64_i32 v[26:27], s[50:51], v26, s17, v[140:141]
	s_nop 0
	v_lshl_add_u64 v[50:51], v[42:43], 0, v[142:143]
	v_cvt_pk_bf16_f32 v18, v18, v19
	v_cvt_pk_bf16_f32 v19, v20, v21
	v_cvt_pk_bf16_f32 v20, v10, v11
	v_add_u32_e32 v10, 0xb0, v150
	v_cvt_pk_bf16_f32 v101, v92, v93
	global_store_dwordx4 v[114:115], v[98:101], off offset:256
	v_mad_i64_i32 v[74:75], s[50:51], v74, s17, v[140:141]
	s_nop 0
	v_lshl_add_u64 v[98:99], v[90:91], 0, v[142:143]
	v_cvt_pk_bf16_f32 v37, v28, v29
	global_store_dwordx4 v[50:51], v[34:37], off offset:256
	v_mad_i64_i32 v[10:11], s[50:51], v10, s17, v[140:141]
	s_nop 0
	v_lshl_add_u64 v[34:35], v[26:27], 0, v[142:143]
	v_cvt_pk_bf16_f32 v85, v76, v77
	global_store_dwordx4 v[98:99], v[82:85], off offset:256
	v_cvt_pk_bf16_f32 v21, v12, v13
	global_store_dwordx4 v[34:35], v[18:21], off offset:256
	s_and_b64 vcc, exec, s[46:47]
	v_lshl_add_u64 v[82:83], v[74:75], 0, v[142:143]
	v_lshl_add_u64 v[18:19], v[10:11], 0, v[142:143]
	s_mov_b32 s40, s42
	s_mov_b32 s28, s8
	s_mov_b32 s43, s42
	s_mov_b32 s46, s8
	s_mov_b64 s[50:51], s[48:49]
	s_mov_b64 s[52:53], s[44:45]
	v_cvt_pk_bf16_f32 v126, v126, v127
	v_cvt_pk_bf16_f32 v127, v128, v129
	v_cvt_pk_bf16_f32 v128, v122, v123
	v_cvt_pk_bf16_f32 v129, v124, v125
	global_store_dwordx4 v[148:149], v[126:129], off
	v_cvt_pk_bf16_f32 v106, v118, v119
	v_cvt_pk_bf16_f32 v107, v120, v121
	v_cvt_pk_bf16_f32 v108, v110, v111
	v_cvt_pk_bf16_f32 v109, v112, v113
	global_store_dwordx4 v[114:115], v[106:109], off
	v_cvt_pk_bf16_f32 v90, v102, v103
	v_cvt_pk_bf16_f32 v91, v104, v105
	v_cvt_pk_bf16_f32 v92, v94, v95
	v_cvt_pk_bf16_f32 v93, v96, v97
	global_store_dwordx4 v[98:99], v[90:93], off
	v_cvt_pk_bf16_f32 v74, v86, v87
	v_cvt_pk_bf16_f32 v75, v88, v89
	v_cvt_pk_bf16_f32 v76, v78, v79
	v_cvt_pk_bf16_f32 v77, v80, v81
	global_store_dwordx4 v[82:83], v[74:77], off
	v_cvt_pk_bf16_f32 v73, v68, v69
	global_store_dwordx4 v[82:83], v[70:73], off offset:256
	v_cvt_pk_bf16_f32 v62, v62, v63
	v_cvt_pk_bf16_f32 v63, v64, v65
	v_cvt_pk_bf16_f32 v64, v58, v59
	v_cvt_pk_bf16_f32 v65, v60, v61
	global_store_dwordx4 v[66:67], v[62:65], off
	v_cvt_pk_bf16_f32 v42, v54, v55
	v_cvt_pk_bf16_f32 v43, v56, v57
	v_cvt_pk_bf16_f32 v44, v46, v47
	v_cvt_pk_bf16_f32 v45, v48, v49
	global_store_dwordx4 v[50:51], v[42:45], off
	v_cvt_pk_bf16_f32 v26, v38, v39
	v_cvt_pk_bf16_f32 v27, v40, v41
	v_cvt_pk_bf16_f32 v28, v30, v31
	v_cvt_pk_bf16_f32 v29, v32, v33
	global_store_dwordx4 v[34:35], v[26:29], off
	v_cvt_pk_bf16_f32 v10, v22, v23
	v_cvt_pk_bf16_f32 v11, v24, v25
	v_cvt_pk_bf16_f32 v12, v14, v15
	v_cvt_pk_bf16_f32 v13, v16, v17
	global_store_dwordx4 v[18:19], v[10:13], off
	v_cvt_pk_bf16_f32 v6, v6, v7
	v_cvt_pk_bf16_f32 v7, v8, v9
	v_cvt_pk_bf16_f32 v8, v2, v3
	v_cvt_pk_bf16_f32 v9, v4, v5
	global_store_dwordx4 v[18:19], v[6:9], off offset:256
	s_cbranch_vccz .LBB0_346
	s_waitcnt vmcnt(0)
	s_cmpk_gt_u32 s25, 0xff
	s_cbranch_scc1 .LBB0_358
	s_barrier
